# as v56 plus s_nop 0 between every m0 write and the LDS-DMA load right behind it (12 sites; hazard-clean build)
# speedup vs baseline: 1.0025x; 1.0025x over previous
; #define PG8_STAGE(bufoff, gbase, voff) do { _Pragma("unroll") for (int _i = 0; _i < 2; ++_i) \
;         __builtin_amdgcn_global_load_lds((const unsigned*)((const char*)(gbase) + (voff)[_i]), (PG8_LAS unsigned*)(lds + (bufoff) + ldsw + _i * 8192), 16, 0, 0); } while (0)
; #define PG8_LDA(dst, b, h) do { _Pragma("unroll") for (int m = 0; m < 4; ++m) _Pragma("unroll") for (int k = 0; k < 2; ++k) dst[m][k] = *(const PG8_LAS bf16x8*)(lds + PG8_SA(b, h) + aoff + m * 2048 + k * 1024); } while (0)
; #define PG8_LDB(dst, b, h) do { _Pragma("unroll") for (int n = 0; n < 2; ++n) _Pragma("unroll") for (int k = 0; k < 2; ++k) dst[n][k] = *(const PG8_LAS bf16x8*)(lds + PG8_SB(b, h) + boff + n * 2048 + k * 1024); } while (0)
; #define PG8_MMA(ai, bj, At, Bt) do { __builtin_amdgcn_s_setprio(1); _Pragma("unroll") for (int m = 0; m < 4; ++m) _Pragma("unroll") for (int n = 0; n < 2; ++n) _Pragma("unroll") for (int k = 0; k < 2; ++k) \
;         acc[ai][bj][m][n] = __builtin_amdgcn_mfma_f32_16x16x32_bf16(Bt[n][k], At[m][k], acc[ai][bj][m][n], 0, 0, 0); __builtin_amdgcn_s_setprio(0); } while (0)
; #define PG8_WAIT_V(n) asm volatile("s_waitcnt vmcnt(" #n ")" ::: "memory")
; #define PG8_WAIT_L(n) asm volatile("s_waitcnt lgkmcnt(" #n ")" ::: "memory")
; #define PG8_BAR __builtin_amdgcn_s_barrier()
; #define PG8_SCHED __builtin_amdgcn_sched_barrier(0)
; template <class Epi, class Sched, bool ALIGN_EPI = false, bool SP2 = false>
; __device__ __forceinline__ void gemm_phase(PG8_LAS unsigned char* lds, const Gemm g, const Sched& S, const Epi& E) {
;     ...
;             const char* a1 = cA + (size_t)(t + 1) * kstep;
;             const char* a2 = last ? nA : cA + (size_t)(t + 2) * kstep; const char* b2 = last ? nB : cB + (size_t)(t + 2) * kstep;
;             const char* a3 = a2 + kstep; const char* b3 = b2 + kstep;
;     ...
;             PG8_LDB(B0, 0, 0); PG8_LDB(B1, 0, 1); PG8_SCHED; PG8_LDA(At, 0, 0); PG8_STAGE(PG8_SA(1, 1), a1 + hstep, voffA);
;             PG8_WAIT_V(8); PG8_WAIT_L(0); PG8_BAR; PG8_MMA(0, 0, At, B0); PG8_MMA(0, 1, At, B1); PG8_BAR; PG8_SCHED;
;             PG8_LDA(At, 0, 1); PG8_STAGE(PG8_SB(0, 0), b2, voffB); PG8_STAGE(PG8_SB(0, 1), b2 + hstep, voffB); PG8_STAGE(PG8_SA(0, 0), a2, voffA);
;             PG8_WAIT_V(8); PG8_WAIT_L(0); PG8_BAR; PG8_MMA(1, 0, At, B0); PG8_MMA(1, 1, At, B1); PG8_BAR; PG8_SCHED;
.LBB0_218:
	ds_read_b128 v[148:151], v157
	ds_read_b128 v[166:169], v157 offset:1024
	ds_read_b128 v[172:175], v157 offset:2048
	ds_read_b128 v[176:179], v157 offset:3072
	ds_read_b128 v[180:183], v158
	ds_read_b128 v[184:187], v158 offset:1024
	ds_read_b128 v[188:191], v158 offset:2048
	ds_read_b128 v[196:199], v158 offset:3072
	s_add_u32 s6, s52, 0xfffc0080
	s_addc_u32 s7, s53, -1
	s_cmp_eq_u32 s72, 12
	s_cselect_b32 s57, s4, s7
	s_cselect_b32 s56, s41, s6
	s_cselect_b32 s55, s39, s33
	s_cselect_b32 s54, s78, s79
	s_add_i32 m0, s37, 0xc000
	ds_read_b128 v[200:203], v159
	ds_read_b128 v[204:207], v159 offset:1024
	ds_read_b128 v[208:211], v159 offset:2048
	ds_read_b128 v[212:215], v159 offset:3072
	ds_read_b128 v[216:219], v159 offset:4096
	ds_read_b128 v[220:223], v159 offset:5120
	ds_read_b128 v[224:227], v159 offset:6144
	ds_read_b128 v[228:231], v159 offset:7168
	global_load_lds_dwordx4 v140, s[52:53]
	s_add_i32 m0, s37, 0xe000
	s_nop 0
	global_load_lds_dwordx4 v142, s[52:53]
	s_waitcnt vmcnt(8)
	s_waitcnt lgkmcnt(0)
	s_barrier
	s_waitcnt lgkmcnt(0)
	v_mfma_f32_16x16x32_bf16 v[124:127], v[148:151], v[200:203], v[124:127]
	v_mfma_f32_16x16x32_bf16 v[116:119], v[172:175], v[200:203], v[116:119]
	v_mfma_f32_16x16x32_bf16 v[108:111], v[148:151], v[208:211], v[108:111]
	v_mfma_f32_16x16x32_bf16 v[100:103], v[172:175], v[208:211], v[100:103]
	v_mfma_f32_16x16x32_bf16 v[92:95], v[148:151], v[216:219], v[92:95]
	v_mfma_f32_16x16x32_bf16 v[84:87], v[172:175], v[216:219], v[84:87]
	v_mfma_f32_16x16x32_bf16 v[76:79], v[148:151], v[224:227], v[76:79]
	v_mfma_f32_16x16x32_bf16 v[68:71], v[172:175], v[224:227], v[68:71]
	v_mfma_f32_16x16x32_bf16 v[124:127], v[166:169], v[204:207], v[124:127]
	v_mfma_f32_16x16x32_bf16 v[116:119], v[176:179], v[204:207], v[116:119]
	v_mfma_f32_16x16x32_bf16 v[108:111], v[166:169], v[212:215], v[108:111]
	v_mfma_f32_16x16x32_bf16 v[100:103], v[176:179], v[212:215], v[100:103]
	v_mfma_f32_16x16x32_bf16 v[92:95], v[166:169], v[220:223], v[92:95]
	v_mfma_f32_16x16x32_bf16 v[84:87], v[176:179], v[220:223], v[84:87]
	v_mfma_f32_16x16x32_bf16 v[76:79], v[166:169], v[228:231], v[76:79]
	v_mfma_f32_16x16x32_bf16 v[68:71], v[176:179], v[228:231], v[68:71]
	v_mfma_f32_16x16x32_bf16 v[120:123], v[180:183], v[200:203], v[120:123]
	v_mfma_f32_16x16x32_bf16 v[112:115], v[188:191], v[200:203], v[112:115]
	v_mfma_f32_16x16x32_bf16 v[104:107], v[180:183], v[208:211], v[104:107]
	v_mfma_f32_16x16x32_bf16 v[96:99], v[188:191], v[208:211], v[96:99]
	v_mfma_f32_16x16x32_bf16 v[88:91], v[180:183], v[216:219], v[88:91]
	v_mfma_f32_16x16x32_bf16 v[80:83], v[188:191], v[216:219], v[80:83]
	v_mfma_f32_16x16x32_bf16 v[72:75], v[180:183], v[224:227], v[72:75]
	v_mfma_f32_16x16x32_bf16 v[64:67], v[188:191], v[224:227], v[64:67]
	v_mfma_f32_16x16x32_bf16 v[120:123], v[184:187], v[204:207], v[120:123]
	v_mfma_f32_16x16x32_bf16 v[112:115], v[196:199], v[204:207], v[112:115]
	v_mfma_f32_16x16x32_bf16 v[104:107], v[184:187], v[212:215], v[104:107]
	v_mfma_f32_16x16x32_bf16 v[96:99], v[196:199], v[212:215], v[96:99]
	v_mfma_f32_16x16x32_bf16 v[88:91], v[184:187], v[220:223], v[88:91]
	v_mfma_f32_16x16x32_bf16 v[80:83], v[196:199], v[220:223], v[80:83]
	v_mfma_f32_16x16x32_bf16 v[72:75], v[184:187], v[228:231], v[72:75]
	v_mfma_f32_16x16x32_bf16 v[64:67], v[196:199], v[228:231], v[64:67]
	s_barrier
	s_add_i32 s6, s69, s36
	s_mov_b32 m0, s6
	ds_read_b128 v[200:203], v159 offset:16384
	ds_read_b128 v[204:207], v159 offset:17408
	ds_read_b128 v[208:211], v159 offset:18432
	ds_read_b128 v[212:215], v159 offset:19456
	ds_read_b128 v[216:219], v159 offset:20480
	ds_read_b128 v[220:223], v159 offset:21504
	ds_read_b128 v[224:227], v159 offset:22528
	ds_read_b128 v[228:231], v159 offset:23552
	global_load_lds_dwordx4 v136, s[54:55]
	s_add_i32 m0, s6, 0x2000
	s_add_u32 s6, s54, 0x40000
	s_addc_u32 s7, s55, 0
	s_add_i32 s73, s74, s36
	global_load_lds_dwordx4 v132, s[54:55]
	s_mov_b32 m0, s73
	s_nop 0
	global_load_lds_dwordx4 v136, s[6:7]
	s_add_i32 m0, s73, 0x2000
	s_nop 0
	global_load_lds_dwordx4 v132, s[6:7]
	s_mov_b32 m0, s37
	s_nop 0
	global_load_lds_dwordx4 v138, s[56:57]
	s_mov_b32 m0, s59
	s_nop 0
	global_load_lds_dwordx4 v134, s[56:57]
	s_waitcnt vmcnt(8)
	s_waitcnt lgkmcnt(0)
	s_barrier
	s_waitcnt lgkmcnt(0)
	v_mfma_f32_16x16x32_bf16 v[60:63], v[148:151], v[200:203], v[60:63]
	v_mfma_f32_16x16x32_bf16 v[52:55], v[172:175], v[200:203], v[52:55]
	v_mfma_f32_16x16x32_bf16 v[44:47], v[148:151], v[208:211], v[44:47]
	v_mfma_f32_16x16x32_bf16 v[36:39], v[172:175], v[208:211], v[36:39]
	v_mfma_f32_16x16x32_bf16 v[28:31], v[148:151], v[216:219], v[28:31]
	v_mfma_f32_16x16x32_bf16 v[20:23], v[172:175], v[216:219], v[20:23]
	v_mfma_f32_16x16x32_bf16 v[12:15], v[148:151], v[224:227], v[12:15]
	v_mfma_f32_16x16x32_bf16 v[4:7], v[172:175], v[224:227], v[4:7]
	v_mfma_f32_16x16x32_bf16 v[60:63], v[166:169], v[204:207], v[60:63]
	v_mfma_f32_16x16x32_bf16 v[52:55], v[176:179], v[204:207], v[52:55]
	v_mfma_f32_16x16x32_bf16 v[44:47], v[166:169], v[212:215], v[44:47]
	v_mfma_f32_16x16x32_bf16 v[36:39], v[176:179], v[212:215], v[36:39]
	v_mfma_f32_16x16x32_bf16 v[28:31], v[166:169], v[220:223], v[28:31]
	v_mfma_f32_16x16x32_bf16 v[20:23], v[176:179], v[220:223], v[20:23]
	v_mfma_f32_16x16x32_bf16 v[12:15], v[166:169], v[228:231], v[12:15]
	v_mfma_f32_16x16x32_bf16 v[4:7], v[176:179], v[228:231], v[4:7]
	v_mfma_f32_16x16x32_bf16 v[56:59], v[180:183], v[200:203], v[56:59]
	v_mfma_f32_16x16x32_bf16 v[48:51], v[188:191], v[200:203], v[48:51]
	v_mfma_f32_16x16x32_bf16 v[40:43], v[180:183], v[208:211], v[40:43]
	v_mfma_f32_16x16x32_bf16 v[32:35], v[188:191], v[208:211], v[32:35]
	v_mfma_f32_16x16x32_bf16 v[24:27], v[180:183], v[216:219], v[24:27]
	v_mfma_f32_16x16x32_bf16 v[16:19], v[188:191], v[216:219], v[16:19]
	v_mfma_f32_16x16x32_bf16 v[8:11], v[180:183], v[224:227], v[8:11]
	v_mfma_f32_16x16x32_bf16 v[0:3], v[188:191], v[224:227], v[0:3]
	v_mfma_f32_16x16x32_bf16 v[56:59], v[184:187], v[204:207], v[56:59]
	v_mfma_f32_16x16x32_bf16 v[48:51], v[196:199], v[204:207], v[48:51]
	v_mfma_f32_16x16x32_bf16 v[40:43], v[184:187], v[212:215], v[40:43]
	v_mfma_f32_16x16x32_bf16 v[32:35], v[196:199], v[212:215], v[32:35]
	v_mfma_f32_16x16x32_bf16 v[24:27], v[184:187], v[220:223], v[24:27]
	v_mfma_f32_16x16x32_bf16 v[16:19], v[196:199], v[220:223], v[16:19]
	v_mfma_f32_16x16x32_bf16 v[8:11], v[184:187], v[228:231], v[8:11]
	v_mfma_f32_16x16x32_bf16 v[0:3], v[196:199], v[228:231], v[0:3]
	s_barrier
; #define PG8_STAGE(bufoff, gbase, voff) do { _Pragma("unroll") for (int _i = 0; _i < 2; ++_i) \
;         __builtin_amdgcn_global_load_lds((const unsigned*)((const char*)(gbase) + (voff)[_i]), (PG8_LAS unsigned*)(lds + (bufoff) + ldsw + _i * 8192), 16, 0, 0); } while (0)
; #define PG8_LDA(dst, b, h) do { _Pragma("unroll") for (int m = 0; m < 4; ++m) _Pragma("unroll") for (int k = 0; k < 2; ++k) dst[m][k] = *(const PG8_LAS bf16x8*)(lds + PG8_SA(b, h) + aoff + m * 2048 + k * 1024); } while (0)
; #define PG8_LDB(dst, b, h) do { _Pragma("unroll") for (int n = 0; n < 2; ++n) _Pragma("unroll") for (int k = 0; k < 2; ++k) dst[n][k] = *(const PG8_LAS bf16x8*)(lds + PG8_SB(b, h) + boff + n * 2048 + k * 1024); } while (0)
; #define PG8_MMA(ai, bj, At, Bt) do { __builtin_amdgcn_s_setprio(1); _Pragma("unroll") for (int m = 0; m < 4; ++m) _Pragma("unroll") for (int n = 0; n < 2; ++n) _Pragma("unroll") for (int k = 0; k < 2; ++k) \
;         acc[ai][bj][m][n] = __builtin_amdgcn_mfma_f32_16x16x32_bf16(Bt[n][k], At[m][k], acc[ai][bj][m][n], 0, 0, 0); __builtin_amdgcn_s_setprio(0); } while (0)
; #define PG8_WAIT_V(n) asm volatile("s_waitcnt vmcnt(" #n ")" ::: "memory")
; #define PG8_WAIT_L(n) asm volatile("s_waitcnt lgkmcnt(" #n ")" ::: "memory")
; #define PG8_BAR __builtin_amdgcn_s_barrier()
; #define PG8_SCHED __builtin_amdgcn_sched_barrier(0)
; template <class Epi, class Sched, bool ALIGN_EPI = false, bool SP2 = false>
; __device__ __forceinline__ void gemm_phase(PG8_LAS unsigned char* lds, const Gemm g, const Sched& S, const Epi& E) {
;     ...
;             PG8_LDB(B0, 1, 0); PG8_LDB(B1, 1, 1); PG8_SCHED; PG8_LDA(At, 1, 0); PG8_STAGE(PG8_SA(0, 1), a2 + hstep, voffA);
;             PG8_WAIT_V(8); PG8_WAIT_L(0); PG8_BAR; PG8_MMA(0, 0, At, B0); PG8_MMA(0, 1, At, B1); PG8_BAR; PG8_SCHED;
;             PG8_LDA(At, 1, 1); PG8_STAGE(PG8_SB(1, 0), b3, voffB); PG8_STAGE(PG8_SB(1, 1), b3 + hstep, voffB); PG8_STAGE(PG8_SA(1, 0), a3, voffA);
;             PG8_WAIT_V(8); PG8_WAIT_L(0); PG8_BAR; PG8_MMA(1, 0, At, B0); PG8_MMA(1, 1, At, B1); PG8_BAR; PG8_SCHED;
	s_add_i32 s73, 0, 0x18000
	v_add_u32_e32 v161, s73, v154
	s_add_i32 s80, 0, 0x1c000
	ds_read_b128 v[148:151], v161
	ds_read_b128 v[166:169], v161 offset:1024
	ds_read_b128 v[172:175], v161 offset:2048
	ds_read_b128 v[176:179], v161 offset:3072
	v_add_u32_e32 v161, s80, v154
	ds_read_b128 v[180:183], v161
	ds_read_b128 v[184:187], v161 offset:1024
	ds_read_b128 v[188:191], v161 offset:2048
	ds_read_b128 v[196:199], v161 offset:3072
	s_add_u32 s6, s56, 0x40000
	s_addc_u32 s7, s57, 0
	s_mov_b32 m0, s60
	ds_read_b128 v[200:203], v159 offset:32768
	ds_read_b128 v[204:207], v159 offset:33792
	ds_read_b128 v[208:211], v159 offset:34816
	ds_read_b128 v[212:215], v159 offset:35840
	ds_read_b128 v[216:219], v159 offset:36864
	ds_read_b128 v[220:223], v159 offset:37888
	ds_read_b128 v[224:227], v159 offset:38912
	ds_read_b128 v[228:231], v159 offset:39936
	global_load_lds_dwordx4 v138, s[6:7]
	s_mov_b32 m0, s61
	s_nop 0
	global_load_lds_dwordx4 v134, s[6:7]
	s_waitcnt vmcnt(8)
	s_waitcnt lgkmcnt(0)
	s_barrier
	s_waitcnt lgkmcnt(0)
	v_mfma_f32_16x16x32_bf16 v[124:127], v[148:151], v[200:203], v[124:127]
	v_mfma_f32_16x16x32_bf16 v[116:119], v[172:175], v[200:203], v[116:119]
	v_mfma_f32_16x16x32_bf16 v[108:111], v[148:151], v[208:211], v[108:111]
	v_mfma_f32_16x16x32_bf16 v[100:103], v[172:175], v[208:211], v[100:103]
	v_mfma_f32_16x16x32_bf16 v[92:95], v[148:151], v[216:219], v[92:95]
	v_mfma_f32_16x16x32_bf16 v[84:87], v[172:175], v[216:219], v[84:87]
	v_mfma_f32_16x16x32_bf16 v[76:79], v[148:151], v[224:227], v[76:79]
	v_mfma_f32_16x16x32_bf16 v[68:71], v[172:175], v[224:227], v[68:71]
	v_mfma_f32_16x16x32_bf16 v[124:127], v[166:169], v[204:207], v[124:127]
	v_mfma_f32_16x16x32_bf16 v[116:119], v[176:179], v[204:207], v[116:119]
	v_mfma_f32_16x16x32_bf16 v[108:111], v[166:169], v[212:215], v[108:111]
	v_mfma_f32_16x16x32_bf16 v[100:103], v[176:179], v[212:215], v[100:103]
	v_mfma_f32_16x16x32_bf16 v[92:95], v[166:169], v[220:223], v[92:95]
	v_mfma_f32_16x16x32_bf16 v[84:87], v[176:179], v[220:223], v[84:87]
	v_mfma_f32_16x16x32_bf16 v[76:79], v[166:169], v[228:231], v[76:79]
	v_mfma_f32_16x16x32_bf16 v[68:71], v[176:179], v[228:231], v[68:71]
	v_mfma_f32_16x16x32_bf16 v[120:123], v[180:183], v[200:203], v[120:123]
	v_mfma_f32_16x16x32_bf16 v[112:115], v[188:191], v[200:203], v[112:115]
	v_mfma_f32_16x16x32_bf16 v[104:107], v[180:183], v[208:211], v[104:107]
	v_mfma_f32_16x16x32_bf16 v[96:99], v[188:191], v[208:211], v[96:99]
	v_mfma_f32_16x16x32_bf16 v[88:91], v[180:183], v[216:219], v[88:91]
	v_mfma_f32_16x16x32_bf16 v[80:83], v[188:191], v[216:219], v[80:83]
	v_mfma_f32_16x16x32_bf16 v[72:75], v[180:183], v[224:227], v[72:75]
	v_mfma_f32_16x16x32_bf16 v[64:67], v[188:191], v[224:227], v[64:67]
	v_mfma_f32_16x16x32_bf16 v[120:123], v[184:187], v[204:207], v[120:123]
	v_mfma_f32_16x16x32_bf16 v[112:115], v[196:199], v[204:207], v[112:115]
	v_mfma_f32_16x16x32_bf16 v[104:107], v[184:187], v[212:215], v[104:107]
	v_mfma_f32_16x16x32_bf16 v[96:99], v[196:199], v[212:215], v[96:99]
	v_mfma_f32_16x16x32_bf16 v[88:91], v[184:187], v[220:223], v[88:91]
	v_mfma_f32_16x16x32_bf16 v[80:83], v[196:199], v[220:223], v[80:83]
	v_mfma_f32_16x16x32_bf16 v[72:75], v[184:187], v[228:231], v[72:75]
	v_mfma_f32_16x16x32_bf16 v[64:67], v[196:199], v[228:231], v[64:67]
	s_barrier
	s_add_i32 s6, s73, s36
	s_add_u32 s98, s54, 0x80
	s_addc_u32 s99, s55, 0
	s_add_u32 s100, s56, 0x80
	s_addc_u32 s101, s57, 0
	s_mov_b32 m0, s6
	ds_read_b128 v[200:203], v159 offset:49152
	ds_read_b128 v[204:207], v159 offset:50176
	ds_read_b128 v[208:211], v159 offset:51200
	ds_read_b128 v[212:215], v159 offset:52224
	ds_read_b128 v[216:219], v159 offset:53248
	ds_read_b128 v[220:223], v159 offset:54272
	ds_read_b128 v[224:227], v159 offset:55296
	ds_read_b128 v[228:231], v159 offset:56320
	global_load_lds_dwordx4 v136, s[98:99]
	s_add_i32 m0, s6, 0x2000
	s_add_u32 s6, s54, 0x40080
	s_addc_u32 s7, s55, 0
	s_add_i32 s54, s80, s36
	global_load_lds_dwordx4 v132, s[98:99]
	s_mov_b32 m0, s54
	s_nop 0
	global_load_lds_dwordx4 v136, s[6:7]
	s_add_i32 m0, s54, 0x2000
	s_nop 0
	global_load_lds_dwordx4 v132, s[6:7]
	s_mov_b32 m0, s67
	s_nop 0
	global_load_lds_dwordx4 v138, s[100:101]
	s_mov_b32 m0, s68
	s_nop 0
	global_load_lds_dwordx4 v134, s[100:101]
	s_waitcnt vmcnt(8)
	s_waitcnt lgkmcnt(0)
	s_barrier
	s_waitcnt lgkmcnt(0)
	v_mfma_f32_16x16x32_bf16 v[60:63], v[148:151], v[200:203], v[60:63]
	v_mfma_f32_16x16x32_bf16 v[52:55], v[172:175], v[200:203], v[52:55]
	v_mfma_f32_16x16x32_bf16 v[44:47], v[148:151], v[208:211], v[44:47]
	v_mfma_f32_16x16x32_bf16 v[36:39], v[172:175], v[208:211], v[36:39]
	v_mfma_f32_16x16x32_bf16 v[28:31], v[148:151], v[216:219], v[28:31]
	v_mfma_f32_16x16x32_bf16 v[20:23], v[172:175], v[216:219], v[20:23]
	v_mfma_f32_16x16x32_bf16 v[12:15], v[148:151], v[224:227], v[12:15]
	v_mfma_f32_16x16x32_bf16 v[4:7], v[172:175], v[224:227], v[4:7]
	v_mfma_f32_16x16x32_bf16 v[60:63], v[166:169], v[204:207], v[60:63]
	v_mfma_f32_16x16x32_bf16 v[52:55], v[176:179], v[204:207], v[52:55]
	v_mfma_f32_16x16x32_bf16 v[44:47], v[166:169], v[212:215], v[44:47]
	v_mfma_f32_16x16x32_bf16 v[36:39], v[176:179], v[212:215], v[36:39]
	v_mfma_f32_16x16x32_bf16 v[28:31], v[166:169], v[220:223], v[28:31]
	v_mfma_f32_16x16x32_bf16 v[20:23], v[176:179], v[220:223], v[20:23]
	v_mfma_f32_16x16x32_bf16 v[12:15], v[166:169], v[228:231], v[12:15]
	v_mfma_f32_16x16x32_bf16 v[4:7], v[176:179], v[228:231], v[4:7]
	v_mfma_f32_16x16x32_bf16 v[56:59], v[180:183], v[200:203], v[56:59]
	v_mfma_f32_16x16x32_bf16 v[48:51], v[188:191], v[200:203], v[48:51]
	v_mfma_f32_16x16x32_bf16 v[40:43], v[180:183], v[208:211], v[40:43]
	v_mfma_f32_16x16x32_bf16 v[32:35], v[188:191], v[208:211], v[32:35]
	v_mfma_f32_16x16x32_bf16 v[24:27], v[180:183], v[216:219], v[24:27]
	v_mfma_f32_16x16x32_bf16 v[16:19], v[188:191], v[216:219], v[16:19]
	v_mfma_f32_16x16x32_bf16 v[8:11], v[180:183], v[224:227], v[8:11]
	v_mfma_f32_16x16x32_bf16 v[0:3], v[188:191], v[224:227], v[0:3]
	v_mfma_f32_16x16x32_bf16 v[56:59], v[184:187], v[204:207], v[56:59]
	v_mfma_f32_16x16x32_bf16 v[48:51], v[196:199], v[204:207], v[48:51]
	v_mfma_f32_16x16x32_bf16 v[40:43], v[184:187], v[212:215], v[40:43]
	v_mfma_f32_16x16x32_bf16 v[32:35], v[196:199], v[212:215], v[32:35]
	v_mfma_f32_16x16x32_bf16 v[24:27], v[184:187], v[220:223], v[24:27]
	v_mfma_f32_16x16x32_bf16 v[16:19], v[196:199], v[220:223], v[16:19]
	v_mfma_f32_16x16x32_bf16 v[8:11], v[184:187], v[228:231], v[8:11]
	v_mfma_f32_16x16x32_bf16 v[0:3], v[196:199], v[228:231], v[0:3]
	s_barrier
	s_add_i32 s72, s72, 2
	s_add_u32 s52, s52, 0x100
	s_addc_u32 s53, s53, 0
	s_add_u32 s79, s79, 0x100
	s_addc_u32 s33, s33, 0
	s_cmp_gt_u32 s72, 13
	s_cbranch_scc0 .LBB0_218
	s_and_b64 vcc, exec, s[34:35]
	s_cbranch_vccz .LBB0_221
	s_barrier

; #define PG8_STAGE(bufoff, gbase, voff) do { _Pragma("unroll") for (int _i = 0; _i < 2; ++_i) \
;         __builtin_amdgcn_global_load_lds((const unsigned*)((const char*)(gbase) + (voff)[_i]), (PG8_LAS unsigned*)(lds + (bufoff) + ldsw + _i * 8192), 16, 0, 0); } while (0)
; #define PG8_LDA(dst, b, h) do { _Pragma("unroll") for (int m = 0; m < 4; ++m) _Pragma("unroll") for (int k = 0; k < 2; ++k) dst[m][k] = *(const PG8_LAS bf16x8*)(lds + PG8_SA(b, h) + aoff + m * 2048 + k * 1024); } while (0)
; #define PG8_LDB(dst, b, h) do { _Pragma("unroll") for (int n = 0; n < 2; ++n) _Pragma("unroll") for (int k = 0; k < 2; ++k) dst[n][k] = *(const PG8_LAS bf16x8*)(lds + PG8_SB(b, h) + boff + n * 2048 + k * 1024); } while (0)
; #define PG8_MMA(ai, bj, At, Bt) do { __builtin_amdgcn_s_setprio(1); _Pragma("unroll") for (int m = 0; m < 4; ++m) _Pragma("unroll") for (int n = 0; n < 2; ++n) _Pragma("unroll") for (int k = 0; k < 2; ++k) \
;         acc[ai][bj][m][n] = __builtin_amdgcn_mfma_f32_16x16x32_bf16(Bt[n][k], At[m][k], acc[ai][bj][m][n], 0, 0, 0); __builtin_amdgcn_s_setprio(0); } while (0)
; #define PG8_WAIT_V(n) asm volatile("s_waitcnt vmcnt(" #n ")" ::: "memory")
; #define PG8_WAIT_L(n) asm volatile("s_waitcnt lgkmcnt(" #n ")" ::: "memory")
; template <class Epi, class Sched, bool ALIGN_EPI = false, bool SP2 = false>
; __device__ __forceinline__ void gemm_phase(PG8_LAS unsigned char* lds, const Gemm g, const Sched& S, const Epi& E) {
;     ...
;             const bool last = (t == nt - 2);
;             const char* a1 = cA + (size_t)(t + 1) * kstep;
;             const char* a2 = last ? nA : cA + (size_t)(t + 2) * kstep; const char* b2 = last ? nB : cB + (size_t)(t + 2) * kstep;
;             const char* a3 = a2 + kstep; const char* b3 = b2 + kstep;
;             if (last && has_next) S.a_ready(nxt);
;             if constexpr (SP2) {
;             PG8_LDB(B0, 0, 0); PG8_LDB(B1, 0, 1); PG8_SCHED; PG8_LDA(At, 0, 0); PG8_STAGE(PG8_SA(1, 1), a1 + hstep, voffA);
;             PG8_WAIT_V(8); PG8_WAIT_L(0); PG8_BAR; PG8_MMA(0, 0, At, B0); PG8_MMA(0, 1, At, B1); PG8_BAR; PG8_SCHED;
;             PG8_LDA(At, 0, 1); PG8_STAGE(PG8_SB(0, 0), b2, voffB); PG8_STAGE(PG8_SB(0, 1), b2 + hstep, voffB); PG8_STAGE(PG8_SA(0, 0), a2, voffA);
;             PG8_WAIT_V(8); PG8_WAIT_L(0); PG8_BAR; PG8_MMA(1, 0, At, B0); PG8_MMA(1, 1, At, B1); PG8_BAR; PG8_SCHED;
.LBB0_323:
	ds_read_b128 v[148:151], v156
	ds_read_b128 v[166:169], v156 offset:1024
	ds_read_b128 v[172:175], v156 offset:2048
	ds_read_b128 v[176:179], v156 offset:3072
	ds_read_b128 v[180:183], v157
	ds_read_b128 v[184:187], v157 offset:1024
	ds_read_b128 v[188:191], v157 offset:2048
	ds_read_b128 v[196:199], v157 offset:3072
	s_add_u32 s56, s54, 0x100
	s_addc_u32 s57, s55, 0
	s_cmp_eq_u32 s69, 40
	s_cselect_b32 s61, s51, s57
	s_cselect_b32 s60, s50, s56
	s_cselect_b32 s59, s53, s33
	s_cselect_b32 s58, s52, s4
	s_add_i32 m0, s37, 0xc000
	ds_read_b128 v[200:203], v158
	ds_read_b128 v[204:207], v158 offset:1024
	ds_read_b128 v[208:211], v158 offset:2048
	ds_read_b128 v[212:215], v158 offset:3072
	ds_read_b128 v[216:219], v158 offset:4096
	ds_read_b128 v[220:223], v158 offset:5120
	ds_read_b128 v[224:227], v158 offset:6144
	ds_read_b128 v[228:231], v158 offset:7168
	global_load_lds_dwordx4 v140, s[54:55]
	s_add_i32 m0, s37, 0xe000
	s_nop 0
	global_load_lds_dwordx4 v142, s[54:55]
	s_waitcnt vmcnt(8)
	s_waitcnt lgkmcnt(0)
	s_barrier
	s_waitcnt lgkmcnt(0)
	v_mfma_f32_16x16x32_bf16 v[124:127], v[148:151], v[200:203], v[124:127]
	v_mfma_f32_16x16x32_bf16 v[120:123], v[172:175], v[200:203], v[120:123]
	v_mfma_f32_16x16x32_bf16 v[108:111], v[148:151], v[208:211], v[108:111]
	v_mfma_f32_16x16x32_bf16 v[104:107], v[172:175], v[208:211], v[104:107]
	v_mfma_f32_16x16x32_bf16 v[92:95], v[148:151], v[216:219], v[92:95]
	v_mfma_f32_16x16x32_bf16 v[88:91], v[172:175], v[216:219], v[88:91]
	v_mfma_f32_16x16x32_bf16 v[76:79], v[148:151], v[224:227], v[76:79]
	v_mfma_f32_16x16x32_bf16 v[72:75], v[172:175], v[224:227], v[72:75]
	v_mfma_f32_16x16x32_bf16 v[124:127], v[166:169], v[204:207], v[124:127]
	v_mfma_f32_16x16x32_bf16 v[120:123], v[176:179], v[204:207], v[120:123]
	v_mfma_f32_16x16x32_bf16 v[108:111], v[166:169], v[212:215], v[108:111]
	v_mfma_f32_16x16x32_bf16 v[104:107], v[176:179], v[212:215], v[104:107]
	v_mfma_f32_16x16x32_bf16 v[92:95], v[166:169], v[220:223], v[92:95]
	v_mfma_f32_16x16x32_bf16 v[88:91], v[176:179], v[220:223], v[88:91]
	v_mfma_f32_16x16x32_bf16 v[76:79], v[166:169], v[228:231], v[76:79]
	v_mfma_f32_16x16x32_bf16 v[72:75], v[176:179], v[228:231], v[72:75]
	v_mfma_f32_16x16x32_bf16 v[116:119], v[180:183], v[200:203], v[116:119]
	v_mfma_f32_16x16x32_bf16 v[112:115], v[188:191], v[200:203], v[112:115]
	v_mfma_f32_16x16x32_bf16 v[100:103], v[180:183], v[208:211], v[100:103]
	v_mfma_f32_16x16x32_bf16 v[96:99], v[188:191], v[208:211], v[96:99]
	v_mfma_f32_16x16x32_bf16 v[84:87], v[180:183], v[216:219], v[84:87]
	v_mfma_f32_16x16x32_bf16 v[80:83], v[188:191], v[216:219], v[80:83]
	v_mfma_f32_16x16x32_bf16 v[68:71], v[180:183], v[224:227], v[68:71]
	v_mfma_f32_16x16x32_bf16 v[64:67], v[188:191], v[224:227], v[64:67]
	v_mfma_f32_16x16x32_bf16 v[116:119], v[184:187], v[204:207], v[116:119]
	v_mfma_f32_16x16x32_bf16 v[112:115], v[196:199], v[204:207], v[112:115]
	v_mfma_f32_16x16x32_bf16 v[100:103], v[184:187], v[212:215], v[100:103]
	v_mfma_f32_16x16x32_bf16 v[96:99], v[196:199], v[212:215], v[96:99]
	v_mfma_f32_16x16x32_bf16 v[84:87], v[184:187], v[220:223], v[84:87]
	v_mfma_f32_16x16x32_bf16 v[80:83], v[196:199], v[220:223], v[80:83]
	v_mfma_f32_16x16x32_bf16 v[68:71], v[184:187], v[228:231], v[68:71]
	v_mfma_f32_16x16x32_bf16 v[64:67], v[196:199], v[228:231], v[64:67]
	s_barrier
	s_add_i32 s6, s74, s36
	s_mov_b32 m0, s6
	ds_read_b128 v[200:203], v158 offset:16384
	ds_read_b128 v[204:207], v158 offset:17408
	ds_read_b128 v[208:211], v158 offset:18432
	ds_read_b128 v[212:215], v158 offset:19456
	ds_read_b128 v[216:219], v158 offset:20480
	ds_read_b128 v[220:223], v158 offset:21504
	ds_read_b128 v[224:227], v158 offset:22528
	ds_read_b128 v[228:231], v158 offset:23552
	global_load_lds_dwordx4 v134, s[58:59]
	s_add_i32 m0, s6, 0x2000
	s_add_u32 s54, s58, 0xb0000
	s_addc_u32 s55, s59, 0
	s_add_i32 s6, s75, s36
	global_load_lds_dwordx4 v138, s[58:59]
	s_mov_b32 m0, s6
	s_nop 0
	global_load_lds_dwordx4 v134, s[54:55]
	s_add_i32 m0, s6, 0x2000
	s_nop 0
	global_load_lds_dwordx4 v138, s[54:55]
	s_mov_b32 m0, s37
	s_nop 0
	global_load_lds_dwordx4 v132, s[60:61]
	s_mov_b32 m0, s30
	s_nop 0
	global_load_lds_dwordx4 v136, s[60:61]
	s_waitcnt vmcnt(8)
	s_waitcnt lgkmcnt(0)
	s_barrier
	s_waitcnt lgkmcnt(0)
	v_mfma_f32_16x16x32_bf16 v[60:63], v[148:151], v[200:203], v[60:63]
	v_mfma_f32_16x16x32_bf16 v[56:59], v[172:175], v[200:203], v[56:59]
	v_mfma_f32_16x16x32_bf16 v[44:47], v[148:151], v[208:211], v[44:47]
	v_mfma_f32_16x16x32_bf16 v[40:43], v[172:175], v[208:211], v[40:43]
	v_mfma_f32_16x16x32_bf16 v[28:31], v[148:151], v[216:219], v[28:31]
	v_mfma_f32_16x16x32_bf16 v[24:27], v[172:175], v[216:219], v[24:27]
	v_mfma_f32_16x16x32_bf16 v[12:15], v[148:151], v[224:227], v[12:15]
	v_mfma_f32_16x16x32_bf16 v[8:11], v[172:175], v[224:227], v[8:11]
	v_mfma_f32_16x16x32_bf16 v[60:63], v[166:169], v[204:207], v[60:63]
	v_mfma_f32_16x16x32_bf16 v[56:59], v[176:179], v[204:207], v[56:59]
	v_mfma_f32_16x16x32_bf16 v[44:47], v[166:169], v[212:215], v[44:47]
	v_mfma_f32_16x16x32_bf16 v[40:43], v[176:179], v[212:215], v[40:43]
	v_mfma_f32_16x16x32_bf16 v[28:31], v[166:169], v[220:223], v[28:31]
	v_mfma_f32_16x16x32_bf16 v[24:27], v[176:179], v[220:223], v[24:27]
	v_mfma_f32_16x16x32_bf16 v[12:15], v[166:169], v[228:231], v[12:15]
	v_mfma_f32_16x16x32_bf16 v[8:11], v[176:179], v[228:231], v[8:11]
	v_mfma_f32_16x16x32_bf16 v[52:55], v[180:183], v[200:203], v[52:55]
	v_mfma_f32_16x16x32_bf16 v[48:51], v[188:191], v[200:203], v[48:51]
	v_mfma_f32_16x16x32_bf16 v[36:39], v[180:183], v[208:211], v[36:39]
	v_mfma_f32_16x16x32_bf16 v[32:35], v[188:191], v[208:211], v[32:35]
	v_mfma_f32_16x16x32_bf16 v[20:23], v[180:183], v[216:219], v[20:23]
	v_mfma_f32_16x16x32_bf16 v[16:19], v[188:191], v[216:219], v[16:19]
	v_mfma_f32_16x16x32_bf16 v[4:7], v[180:183], v[224:227], v[4:7]
	v_mfma_f32_16x16x32_bf16 v[0:3], v[188:191], v[224:227], v[0:3]
	v_mfma_f32_16x16x32_bf16 v[52:55], v[184:187], v[204:207], v[52:55]
	v_mfma_f32_16x16x32_bf16 v[48:51], v[196:199], v[204:207], v[48:51]
	v_mfma_f32_16x16x32_bf16 v[36:39], v[184:187], v[212:215], v[36:39]
	v_mfma_f32_16x16x32_bf16 v[32:35], v[196:199], v[212:215], v[32:35]
	v_mfma_f32_16x16x32_bf16 v[20:23], v[184:187], v[220:223], v[20:23]
	v_mfma_f32_16x16x32_bf16 v[16:19], v[196:199], v[220:223], v[16:19]
	v_mfma_f32_16x16x32_bf16 v[4:7], v[184:187], v[228:231], v[4:7]
	v_mfma_f32_16x16x32_bf16 v[0:3], v[196:199], v[228:231], v[0:3]
	s_barrier
; #define PG8_STAGE(bufoff, gbase, voff) do { _Pragma("unroll") for (int _i = 0; _i < 2; ++_i) \
;         __builtin_amdgcn_global_load_lds((const unsigned*)((const char*)(gbase) + (voff)[_i]), (PG8_LAS unsigned*)(lds + (bufoff) + ldsw + _i * 8192), 16, 0, 0); } while (0)
; #define PG8_LDA(dst, b, h) do { _Pragma("unroll") for (int m = 0; m < 4; ++m) _Pragma("unroll") for (int k = 0; k < 2; ++k) dst[m][k] = *(const PG8_LAS bf16x8*)(lds + PG8_SA(b, h) + aoff + m * 2048 + k * 1024); } while (0)
; #define PG8_LDB(dst, b, h) do { _Pragma("unroll") for (int n = 0; n < 2; ++n) _Pragma("unroll") for (int k = 0; k < 2; ++k) dst[n][k] = *(const PG8_LAS bf16x8*)(lds + PG8_SB(b, h) + boff + n * 2048 + k * 1024); } while (0)
; #define PG8_MMA(ai, bj, At, Bt) do { __builtin_amdgcn_s_setprio(1); _Pragma("unroll") for (int m = 0; m < 4; ++m) _Pragma("unroll") for (int n = 0; n < 2; ++n) _Pragma("unroll") for (int k = 0; k < 2; ++k) \
;         acc[ai][bj][m][n] = __builtin_amdgcn_mfma_f32_16x16x32_bf16(Bt[n][k], At[m][k], acc[ai][bj][m][n], 0, 0, 0); __builtin_amdgcn_s_setprio(0); } while (0)
; #define PG8_WAIT_V(n) asm volatile("s_waitcnt vmcnt(" #n ")" ::: "memory")
; #define PG8_WAIT_L(n) asm volatile("s_waitcnt lgkmcnt(" #n ")" ::: "memory")
; #define PG8_BAR __builtin_amdgcn_s_barrier()
; #define PG8_SCHED __builtin_amdgcn_sched_barrier(0)
; template <class Epi, class Sched, bool ALIGN_EPI = false, bool SP2 = false>
; __device__ __forceinline__ void gemm_phase(PG8_LAS unsigned char* lds, const Gemm g, const Sched& S, const Epi& E) {
;     ...
;             PG8_LDB(B0, 1, 0); PG8_LDB(B1, 1, 1); PG8_SCHED; PG8_LDA(At, 1, 0); PG8_STAGE(PG8_SA(0, 1), a2 + hstep, voffA);
;             PG8_WAIT_V(8); PG8_WAIT_L(0); PG8_BAR; PG8_MMA(0, 0, At, B0); PG8_MMA(0, 1, At, B1); PG8_BAR; PG8_SCHED;
;             PG8_LDA(At, 1, 1); PG8_STAGE(PG8_SB(1, 0), b3, voffB); PG8_STAGE(PG8_SB(1, 1), b3 + hstep, voffB); PG8_STAGE(PG8_SA(1, 0), a3, voffA);
;             PG8_WAIT_V(8); PG8_WAIT_L(0); PG8_BAR; PG8_MMA(1, 0, At, B0); PG8_MMA(1, 1, At, B1); PG8_BAR; PG8_SCHED;
	s_add_i32 s6, 0, 0x18000
	v_add_u32_e32 v161, s6, v154
	s_add_i32 s7, 0, 0x1c000
	ds_read_b128 v[148:151], v161
	ds_read_b128 v[166:169], v161 offset:1024
	ds_read_b128 v[172:175], v161 offset:2048
	ds_read_b128 v[176:179], v161 offset:3072
	v_add_u32_e32 v161, s7, v154
	ds_read_b128 v[180:183], v161
	ds_read_b128 v[184:187], v161 offset:1024
	ds_read_b128 v[188:191], v161 offset:2048
	ds_read_b128 v[196:199], v161 offset:3072
	s_add_u32 s54, s60, 0xb0000
	s_addc_u32 s55, s61, 0
	s_mov_b32 m0, s31
	ds_read_b128 v[200:203], v158 offset:32768
	ds_read_b128 v[204:207], v158 offset:33792
	ds_read_b128 v[208:211], v158 offset:34816
	ds_read_b128 v[212:215], v158 offset:35840
	ds_read_b128 v[216:219], v158 offset:36864
	ds_read_b128 v[220:223], v158 offset:37888
	ds_read_b128 v[224:227], v158 offset:38912
	ds_read_b128 v[228:231], v158 offset:39936
	global_load_lds_dwordx4 v132, s[54:55]
	s_mov_b32 m0, s76
	s_nop 0
	global_load_lds_dwordx4 v136, s[54:55]
	s_waitcnt vmcnt(8)
	s_waitcnt lgkmcnt(0)
	s_barrier
	s_waitcnt lgkmcnt(0)
	v_mfma_f32_16x16x32_bf16 v[124:127], v[148:151], v[200:203], v[124:127]
	v_mfma_f32_16x16x32_bf16 v[120:123], v[172:175], v[200:203], v[120:123]
	v_mfma_f32_16x16x32_bf16 v[108:111], v[148:151], v[208:211], v[108:111]
	v_mfma_f32_16x16x32_bf16 v[104:107], v[172:175], v[208:211], v[104:107]
	v_mfma_f32_16x16x32_bf16 v[92:95], v[148:151], v[216:219], v[92:95]
	v_mfma_f32_16x16x32_bf16 v[88:91], v[172:175], v[216:219], v[88:91]
	v_mfma_f32_16x16x32_bf16 v[76:79], v[148:151], v[224:227], v[76:79]
	v_mfma_f32_16x16x32_bf16 v[72:75], v[172:175], v[224:227], v[72:75]
	v_mfma_f32_16x16x32_bf16 v[124:127], v[166:169], v[204:207], v[124:127]
	v_mfma_f32_16x16x32_bf16 v[120:123], v[176:179], v[204:207], v[120:123]
	v_mfma_f32_16x16x32_bf16 v[108:111], v[166:169], v[212:215], v[108:111]
	v_mfma_f32_16x16x32_bf16 v[104:107], v[176:179], v[212:215], v[104:107]
	v_mfma_f32_16x16x32_bf16 v[92:95], v[166:169], v[220:223], v[92:95]
	v_mfma_f32_16x16x32_bf16 v[88:91], v[176:179], v[220:223], v[88:91]
	v_mfma_f32_16x16x32_bf16 v[76:79], v[166:169], v[228:231], v[76:79]
	v_mfma_f32_16x16x32_bf16 v[72:75], v[176:179], v[228:231], v[72:75]
	v_mfma_f32_16x16x32_bf16 v[116:119], v[180:183], v[200:203], v[116:119]
	v_mfma_f32_16x16x32_bf16 v[112:115], v[188:191], v[200:203], v[112:115]
	v_mfma_f32_16x16x32_bf16 v[100:103], v[180:183], v[208:211], v[100:103]
	v_mfma_f32_16x16x32_bf16 v[96:99], v[188:191], v[208:211], v[96:99]
	v_mfma_f32_16x16x32_bf16 v[84:87], v[180:183], v[216:219], v[84:87]
	v_mfma_f32_16x16x32_bf16 v[80:83], v[188:191], v[216:219], v[80:83]
	v_mfma_f32_16x16x32_bf16 v[68:71], v[180:183], v[224:227], v[68:71]
	v_mfma_f32_16x16x32_bf16 v[64:67], v[188:191], v[224:227], v[64:67]
	v_mfma_f32_16x16x32_bf16 v[116:119], v[184:187], v[204:207], v[116:119]
	v_mfma_f32_16x16x32_bf16 v[112:115], v[196:199], v[204:207], v[112:115]
	v_mfma_f32_16x16x32_bf16 v[100:103], v[184:187], v[212:215], v[100:103]
	v_mfma_f32_16x16x32_bf16 v[96:99], v[196:199], v[212:215], v[96:99]
	v_mfma_f32_16x16x32_bf16 v[84:87], v[184:187], v[220:223], v[84:87]
	v_mfma_f32_16x16x32_bf16 v[80:83], v[196:199], v[220:223], v[80:83]
	v_mfma_f32_16x16x32_bf16 v[68:71], v[184:187], v[228:231], v[68:71]
	v_mfma_f32_16x16x32_bf16 v[64:67], v[196:199], v[228:231], v[64:67]
	s_barrier
	s_add_i32 s6, s6, s36
	s_add_u32 s98, s58, 0x80
	s_addc_u32 s99, s59, 0
	s_add_u32 s100, s60, 0x80
	s_addc_u32 s101, s61, 0
	s_mov_b32 m0, s6
	ds_read_b128 v[200:203], v158 offset:49152
	ds_read_b128 v[204:207], v158 offset:50176
	ds_read_b128 v[208:211], v158 offset:51200
	ds_read_b128 v[212:215], v158 offset:52224
	ds_read_b128 v[216:219], v158 offset:53248
	ds_read_b128 v[220:223], v158 offset:54272
	ds_read_b128 v[224:227], v158 offset:55296
	ds_read_b128 v[228:231], v158 offset:56320
	global_load_lds_dwordx4 v134, s[98:99]
	s_add_i32 m0, s6, 0x2000
	s_add_u32 s54, s58, 0xb0080
	s_addc_u32 s55, s59, 0
	s_add_i32 s6, s7, s36
	global_load_lds_dwordx4 v138, s[98:99]
	s_mov_b32 m0, s6
	s_nop 0
	global_load_lds_dwordx4 v134, s[54:55]
	s_add_i32 m0, s6, 0x2000
	s_nop 0
	global_load_lds_dwordx4 v138, s[54:55]
	s_mov_b32 m0, s78
	s_nop 0
	global_load_lds_dwordx4 v132, s[100:101]
	s_mov_b32 m0, s79
	s_nop 0
	global_load_lds_dwordx4 v136, s[100:101]
	s_waitcnt vmcnt(8)
	s_waitcnt lgkmcnt(0)
	s_barrier
	s_waitcnt lgkmcnt(0)
	v_mfma_f32_16x16x32_bf16 v[60:63], v[148:151], v[200:203], v[60:63]
	v_mfma_f32_16x16x32_bf16 v[56:59], v[172:175], v[200:203], v[56:59]
	v_mfma_f32_16x16x32_bf16 v[44:47], v[148:151], v[208:211], v[44:47]
	v_mfma_f32_16x16x32_bf16 v[40:43], v[172:175], v[208:211], v[40:43]
	v_mfma_f32_16x16x32_bf16 v[28:31], v[148:151], v[216:219], v[28:31]
	v_mfma_f32_16x16x32_bf16 v[24:27], v[172:175], v[216:219], v[24:27]
	v_mfma_f32_16x16x32_bf16 v[12:15], v[148:151], v[224:227], v[12:15]
	v_mfma_f32_16x16x32_bf16 v[8:11], v[172:175], v[224:227], v[8:11]
	v_mfma_f32_16x16x32_bf16 v[60:63], v[166:169], v[204:207], v[60:63]
	v_mfma_f32_16x16x32_bf16 v[56:59], v[176:179], v[204:207], v[56:59]
	v_mfma_f32_16x16x32_bf16 v[44:47], v[166:169], v[212:215], v[44:47]
	v_mfma_f32_16x16x32_bf16 v[40:43], v[176:179], v[212:215], v[40:43]
	v_mfma_f32_16x16x32_bf16 v[28:31], v[166:169], v[220:223], v[28:31]
	v_mfma_f32_16x16x32_bf16 v[24:27], v[176:179], v[220:223], v[24:27]
	v_mfma_f32_16x16x32_bf16 v[12:15], v[166:169], v[228:231], v[12:15]
	v_mfma_f32_16x16x32_bf16 v[8:11], v[176:179], v[228:231], v[8:11]
	v_mfma_f32_16x16x32_bf16 v[52:55], v[180:183], v[200:203], v[52:55]
	v_mfma_f32_16x16x32_bf16 v[48:51], v[188:191], v[200:203], v[48:51]
	v_mfma_f32_16x16x32_bf16 v[36:39], v[180:183], v[208:211], v[36:39]
	v_mfma_f32_16x16x32_bf16 v[32:35], v[188:191], v[208:211], v[32:35]
	v_mfma_f32_16x16x32_bf16 v[20:23], v[180:183], v[216:219], v[20:23]
	v_mfma_f32_16x16x32_bf16 v[16:19], v[188:191], v[216:219], v[16:19]
	v_mfma_f32_16x16x32_bf16 v[4:7], v[180:183], v[224:227], v[4:7]
	v_mfma_f32_16x16x32_bf16 v[0:3], v[188:191], v[224:227], v[0:3]
	v_mfma_f32_16x16x32_bf16 v[52:55], v[184:187], v[204:207], v[52:55]
	v_mfma_f32_16x16x32_bf16 v[48:51], v[196:199], v[204:207], v[48:51]
	v_mfma_f32_16x16x32_bf16 v[36:39], v[184:187], v[212:215], v[36:39]
	v_mfma_f32_16x16x32_bf16 v[32:35], v[196:199], v[212:215], v[32:35]
	v_mfma_f32_16x16x32_bf16 v[20:23], v[184:187], v[220:223], v[20:23]
	v_mfma_f32_16x16x32_bf16 v[16:19], v[196:199], v[220:223], v[16:19]
	v_mfma_f32_16x16x32_bf16 v[4:7], v[184:187], v[228:231], v[4:7]
	v_mfma_f32_16x16x32_bf16 v[0:3], v[196:199], v[228:231], v[0:3]
	s_barrier
	s_add_i32 s69, s69, 2
	s_add_u32 s4, s4, 0x100
	s_addc_u32 s33, s33, 0
	s_cmp_gt_u32 s69, 41
	s_mov_b64 s[54:55], s[56:57]
	s_cbranch_scc0 .LBB0_323
	s_and_b64 vcc, exec, s[40:41]
	s_cbranch_vccz .LBB0_326
	s_barrier

; #define PG8_STAGE(bufoff, gbase, voff) do { _Pragma("unroll") for (int _i = 0; _i < 2; ++_i) \
;         __builtin_amdgcn_global_load_lds((const unsigned*)((const char*)(gbase) + (voff)[_i]), (PG8_LAS unsigned*)(lds + (bufoff) + ldsw + _i * 8192), 16, 0, 0); } while (0)
; #define PG8_LDA(dst, b, h) do { _Pragma("unroll") for (int m = 0; m < 4; ++m) _Pragma("unroll") for (int k = 0; k < 2; ++k) dst[m][k] = *(const PG8_LAS bf16x8*)(lds + PG8_SA(b, h) + aoff + m * 2048 + k * 1024); } while (0)
; #define PG8_LDB(dst, b, h) do { _Pragma("unroll") for (int n = 0; n < 2; ++n) _Pragma("unroll") for (int k = 0; k < 2; ++k) dst[n][k] = *(const PG8_LAS bf16x8*)(lds + PG8_SB(b, h) + boff + n * 2048 + k * 1024); } while (0)
; #define PG8_MMA(ai, bj, At, Bt) do { __builtin_amdgcn_s_setprio(1); _Pragma("unroll") for (int m = 0; m < 4; ++m) _Pragma("unroll") for (int n = 0; n < 2; ++n) _Pragma("unroll") for (int k = 0; k < 2; ++k) \
;         acc[ai][bj][m][n] = __builtin_amdgcn_mfma_f32_16x16x32_bf16(Bt[n][k], At[m][k], acc[ai][bj][m][n], 0, 0, 0); __builtin_amdgcn_s_setprio(0); } while (0)
; #define PG8_WAIT_V(n) asm volatile("s_waitcnt vmcnt(" #n ")" ::: "memory")
; #define PG8_WAIT_L(n) asm volatile("s_waitcnt lgkmcnt(" #n ")" ::: "memory")
; template <class Epi, class Sched, bool ALIGN_EPI = false, bool SP2 = false>
; __device__ __forceinline__ void gemm_phase(PG8_LAS unsigned char* lds, const Gemm g, const Sched& S, const Epi& E) {
;     ...
;             const bool last = (t == nt - 2);
;             const char* a1 = cA + (size_t)(t + 1) * kstep;
;             const char* a2 = last ? nA : cA + (size_t)(t + 2) * kstep; const char* b2 = last ? nB : cB + (size_t)(t + 2) * kstep;
;             const char* a3 = a2 + kstep; const char* b3 = b2 + kstep;
;             if (last && has_next) S.a_ready(nxt);
;             if constexpr (SP2) {
;             PG8_LDB(B0, 0, 0); PG8_LDB(B1, 0, 1); PG8_SCHED; PG8_LDA(At, 0, 0); PG8_STAGE(PG8_SA(1, 1), a1 + hstep, voffA);
;             PG8_WAIT_V(8); PG8_WAIT_L(0); PG8_BAR; PG8_MMA(0, 0, At, B0); PG8_MMA(0, 1, At, B1); PG8_BAR; PG8_SCHED;
;             PG8_LDA(At, 0, 1); PG8_STAGE(PG8_SB(0, 0), b2, voffB); PG8_STAGE(PG8_SB(0, 1), b2 + hstep, voffB); PG8_STAGE(PG8_SA(0, 0), a2, voffA);
;             PG8_WAIT_V(8); PG8_WAIT_L(0); PG8_BAR; PG8_MMA(1, 0, At, B0); PG8_MMA(1, 1, At, B1); PG8_BAR; PG8_SCHED;
.LBB0_463:
	ds_read_b128 v[152:155], v172
	ds_read_b128 v[156:159], v172 offset:1024
	ds_read_b128 v[166:169], v172 offset:2048
	ds_read_b128 v[176:179], v172 offset:3072
	ds_read_b128 v[180:183], v173
	ds_read_b128 v[184:187], v173 offset:1024
	ds_read_b128 v[188:191], v173 offset:2048
	ds_read_b128 v[196:199], v173 offset:3072
	s_add_u32 s6, s60, 0xfffc0080
	s_addc_u32 s7, s61, -1
	s_cmp_eq_u32 s72, 12
	s_cselect_b32 s81, s49, s7
	s_cselect_b32 s80, s55, s6
	s_cselect_b32 s79, s53, s33
	s_cselect_b32 s78, vcc_lo, vcc_hi
	s_add_i32 m0, s31, 0xc000
	ds_read_b128 v[200:203], v174
	ds_read_b128 v[204:207], v174 offset:1024
	ds_read_b128 v[208:211], v174 offset:2048
	ds_read_b128 v[212:215], v174 offset:3072
	ds_read_b128 v[216:219], v174 offset:4096
	ds_read_b128 v[220:223], v174 offset:5120
	ds_read_b128 v[224:227], v174 offset:6144
	ds_read_b128 v[228:231], v174 offset:7168
	global_load_lds_dwordx4 v144, s[60:61]
	s_add_i32 m0, s31, 0xe000
	s_nop 0
	global_load_lds_dwordx4 v146, s[60:61]
	s_waitcnt vmcnt(8)
	s_waitcnt lgkmcnt(0)
	s_barrier
	s_waitcnt lgkmcnt(0)
	v_mfma_f32_16x16x32_bf16 v[124:127], v[152:155], v[200:203], v[124:127]
	v_mfma_f32_16x16x32_bf16 v[120:123], v[166:169], v[200:203], v[120:123]
	v_mfma_f32_16x16x32_bf16 v[108:111], v[152:155], v[208:211], v[108:111]
	v_mfma_f32_16x16x32_bf16 v[104:107], v[166:169], v[208:211], v[104:107]
	v_mfma_f32_16x16x32_bf16 v[92:95], v[152:155], v[216:219], v[92:95]
	v_mfma_f32_16x16x32_bf16 v[88:91], v[166:169], v[216:219], v[88:91]
	v_mfma_f32_16x16x32_bf16 v[76:79], v[152:155], v[224:227], v[76:79]
	v_mfma_f32_16x16x32_bf16 v[72:75], v[166:169], v[224:227], v[72:75]
	v_mfma_f32_16x16x32_bf16 v[124:127], v[156:159], v[204:207], v[124:127]
	v_mfma_f32_16x16x32_bf16 v[120:123], v[176:179], v[204:207], v[120:123]
	v_mfma_f32_16x16x32_bf16 v[108:111], v[156:159], v[212:215], v[108:111]
	v_mfma_f32_16x16x32_bf16 v[104:107], v[176:179], v[212:215], v[104:107]
	v_mfma_f32_16x16x32_bf16 v[92:95], v[156:159], v[220:223], v[92:95]
	v_mfma_f32_16x16x32_bf16 v[88:91], v[176:179], v[220:223], v[88:91]
	v_mfma_f32_16x16x32_bf16 v[76:79], v[156:159], v[228:231], v[76:79]
	v_mfma_f32_16x16x32_bf16 v[72:75], v[176:179], v[228:231], v[72:75]
	v_mfma_f32_16x16x32_bf16 v[116:119], v[180:183], v[200:203], v[116:119]
	v_mfma_f32_16x16x32_bf16 v[112:115], v[188:191], v[200:203], v[112:115]
	v_mfma_f32_16x16x32_bf16 v[100:103], v[180:183], v[208:211], v[100:103]
	v_mfma_f32_16x16x32_bf16 v[96:99], v[188:191], v[208:211], v[96:99]
	v_mfma_f32_16x16x32_bf16 v[84:87], v[180:183], v[216:219], v[84:87]
	v_mfma_f32_16x16x32_bf16 v[80:83], v[188:191], v[216:219], v[80:83]
	v_mfma_f32_16x16x32_bf16 v[68:71], v[180:183], v[224:227], v[68:71]
	v_mfma_f32_16x16x32_bf16 v[64:67], v[188:191], v[224:227], v[64:67]
	v_mfma_f32_16x16x32_bf16 v[116:119], v[184:187], v[204:207], v[116:119]
	v_mfma_f32_16x16x32_bf16 v[112:115], v[196:199], v[204:207], v[112:115]
	v_mfma_f32_16x16x32_bf16 v[100:103], v[184:187], v[212:215], v[100:103]
	v_mfma_f32_16x16x32_bf16 v[96:99], v[196:199], v[212:215], v[96:99]
	v_mfma_f32_16x16x32_bf16 v[84:87], v[184:187], v[220:223], v[84:87]
	v_mfma_f32_16x16x32_bf16 v[80:83], v[196:199], v[220:223], v[80:83]
	v_mfma_f32_16x16x32_bf16 v[68:71], v[184:187], v[228:231], v[68:71]
	v_mfma_f32_16x16x32_bf16 v[64:67], v[196:199], v[228:231], v[64:67]
	s_barrier
	s_add_i32 s6, s69, s30
	s_mov_b32 m0, s6
	ds_read_b128 v[200:203], v174 offset:16384
	ds_read_b128 v[204:207], v174 offset:17408
	ds_read_b128 v[208:211], v174 offset:18432
	ds_read_b128 v[212:215], v174 offset:19456
	ds_read_b128 v[216:219], v174 offset:20480
	ds_read_b128 v[220:223], v174 offset:21504
	ds_read_b128 v[224:227], v174 offset:22528
	ds_read_b128 v[228:231], v174 offset:23552
	global_load_lds_dwordx4 v134, s[78:79]
	s_add_i32 m0, s6, 0x2000
	s_add_u32 s6, s78, 0x40000
	s_addc_u32 s7, s79, 0
	s_add_i32 s73, s74, s30
	global_load_lds_dwordx4 v138, s[78:79]
	s_mov_b32 m0, s73
	s_nop 0
	global_load_lds_dwordx4 v134, s[6:7]
	s_add_i32 m0, s73, 0x2000
	s_nop 0
	global_load_lds_dwordx4 v138, s[6:7]
	s_mov_b32 m0, s31
	s_nop 0
	global_load_lds_dwordx4 v132, s[80:81]
	s_mov_b32 m0, s36
	s_nop 0
	global_load_lds_dwordx4 v136, s[80:81]
	s_waitcnt vmcnt(8)
	s_waitcnt lgkmcnt(0)
	s_barrier
	s_waitcnt lgkmcnt(0)
	v_mfma_f32_16x16x32_bf16 v[60:63], v[152:155], v[200:203], v[60:63]
	v_mfma_f32_16x16x32_bf16 v[56:59], v[166:169], v[200:203], v[56:59]
	v_mfma_f32_16x16x32_bf16 v[44:47], v[152:155], v[208:211], v[44:47]
	v_mfma_f32_16x16x32_bf16 v[40:43], v[166:169], v[208:211], v[40:43]
	v_mfma_f32_16x16x32_bf16 v[28:31], v[152:155], v[216:219], v[28:31]
	v_mfma_f32_16x16x32_bf16 v[24:27], v[166:169], v[216:219], v[24:27]
	v_mfma_f32_16x16x32_bf16 v[12:15], v[152:155], v[224:227], v[12:15]
	v_mfma_f32_16x16x32_bf16 v[8:11], v[166:169], v[224:227], v[8:11]
	v_mfma_f32_16x16x32_bf16 v[60:63], v[156:159], v[204:207], v[60:63]
	v_mfma_f32_16x16x32_bf16 v[56:59], v[176:179], v[204:207], v[56:59]
	v_mfma_f32_16x16x32_bf16 v[44:47], v[156:159], v[212:215], v[44:47]
	v_mfma_f32_16x16x32_bf16 v[40:43], v[176:179], v[212:215], v[40:43]
	v_mfma_f32_16x16x32_bf16 v[28:31], v[156:159], v[220:223], v[28:31]
	v_mfma_f32_16x16x32_bf16 v[24:27], v[176:179], v[220:223], v[24:27]
	v_mfma_f32_16x16x32_bf16 v[12:15], v[156:159], v[228:231], v[12:15]
	v_mfma_f32_16x16x32_bf16 v[8:11], v[176:179], v[228:231], v[8:11]
	v_mfma_f32_16x16x32_bf16 v[52:55], v[180:183], v[200:203], v[52:55]
	v_mfma_f32_16x16x32_bf16 v[48:51], v[188:191], v[200:203], v[48:51]
	v_mfma_f32_16x16x32_bf16 v[36:39], v[180:183], v[208:211], v[36:39]
	v_mfma_f32_16x16x32_bf16 v[32:35], v[188:191], v[208:211], v[32:35]
	v_mfma_f32_16x16x32_bf16 v[20:23], v[180:183], v[216:219], v[20:23]
	v_mfma_f32_16x16x32_bf16 v[16:19], v[188:191], v[216:219], v[16:19]
	v_mfma_f32_16x16x32_bf16 v[4:7], v[180:183], v[224:227], v[4:7]
	v_mfma_f32_16x16x32_bf16 v[0:3], v[188:191], v[224:227], v[0:3]
	v_mfma_f32_16x16x32_bf16 v[52:55], v[184:187], v[204:207], v[52:55]
	v_mfma_f32_16x16x32_bf16 v[48:51], v[196:199], v[204:207], v[48:51]
	v_mfma_f32_16x16x32_bf16 v[36:39], v[184:187], v[212:215], v[36:39]
	v_mfma_f32_16x16x32_bf16 v[32:35], v[196:199], v[212:215], v[32:35]
	v_mfma_f32_16x16x32_bf16 v[20:23], v[184:187], v[220:223], v[20:23]
	v_mfma_f32_16x16x32_bf16 v[16:19], v[196:199], v[220:223], v[16:19]
	v_mfma_f32_16x16x32_bf16 v[4:7], v[184:187], v[228:231], v[4:7]
	v_mfma_f32_16x16x32_bf16 v[0:3], v[196:199], v[228:231], v[0:3]
	s_barrier
; #define PG8_STAGE(bufoff, gbase, voff) do { _Pragma("unroll") for (int _i = 0; _i < 2; ++_i) \
;         __builtin_amdgcn_global_load_lds((const unsigned*)((const char*)(gbase) + (voff)[_i]), (PG8_LAS unsigned*)(lds + (bufoff) + ldsw + _i * 8192), 16, 0, 0); } while (0)
; #define PG8_LDA(dst, b, h) do { _Pragma("unroll") for (int m = 0; m < 4; ++m) _Pragma("unroll") for (int k = 0; k < 2; ++k) dst[m][k] = *(const PG8_LAS bf16x8*)(lds + PG8_SA(b, h) + aoff + m * 2048 + k * 1024); } while (0)
; #define PG8_LDB(dst, b, h) do { _Pragma("unroll") for (int n = 0; n < 2; ++n) _Pragma("unroll") for (int k = 0; k < 2; ++k) dst[n][k] = *(const PG8_LAS bf16x8*)(lds + PG8_SB(b, h) + boff + n * 2048 + k * 1024); } while (0)
; #define PG8_MMA(ai, bj, At, Bt) do { __builtin_amdgcn_s_setprio(1); _Pragma("unroll") for (int m = 0; m < 4; ++m) _Pragma("unroll") for (int n = 0; n < 2; ++n) _Pragma("unroll") for (int k = 0; k < 2; ++k) \
;         acc[ai][bj][m][n] = __builtin_amdgcn_mfma_f32_16x16x32_bf16(Bt[n][k], At[m][k], acc[ai][bj][m][n], 0, 0, 0); __builtin_amdgcn_s_setprio(0); } while (0)
; #define PG8_WAIT_V(n) asm volatile("s_waitcnt vmcnt(" #n ")" ::: "memory")
; #define PG8_WAIT_L(n) asm volatile("s_waitcnt lgkmcnt(" #n ")" ::: "memory")
; #define PG8_BAR __builtin_amdgcn_s_barrier()
; #define PG8_SCHED __builtin_amdgcn_sched_barrier(0)
; template <class Epi, class Sched, bool ALIGN_EPI = false, bool SP2 = false>
; __device__ __forceinline__ void gemm_phase(PG8_LAS unsigned char* lds, const Gemm g, const Sched& S, const Epi& E) {
;     ...
;             PG8_LDB(B0, 1, 0); PG8_LDB(B1, 1, 1); PG8_SCHED; PG8_LDA(At, 1, 0); PG8_STAGE(PG8_SA(0, 1), a2 + hstep, voffA);
;             PG8_WAIT_V(8); PG8_WAIT_L(0); PG8_BAR; PG8_MMA(0, 0, At, B0); PG8_MMA(0, 1, At, B1); PG8_BAR; PG8_SCHED;
;             PG8_LDA(At, 1, 1); PG8_STAGE(PG8_SB(1, 0), b3, voffB); PG8_STAGE(PG8_SB(1, 1), b3 + hstep, voffB); PG8_STAGE(PG8_SA(1, 0), a3, voffA);
;             PG8_WAIT_V(8); PG8_WAIT_L(0); PG8_BAR; PG8_MMA(1, 0, At, B0); PG8_MMA(1, 1, At, B1); PG8_BAR; PG8_SCHED;
	s_add_i32 s73, 0, 0x18000
	v_add_u32_e32 v175, s73, v143
	s_add_i32 s82, 0, 0x1c000
	ds_read_b128 v[152:155], v175
	ds_read_b128 v[156:159], v175 offset:1024
	ds_read_b128 v[166:169], v175 offset:2048
	ds_read_b128 v[176:179], v175 offset:3072
	v_add_u32_e32 v175, s82, v143
	ds_read_b128 v[180:183], v175
	ds_read_b128 v[184:187], v175 offset:1024
	ds_read_b128 v[188:191], v175 offset:2048
	ds_read_b128 v[196:199], v175 offset:3072
	s_add_u32 s6, s80, 0x40000
	s_addc_u32 s7, s81, 0
	s_mov_b32 m0, s37
	ds_read_b128 v[200:203], v174 offset:32768
	ds_read_b128 v[204:207], v174 offset:33792
	ds_read_b128 v[208:211], v174 offset:34816
	ds_read_b128 v[212:215], v174 offset:35840
	ds_read_b128 v[216:219], v174 offset:36864
	ds_read_b128 v[220:223], v174 offset:37888
	ds_read_b128 v[224:227], v174 offset:38912
	ds_read_b128 v[228:231], v174 offset:39936
	global_load_lds_dwordx4 v132, s[6:7]
	s_mov_b32 m0, s42
	s_nop 0
	global_load_lds_dwordx4 v136, s[6:7]
	s_waitcnt vmcnt(8)
	s_waitcnt lgkmcnt(0)
	s_barrier
	s_waitcnt lgkmcnt(0)
	v_mfma_f32_16x16x32_bf16 v[124:127], v[152:155], v[200:203], v[124:127]
	v_mfma_f32_16x16x32_bf16 v[120:123], v[166:169], v[200:203], v[120:123]
	v_mfma_f32_16x16x32_bf16 v[108:111], v[152:155], v[208:211], v[108:111]
	v_mfma_f32_16x16x32_bf16 v[104:107], v[166:169], v[208:211], v[104:107]
	v_mfma_f32_16x16x32_bf16 v[92:95], v[152:155], v[216:219], v[92:95]
	v_mfma_f32_16x16x32_bf16 v[88:91], v[166:169], v[216:219], v[88:91]
	v_mfma_f32_16x16x32_bf16 v[76:79], v[152:155], v[224:227], v[76:79]
	v_mfma_f32_16x16x32_bf16 v[72:75], v[166:169], v[224:227], v[72:75]
	v_mfma_f32_16x16x32_bf16 v[124:127], v[156:159], v[204:207], v[124:127]
	v_mfma_f32_16x16x32_bf16 v[120:123], v[176:179], v[204:207], v[120:123]
	v_mfma_f32_16x16x32_bf16 v[108:111], v[156:159], v[212:215], v[108:111]
	v_mfma_f32_16x16x32_bf16 v[104:107], v[176:179], v[212:215], v[104:107]
	v_mfma_f32_16x16x32_bf16 v[92:95], v[156:159], v[220:223], v[92:95]
	v_mfma_f32_16x16x32_bf16 v[88:91], v[176:179], v[220:223], v[88:91]
	v_mfma_f32_16x16x32_bf16 v[76:79], v[156:159], v[228:231], v[76:79]
	v_mfma_f32_16x16x32_bf16 v[72:75], v[176:179], v[228:231], v[72:75]
	v_mfma_f32_16x16x32_bf16 v[116:119], v[180:183], v[200:203], v[116:119]
	v_mfma_f32_16x16x32_bf16 v[112:115], v[188:191], v[200:203], v[112:115]
	v_mfma_f32_16x16x32_bf16 v[100:103], v[180:183], v[208:211], v[100:103]
	v_mfma_f32_16x16x32_bf16 v[96:99], v[188:191], v[208:211], v[96:99]
	v_mfma_f32_16x16x32_bf16 v[84:87], v[180:183], v[216:219], v[84:87]
	v_mfma_f32_16x16x32_bf16 v[80:83], v[188:191], v[216:219], v[80:83]
	v_mfma_f32_16x16x32_bf16 v[68:71], v[180:183], v[224:227], v[68:71]
	v_mfma_f32_16x16x32_bf16 v[64:67], v[188:191], v[224:227], v[64:67]
	v_mfma_f32_16x16x32_bf16 v[116:119], v[184:187], v[204:207], v[116:119]
	v_mfma_f32_16x16x32_bf16 v[112:115], v[196:199], v[204:207], v[112:115]
	v_mfma_f32_16x16x32_bf16 v[100:103], v[184:187], v[212:215], v[100:103]
	v_mfma_f32_16x16x32_bf16 v[96:99], v[196:199], v[212:215], v[96:99]
	v_mfma_f32_16x16x32_bf16 v[84:87], v[184:187], v[220:223], v[84:87]
	v_mfma_f32_16x16x32_bf16 v[80:83], v[196:199], v[220:223], v[80:83]
	v_mfma_f32_16x16x32_bf16 v[68:71], v[184:187], v[228:231], v[68:71]
	v_mfma_f32_16x16x32_bf16 v[64:67], v[196:199], v[228:231], v[64:67]
	s_barrier
	s_add_i32 s6, s73, s30
	s_add_u32 s98, s78, 0x80
	s_addc_u32 s99, s79, 0
	s_add_u32 s100, s80, 0x80
	s_addc_u32 s101, s81, 0
	s_mov_b32 m0, s6
	ds_read_b128 v[200:203], v174 offset:49152
	ds_read_b128 v[204:207], v174 offset:50176
	ds_read_b128 v[208:211], v174 offset:51200
	ds_read_b128 v[212:215], v174 offset:52224
	ds_read_b128 v[216:219], v174 offset:53248
	ds_read_b128 v[220:223], v174 offset:54272
	ds_read_b128 v[224:227], v174 offset:55296
	ds_read_b128 v[228:231], v174 offset:56320
	global_load_lds_dwordx4 v134, s[98:99]
	s_add_i32 m0, s6, 0x2000
	s_add_u32 s6, s78, 0x40080
	s_addc_u32 s7, s79, 0
	s_add_i32 s73, s82, s30
	global_load_lds_dwordx4 v138, s[98:99]
	s_mov_b32 m0, s73
	s_nop 0
	global_load_lds_dwordx4 v134, s[6:7]
	s_add_i32 m0, s73, 0x2000
	s_nop 0
	global_load_lds_dwordx4 v138, s[6:7]
	s_mov_b32 m0, s67
	s_nop 0
	global_load_lds_dwordx4 v132, s[100:101]
	s_mov_b32 m0, s68
	s_nop 0
	global_load_lds_dwordx4 v136, s[100:101]
	s_waitcnt vmcnt(8)
	s_waitcnt lgkmcnt(0)
	s_barrier
	s_waitcnt lgkmcnt(0)
	v_mfma_f32_16x16x32_bf16 v[60:63], v[152:155], v[200:203], v[60:63]
	v_mfma_f32_16x16x32_bf16 v[56:59], v[166:169], v[200:203], v[56:59]
	v_mfma_f32_16x16x32_bf16 v[44:47], v[152:155], v[208:211], v[44:47]
	v_mfma_f32_16x16x32_bf16 v[40:43], v[166:169], v[208:211], v[40:43]
	v_mfma_f32_16x16x32_bf16 v[28:31], v[152:155], v[216:219], v[28:31]
	v_mfma_f32_16x16x32_bf16 v[24:27], v[166:169], v[216:219], v[24:27]
	v_mfma_f32_16x16x32_bf16 v[12:15], v[152:155], v[224:227], v[12:15]
	v_mfma_f32_16x16x32_bf16 v[8:11], v[166:169], v[224:227], v[8:11]
	v_mfma_f32_16x16x32_bf16 v[60:63], v[156:159], v[204:207], v[60:63]
	v_mfma_f32_16x16x32_bf16 v[56:59], v[176:179], v[204:207], v[56:59]
	v_mfma_f32_16x16x32_bf16 v[44:47], v[156:159], v[212:215], v[44:47]
	v_mfma_f32_16x16x32_bf16 v[40:43], v[176:179], v[212:215], v[40:43]
	v_mfma_f32_16x16x32_bf16 v[28:31], v[156:159], v[220:223], v[28:31]
	v_mfma_f32_16x16x32_bf16 v[24:27], v[176:179], v[220:223], v[24:27]
	v_mfma_f32_16x16x32_bf16 v[12:15], v[156:159], v[228:231], v[12:15]
	v_mfma_f32_16x16x32_bf16 v[8:11], v[176:179], v[228:231], v[8:11]
	v_mfma_f32_16x16x32_bf16 v[52:55], v[180:183], v[200:203], v[52:55]
	v_mfma_f32_16x16x32_bf16 v[48:51], v[188:191], v[200:203], v[48:51]
	v_mfma_f32_16x16x32_bf16 v[36:39], v[180:183], v[208:211], v[36:39]
	v_mfma_f32_16x16x32_bf16 v[32:35], v[188:191], v[208:211], v[32:35]
	v_mfma_f32_16x16x32_bf16 v[20:23], v[180:183], v[216:219], v[20:23]
	v_mfma_f32_16x16x32_bf16 v[16:19], v[188:191], v[216:219], v[16:19]
	v_mfma_f32_16x16x32_bf16 v[4:7], v[180:183], v[224:227], v[4:7]
	v_mfma_f32_16x16x32_bf16 v[0:3], v[188:191], v[224:227], v[0:3]
	v_mfma_f32_16x16x32_bf16 v[52:55], v[184:187], v[204:207], v[52:55]
	v_mfma_f32_16x16x32_bf16 v[48:51], v[196:199], v[204:207], v[48:51]
	v_mfma_f32_16x16x32_bf16 v[36:39], v[184:187], v[212:215], v[36:39]
	v_mfma_f32_16x16x32_bf16 v[32:35], v[196:199], v[212:215], v[32:35]
	v_mfma_f32_16x16x32_bf16 v[20:23], v[184:187], v[220:223], v[20:23]
	v_mfma_f32_16x16x32_bf16 v[16:19], v[196:199], v[220:223], v[16:19]
	v_mfma_f32_16x16x32_bf16 v[4:7], v[184:187], v[228:231], v[4:7]
	v_mfma_f32_16x16x32_bf16 v[0:3], v[196:199], v[228:231], v[0:3]
	s_barrier
	s_add_i32 s72, s72, 2
	s_add_u32 s60, s60, 0x100
	s_addc_u32 s61, s61, 0
	s_add_u32 vcc_hi, vcc_hi, 0x100
	s_addc_u32 s33, s33, 0
	s_cmp_gt_u32 s72, 13
	s_cbranch_scc0 .LBB0_463
	s_and_b64 vcc, exec, s[50:51]
	s_cbranch_vccz .LBB0_466
	s_barrier

; #define PG8_STAGE(bufoff, gbase, voff) do { _Pragma("unroll") for (int _i = 0; _i < 2; ++_i) \
;         __builtin_amdgcn_global_load_lds((const unsigned*)((const char*)(gbase) + (voff)[_i]), (PG8_LAS unsigned*)(lds + (bufoff) + ldsw + _i * 8192), 16, 0, 0); } while (0)
; #define PG8_LDA(dst, b, h) do { _Pragma("unroll") for (int m = 0; m < 4; ++m) _Pragma("unroll") for (int k = 0; k < 2; ++k) dst[m][k] = *(const PG8_LAS bf16x8*)(lds + PG8_SA(b, h) + aoff + m * 2048 + k * 1024); } while (0)
; #define PG8_LDB(dst, b, h) do { _Pragma("unroll") for (int n = 0; n < 2; ++n) _Pragma("unroll") for (int k = 0; k < 2; ++k) dst[n][k] = *(const PG8_LAS bf16x8*)(lds + PG8_SB(b, h) + boff + n * 2048 + k * 1024); } while (0)
; #define PG8_MMA(ai, bj, At, Bt) do { __builtin_amdgcn_s_setprio(1); _Pragma("unroll") for (int m = 0; m < 4; ++m) _Pragma("unroll") for (int n = 0; n < 2; ++n) _Pragma("unroll") for (int k = 0; k < 2; ++k) \
;         acc[ai][bj][m][n] = __builtin_amdgcn_mfma_f32_16x16x32_bf16(Bt[n][k], At[m][k], acc[ai][bj][m][n], 0, 0, 0); __builtin_amdgcn_s_setprio(0); } while (0)
; #define PG8_WAIT_V(n) asm volatile("s_waitcnt vmcnt(" #n ")" ::: "memory")
; #define PG8_WAIT_L(n) asm volatile("s_waitcnt lgkmcnt(" #n ")" ::: "memory")
; template <class Epi, class Sched, bool ALIGN_EPI = false, bool SP2 = false>
; __device__ __forceinline__ void gemm_phase(PG8_LAS unsigned char* lds, const Gemm g, const Sched& S, const Epi& E) {
;     ...
;             const bool last = (t == nt - 2);
;             const char* a1 = cA + (size_t)(t + 1) * kstep;
;             const char* a2 = last ? nA : cA + (size_t)(t + 2) * kstep; const char* b2 = last ? nB : cB + (size_t)(t + 2) * kstep;
;             const char* a3 = a2 + kstep; const char* b3 = b2 + kstep;
;             if (last && has_next) S.a_ready(nxt);
;             if constexpr (SP2) {
;             PG8_LDB(B0, 0, 0); PG8_LDB(B1, 0, 1); PG8_SCHED; PG8_LDA(At, 0, 0); PG8_STAGE(PG8_SA(1, 1), a1 + hstep, voffA);
;             PG8_WAIT_V(8); PG8_WAIT_L(0); PG8_BAR; PG8_MMA(0, 0, At, B0); PG8_MMA(0, 1, At, B1); PG8_BAR; PG8_SCHED;
;             PG8_LDA(At, 0, 1); PG8_STAGE(PG8_SB(0, 0), b2, voffB); PG8_STAGE(PG8_SB(0, 1), b2 + hstep, voffB); PG8_STAGE(PG8_SA(0, 0), a2, voffA);
;             PG8_WAIT_V(8); PG8_WAIT_L(0); PG8_BAR; PG8_MMA(1, 0, At, B0); PG8_MMA(1, 1, At, B1); PG8_BAR; PG8_SCHED;
.LBB0_777:
	ds_read_b128 v[144:147], v158
	ds_read_b128 v[168:171], v158 offset:1024
	ds_read_b128 v[172:175], v158 offset:2048
	ds_read_b128 v[176:179], v158 offset:3072
	ds_read_b128 v[180:183], v159
	ds_read_b128 v[184:187], v159 offset:1024
	ds_read_b128 v[188:191], v159 offset:2048
	ds_read_b128 v[196:199], v159 offset:3072
	s_add_u32 s60, s58, 0x100
	s_addc_u32 s61, s59, 0
	s_cmp_eq_u32 s72, 8
	s_cselect_b32 s81, s49, s61
	s_cselect_b32 s80, s48, s60
	s_cselect_b32 s79, s57, vcc_lo
	s_cselect_b32 s78, s56, s33
	s_add_i32 m0, s76, 0xc000
	ds_read_b128 v[200:203], v163
	ds_read_b128 v[204:207], v163 offset:1024
	ds_read_b128 v[208:211], v163 offset:2048
	ds_read_b128 v[212:215], v163 offset:3072
	ds_read_b128 v[216:219], v163 offset:4096
	ds_read_b128 v[220:223], v163 offset:5120
	ds_read_b128 v[224:227], v163 offset:6144
	ds_read_b128 v[228:231], v163 offset:7168
	global_load_lds_dwordx4 v136, s[58:59]
	s_add_i32 m0, s76, 0xe000
	s_nop 0
	global_load_lds_dwordx4 v138, s[58:59]
	s_waitcnt vmcnt(8)
	s_waitcnt lgkmcnt(0)
	s_barrier
	s_waitcnt lgkmcnt(0)
	v_mfma_f32_16x16x32_bf16 v[124:127], v[144:147], v[200:203], v[124:127]
	v_mfma_f32_16x16x32_bf16 v[120:123], v[172:175], v[200:203], v[120:123]
	v_mfma_f32_16x16x32_bf16 v[108:111], v[144:147], v[208:211], v[108:111]
	v_mfma_f32_16x16x32_bf16 v[104:107], v[172:175], v[208:211], v[104:107]
	v_mfma_f32_16x16x32_bf16 v[92:95], v[144:147], v[216:219], v[92:95]
	v_mfma_f32_16x16x32_bf16 v[88:91], v[172:175], v[216:219], v[88:91]
	v_mfma_f32_16x16x32_bf16 v[76:79], v[144:147], v[224:227], v[76:79]
	v_mfma_f32_16x16x32_bf16 v[72:75], v[172:175], v[224:227], v[72:75]
	v_mfma_f32_16x16x32_bf16 v[124:127], v[168:171], v[204:207], v[124:127]
	v_mfma_f32_16x16x32_bf16 v[120:123], v[176:179], v[204:207], v[120:123]
	v_mfma_f32_16x16x32_bf16 v[108:111], v[168:171], v[212:215], v[108:111]
	v_mfma_f32_16x16x32_bf16 v[104:107], v[176:179], v[212:215], v[104:107]
	v_mfma_f32_16x16x32_bf16 v[92:95], v[168:171], v[220:223], v[92:95]
	v_mfma_f32_16x16x32_bf16 v[88:91], v[176:179], v[220:223], v[88:91]
	v_mfma_f32_16x16x32_bf16 v[76:79], v[168:171], v[228:231], v[76:79]
	v_mfma_f32_16x16x32_bf16 v[72:75], v[176:179], v[228:231], v[72:75]
	v_mfma_f32_16x16x32_bf16 v[116:119], v[180:183], v[200:203], v[116:119]
	v_mfma_f32_16x16x32_bf16 v[112:115], v[188:191], v[200:203], v[112:115]
	v_mfma_f32_16x16x32_bf16 v[100:103], v[180:183], v[208:211], v[100:103]
	v_mfma_f32_16x16x32_bf16 v[96:99], v[188:191], v[208:211], v[96:99]
	v_mfma_f32_16x16x32_bf16 v[84:87], v[180:183], v[216:219], v[84:87]
	v_mfma_f32_16x16x32_bf16 v[80:83], v[188:191], v[216:219], v[80:83]
	v_mfma_f32_16x16x32_bf16 v[68:71], v[180:183], v[224:227], v[68:71]
	v_mfma_f32_16x16x32_bf16 v[64:67], v[188:191], v[224:227], v[64:67]
	v_mfma_f32_16x16x32_bf16 v[116:119], v[184:187], v[204:207], v[116:119]
	v_mfma_f32_16x16x32_bf16 v[112:115], v[196:199], v[204:207], v[112:115]
	v_mfma_f32_16x16x32_bf16 v[100:103], v[184:187], v[212:215], v[100:103]
	v_mfma_f32_16x16x32_bf16 v[96:99], v[196:199], v[212:215], v[96:99]
	v_mfma_f32_16x16x32_bf16 v[84:87], v[184:187], v[220:223], v[84:87]
	v_mfma_f32_16x16x32_bf16 v[80:83], v[196:199], v[220:223], v[80:83]
	v_mfma_f32_16x16x32_bf16 v[68:71], v[184:187], v[228:231], v[68:71]
	v_mfma_f32_16x16x32_bf16 v[64:67], v[196:199], v[228:231], v[64:67]
	s_barrier
	s_add_i32 s6, s26, s67
	s_mov_b32 m0, s6
	ds_read_b128 v[200:203], v163 offset:16384
	ds_read_b128 v[204:207], v163 offset:17408
	ds_read_b128 v[208:211], v163 offset:18432
	ds_read_b128 v[212:215], v163 offset:19456
	ds_read_b128 v[216:219], v163 offset:20480
	ds_read_b128 v[220:223], v163 offset:21504
	ds_read_b128 v[224:227], v163 offset:22528
	ds_read_b128 v[228:231], v163 offset:23552
	global_load_lds_dwordx4 v130, s[78:79]
	s_add_i32 m0, s6, 0x2000
	s_add_u32 s6, s78, 0x30000
	s_addc_u32 s7, s79, 0
	s_add_i32 s58, s74, s67
	global_load_lds_dwordx4 v134, s[78:79]
	s_mov_b32 m0, s58
	s_nop 0
	global_load_lds_dwordx4 v130, s[6:7]
	s_add_i32 m0, s58, 0x2000
	s_nop 0
	global_load_lds_dwordx4 v134, s[6:7]
	s_mov_b32 m0, s76
	s_nop 0
	global_load_lds_dwordx4 v128, s[80:81]
	s_mov_b32 m0, s77
	s_nop 0
	global_load_lds_dwordx4 v132, s[80:81]
	s_waitcnt vmcnt(8)
	s_waitcnt lgkmcnt(0)
	s_barrier
	s_waitcnt lgkmcnt(0)
	v_mfma_f32_16x16x32_bf16 v[60:63], v[144:147], v[200:203], v[60:63]
	v_mfma_f32_16x16x32_bf16 v[56:59], v[172:175], v[200:203], v[56:59]
	v_mfma_f32_16x16x32_bf16 v[44:47], v[144:147], v[208:211], v[44:47]
	v_mfma_f32_16x16x32_bf16 v[40:43], v[172:175], v[208:211], v[40:43]
	v_mfma_f32_16x16x32_bf16 v[28:31], v[144:147], v[216:219], v[28:31]
	v_mfma_f32_16x16x32_bf16 v[24:27], v[172:175], v[216:219], v[24:27]
	v_mfma_f32_16x16x32_bf16 v[12:15], v[144:147], v[224:227], v[12:15]
	v_mfma_f32_16x16x32_bf16 v[8:11], v[172:175], v[224:227], v[8:11]
	v_mfma_f32_16x16x32_bf16 v[60:63], v[168:171], v[204:207], v[60:63]
	v_mfma_f32_16x16x32_bf16 v[56:59], v[176:179], v[204:207], v[56:59]
	v_mfma_f32_16x16x32_bf16 v[44:47], v[168:171], v[212:215], v[44:47]
	v_mfma_f32_16x16x32_bf16 v[40:43], v[176:179], v[212:215], v[40:43]
	v_mfma_f32_16x16x32_bf16 v[28:31], v[168:171], v[220:223], v[28:31]
	v_mfma_f32_16x16x32_bf16 v[24:27], v[176:179], v[220:223], v[24:27]
	v_mfma_f32_16x16x32_bf16 v[12:15], v[168:171], v[228:231], v[12:15]
	v_mfma_f32_16x16x32_bf16 v[8:11], v[176:179], v[228:231], v[8:11]
	v_mfma_f32_16x16x32_bf16 v[52:55], v[180:183], v[200:203], v[52:55]
	v_mfma_f32_16x16x32_bf16 v[48:51], v[188:191], v[200:203], v[48:51]
	v_mfma_f32_16x16x32_bf16 v[36:39], v[180:183], v[208:211], v[36:39]
	v_mfma_f32_16x16x32_bf16 v[32:35], v[188:191], v[208:211], v[32:35]
	v_mfma_f32_16x16x32_bf16 v[20:23], v[180:183], v[216:219], v[20:23]
	v_mfma_f32_16x16x32_bf16 v[16:19], v[188:191], v[216:219], v[16:19]
	v_mfma_f32_16x16x32_bf16 v[4:7], v[180:183], v[224:227], v[4:7]
	v_mfma_f32_16x16x32_bf16 v[0:3], v[188:191], v[224:227], v[0:3]
	v_mfma_f32_16x16x32_bf16 v[52:55], v[184:187], v[204:207], v[52:55]
	v_mfma_f32_16x16x32_bf16 v[48:51], v[196:199], v[204:207], v[48:51]
	v_mfma_f32_16x16x32_bf16 v[36:39], v[184:187], v[212:215], v[36:39]
	v_mfma_f32_16x16x32_bf16 v[32:35], v[196:199], v[212:215], v[32:35]
	v_mfma_f32_16x16x32_bf16 v[20:23], v[184:187], v[220:223], v[20:23]
	v_mfma_f32_16x16x32_bf16 v[16:19], v[196:199], v[220:223], v[16:19]
	v_mfma_f32_16x16x32_bf16 v[4:7], v[184:187], v[228:231], v[4:7]
	v_mfma_f32_16x16x32_bf16 v[0:3], v[196:199], v[228:231], v[0:3]
	s_barrier
; #define PG8_STAGE(bufoff, gbase, voff) do { _Pragma("unroll") for (int _i = 0; _i < 2; ++_i) \
;         __builtin_amdgcn_global_load_lds((const unsigned*)((const char*)(gbase) + (voff)[_i]), (PG8_LAS unsigned*)(lds + (bufoff) + ldsw + _i * 8192), 16, 0, 0); } while (0)
; #define PG8_LDA(dst, b, h) do { _Pragma("unroll") for (int m = 0; m < 4; ++m) _Pragma("unroll") for (int k = 0; k < 2; ++k) dst[m][k] = *(const PG8_LAS bf16x8*)(lds + PG8_SA(b, h) + aoff + m * 2048 + k * 1024); } while (0)
; #define PG8_LDB(dst, b, h) do { _Pragma("unroll") for (int n = 0; n < 2; ++n) _Pragma("unroll") for (int k = 0; k < 2; ++k) dst[n][k] = *(const PG8_LAS bf16x8*)(lds + PG8_SB(b, h) + boff + n * 2048 + k * 1024); } while (0)
; #define PG8_MMA(ai, bj, At, Bt) do { __builtin_amdgcn_s_setprio(1); _Pragma("unroll") for (int m = 0; m < 4; ++m) _Pragma("unroll") for (int n = 0; n < 2; ++n) _Pragma("unroll") for (int k = 0; k < 2; ++k) \
;         acc[ai][bj][m][n] = __builtin_amdgcn_mfma_f32_16x16x32_bf16(Bt[n][k], At[m][k], acc[ai][bj][m][n], 0, 0, 0); __builtin_amdgcn_s_setprio(0); } while (0)
; #define PG8_WAIT_V(n) asm volatile("s_waitcnt vmcnt(" #n ")" ::: "memory")
; #define PG8_WAIT_L(n) asm volatile("s_waitcnt lgkmcnt(" #n ")" ::: "memory")
; #define PG8_BAR __builtin_amdgcn_s_barrier()
; #define PG8_SCHED __builtin_amdgcn_sched_barrier(0)
; template <class Epi, class Sched, bool ALIGN_EPI = false, bool SP2 = false>
; __device__ __forceinline__ void gemm_phase(PG8_LAS unsigned char* lds, const Gemm g, const Sched& S, const Epi& E) {
;     ...
;             PG8_LDB(B0, 1, 0); PG8_LDB(B1, 1, 1); PG8_SCHED; PG8_LDA(At, 1, 0); PG8_STAGE(PG8_SA(0, 1), a2 + hstep, voffA);
;             PG8_WAIT_V(8); PG8_WAIT_L(0); PG8_BAR; PG8_MMA(0, 0, At, B0); PG8_MMA(0, 1, At, B1); PG8_BAR; PG8_SCHED;
;             PG8_LDA(At, 1, 1); PG8_STAGE(PG8_SB(1, 0), b3, voffB); PG8_STAGE(PG8_SB(1, 1), b3 + hstep, voffB); PG8_STAGE(PG8_SA(1, 0), a3, voffA);
;             PG8_WAIT_V(8); PG8_WAIT_L(0); PG8_BAR; PG8_MMA(1, 0, At, B0); PG8_MMA(1, 1, At, B1); PG8_BAR; PG8_SCHED;
	s_add_i32 s58, 0, 0x18000
	v_add_u32_e32 v167, s58, v156
	s_add_i32 s59, 0, 0x1c000
	ds_read_b128 v[144:147], v167
	ds_read_b128 v[168:171], v167 offset:1024
	ds_read_b128 v[172:175], v167 offset:2048
	ds_read_b128 v[176:179], v167 offset:3072
	v_add_u32_e32 v167, s59, v156
	ds_read_b128 v[180:183], v167
	ds_read_b128 v[184:187], v167 offset:1024
	ds_read_b128 v[188:191], v167 offset:2048
	ds_read_b128 v[196:199], v167 offset:3072
	s_add_u32 s6, s80, 0x30000
	s_addc_u32 s7, s81, 0
	s_mov_b32 m0, s36
	ds_read_b128 v[200:203], v163 offset:32768
	ds_read_b128 v[204:207], v163 offset:33792
	ds_read_b128 v[208:211], v163 offset:34816
	ds_read_b128 v[212:215], v163 offset:35840
	ds_read_b128 v[216:219], v163 offset:36864
	ds_read_b128 v[220:223], v163 offset:37888
	ds_read_b128 v[224:227], v163 offset:38912
	ds_read_b128 v[228:231], v163 offset:39936
	global_load_lds_dwordx4 v128, s[6:7]
	s_mov_b32 m0, s37
	s_nop 0
	global_load_lds_dwordx4 v132, s[6:7]
	s_waitcnt vmcnt(8)
	s_waitcnt lgkmcnt(0)
	s_barrier
	s_waitcnt lgkmcnt(0)
	v_mfma_f32_16x16x32_bf16 v[124:127], v[144:147], v[200:203], v[124:127]
	v_mfma_f32_16x16x32_bf16 v[120:123], v[172:175], v[200:203], v[120:123]
	v_mfma_f32_16x16x32_bf16 v[108:111], v[144:147], v[208:211], v[108:111]
	v_mfma_f32_16x16x32_bf16 v[104:107], v[172:175], v[208:211], v[104:107]
	v_mfma_f32_16x16x32_bf16 v[92:95], v[144:147], v[216:219], v[92:95]
	v_mfma_f32_16x16x32_bf16 v[88:91], v[172:175], v[216:219], v[88:91]
	v_mfma_f32_16x16x32_bf16 v[76:79], v[144:147], v[224:227], v[76:79]
	v_mfma_f32_16x16x32_bf16 v[72:75], v[172:175], v[224:227], v[72:75]
	v_mfma_f32_16x16x32_bf16 v[124:127], v[168:171], v[204:207], v[124:127]
	v_mfma_f32_16x16x32_bf16 v[120:123], v[176:179], v[204:207], v[120:123]
	v_mfma_f32_16x16x32_bf16 v[108:111], v[168:171], v[212:215], v[108:111]
	v_mfma_f32_16x16x32_bf16 v[104:107], v[176:179], v[212:215], v[104:107]
	v_mfma_f32_16x16x32_bf16 v[92:95], v[168:171], v[220:223], v[92:95]
	v_mfma_f32_16x16x32_bf16 v[88:91], v[176:179], v[220:223], v[88:91]
	v_mfma_f32_16x16x32_bf16 v[76:79], v[168:171], v[228:231], v[76:79]
	v_mfma_f32_16x16x32_bf16 v[72:75], v[176:179], v[228:231], v[72:75]
	v_mfma_f32_16x16x32_bf16 v[116:119], v[180:183], v[200:203], v[116:119]
	v_mfma_f32_16x16x32_bf16 v[112:115], v[188:191], v[200:203], v[112:115]
	v_mfma_f32_16x16x32_bf16 v[100:103], v[180:183], v[208:211], v[100:103]
	v_mfma_f32_16x16x32_bf16 v[96:99], v[188:191], v[208:211], v[96:99]
	v_mfma_f32_16x16x32_bf16 v[84:87], v[180:183], v[216:219], v[84:87]
	v_mfma_f32_16x16x32_bf16 v[80:83], v[188:191], v[216:219], v[80:83]
	v_mfma_f32_16x16x32_bf16 v[68:71], v[180:183], v[224:227], v[68:71]
	v_mfma_f32_16x16x32_bf16 v[64:67], v[188:191], v[224:227], v[64:67]
	v_mfma_f32_16x16x32_bf16 v[116:119], v[184:187], v[204:207], v[116:119]
	v_mfma_f32_16x16x32_bf16 v[112:115], v[196:199], v[204:207], v[112:115]
	v_mfma_f32_16x16x32_bf16 v[100:103], v[184:187], v[212:215], v[100:103]
	v_mfma_f32_16x16x32_bf16 v[96:99], v[196:199], v[212:215], v[96:99]
	v_mfma_f32_16x16x32_bf16 v[84:87], v[184:187], v[220:223], v[84:87]
	v_mfma_f32_16x16x32_bf16 v[80:83], v[196:199], v[220:223], v[80:83]
	v_mfma_f32_16x16x32_bf16 v[68:71], v[184:187], v[228:231], v[68:71]
	v_mfma_f32_16x16x32_bf16 v[64:67], v[196:199], v[228:231], v[64:67]
	s_barrier
	s_add_i32 s6, s58, s67
	s_add_u32 s98, s78, 0x80
	s_addc_u32 s99, s79, 0
	s_add_u32 s100, s80, 0x80
	s_addc_u32 s101, s81, 0
	s_mov_b32 m0, s6
	ds_read_b128 v[200:203], v163 offset:49152
	ds_read_b128 v[204:207], v163 offset:50176
	ds_read_b128 v[208:211], v163 offset:51200
	ds_read_b128 v[212:215], v163 offset:52224
	ds_read_b128 v[216:219], v163 offset:53248
	ds_read_b128 v[220:223], v163 offset:54272
	ds_read_b128 v[224:227], v163 offset:55296
	ds_read_b128 v[228:231], v163 offset:56320
	global_load_lds_dwordx4 v130, s[98:99]
	s_add_i32 m0, s6, 0x2000
	s_add_u32 s6, s78, 0x30080
	s_addc_u32 s7, s79, 0
	s_add_i32 s58, s59, s67
	global_load_lds_dwordx4 v134, s[98:99]
	s_mov_b32 m0, s58
	s_nop 0
	global_load_lds_dwordx4 v130, s[6:7]
	s_add_i32 m0, s58, 0x2000
	s_nop 0
	global_load_lds_dwordx4 v134, s[6:7]
	s_mov_b32 m0, s31
	s_nop 0
	global_load_lds_dwordx4 v128, s[100:101]
	s_mov_b32 m0, s4
	s_nop 0
	global_load_lds_dwordx4 v132, s[100:101]
	s_waitcnt vmcnt(8)
	s_waitcnt lgkmcnt(0)
	s_barrier
	s_waitcnt lgkmcnt(0)
	v_mfma_f32_16x16x32_bf16 v[60:63], v[144:147], v[200:203], v[60:63]
	v_mfma_f32_16x16x32_bf16 v[56:59], v[172:175], v[200:203], v[56:59]
	v_mfma_f32_16x16x32_bf16 v[44:47], v[144:147], v[208:211], v[44:47]
	v_mfma_f32_16x16x32_bf16 v[40:43], v[172:175], v[208:211], v[40:43]
	v_mfma_f32_16x16x32_bf16 v[28:31], v[144:147], v[216:219], v[28:31]
	v_mfma_f32_16x16x32_bf16 v[24:27], v[172:175], v[216:219], v[24:27]
	v_mfma_f32_16x16x32_bf16 v[12:15], v[144:147], v[224:227], v[12:15]
	v_mfma_f32_16x16x32_bf16 v[8:11], v[172:175], v[224:227], v[8:11]
	v_mfma_f32_16x16x32_bf16 v[60:63], v[168:171], v[204:207], v[60:63]
	v_mfma_f32_16x16x32_bf16 v[56:59], v[176:179], v[204:207], v[56:59]
	v_mfma_f32_16x16x32_bf16 v[44:47], v[168:171], v[212:215], v[44:47]
	v_mfma_f32_16x16x32_bf16 v[40:43], v[176:179], v[212:215], v[40:43]
	v_mfma_f32_16x16x32_bf16 v[28:31], v[168:171], v[220:223], v[28:31]
	v_mfma_f32_16x16x32_bf16 v[24:27], v[176:179], v[220:223], v[24:27]
	v_mfma_f32_16x16x32_bf16 v[12:15], v[168:171], v[228:231], v[12:15]
	v_mfma_f32_16x16x32_bf16 v[8:11], v[176:179], v[228:231], v[8:11]
	v_mfma_f32_16x16x32_bf16 v[52:55], v[180:183], v[200:203], v[52:55]
	v_mfma_f32_16x16x32_bf16 v[48:51], v[188:191], v[200:203], v[48:51]
	v_mfma_f32_16x16x32_bf16 v[36:39], v[180:183], v[208:211], v[36:39]
	v_mfma_f32_16x16x32_bf16 v[32:35], v[188:191], v[208:211], v[32:35]
	v_mfma_f32_16x16x32_bf16 v[20:23], v[180:183], v[216:219], v[20:23]
	v_mfma_f32_16x16x32_bf16 v[16:19], v[188:191], v[216:219], v[16:19]
	v_mfma_f32_16x16x32_bf16 v[4:7], v[180:183], v[224:227], v[4:7]
	v_mfma_f32_16x16x32_bf16 v[0:3], v[188:191], v[224:227], v[0:3]
	v_mfma_f32_16x16x32_bf16 v[52:55], v[184:187], v[204:207], v[52:55]
	v_mfma_f32_16x16x32_bf16 v[48:51], v[196:199], v[204:207], v[48:51]
	v_mfma_f32_16x16x32_bf16 v[36:39], v[184:187], v[212:215], v[36:39]
	v_mfma_f32_16x16x32_bf16 v[32:35], v[196:199], v[212:215], v[32:35]
	v_mfma_f32_16x16x32_bf16 v[20:23], v[184:187], v[220:223], v[20:23]
	v_mfma_f32_16x16x32_bf16 v[16:19], v[196:199], v[220:223], v[16:19]
	v_mfma_f32_16x16x32_bf16 v[4:7], v[184:187], v[228:231], v[4:7]
	v_mfma_f32_16x16x32_bf16 v[0:3], v[196:199], v[228:231], v[0:3]
	s_barrier
	s_add_i32 s72, s72, 2
	s_add_u32 s33, s33, 0x100
	s_addc_u32 vcc_lo, vcc_lo, 0
	s_cmp_gt_u32 s72, 9
	s_mov_b64 s[58:59], s[60:61]
	s_cbranch_scc0 .LBB0_777
	s_and_b64 vcc, exec, s[54:55]
	s_cbranch_vccz .LBB0_780
	s_barrier

; #define PG8_STAGE(bufoff, gbase, voff) do { _Pragma("unroll") for (int _i = 0; _i < 2; ++_i) \
;         __builtin_amdgcn_global_load_lds((const unsigned*)((const char*)(gbase) + (voff)[_i]), (PG8_LAS unsigned*)(lds + (bufoff) + ldsw + _i * 8192), 16, 0, 0); } while (0)
; #define PG8_LDA(dst, b, h) do { _Pragma("unroll") for (int m = 0; m < 4; ++m) _Pragma("unroll") for (int k = 0; k < 2; ++k) dst[m][k] = *(const PG8_LAS bf16x8*)(lds + PG8_SA(b, h) + aoff + m * 2048 + k * 1024); } while (0)
; #define PG8_LDB(dst, b, h) do { _Pragma("unroll") for (int n = 0; n < 2; ++n) _Pragma("unroll") for (int k = 0; k < 2; ++k) dst[n][k] = *(const PG8_LAS bf16x8*)(lds + PG8_SB(b, h) + boff + n * 2048 + k * 1024); } while (0)
; #define PG8_MMA(ai, bj, At, Bt) do { __builtin_amdgcn_s_setprio(1); _Pragma("unroll") for (int m = 0; m < 4; ++m) _Pragma("unroll") for (int n = 0; n < 2; ++n) _Pragma("unroll") for (int k = 0; k < 2; ++k) \
;         acc[ai][bj][m][n] = __builtin_amdgcn_mfma_f32_16x16x32_bf16(Bt[n][k], At[m][k], acc[ai][bj][m][n], 0, 0, 0); __builtin_amdgcn_s_setprio(0); } while (0)
; #define PG8_WAIT_V(n) asm volatile("s_waitcnt vmcnt(" #n ")" ::: "memory")
; #define PG8_WAIT_L(n) asm volatile("s_waitcnt lgkmcnt(" #n ")" ::: "memory")
; template <class Epi, class Sched, bool ALIGN_EPI = false, bool SP2 = false>
; __device__ __forceinline__ void gemm_phase(PG8_LAS unsigned char* lds, const Gemm g, const Sched& S, const Epi& E) {
;     ...
;             const bool last = (t == nt - 2);
;             const char* a1 = cA + (size_t)(t + 1) * kstep;
;             const char* a2 = last ? nA : cA + (size_t)(t + 2) * kstep; const char* b2 = last ? nB : cB + (size_t)(t + 2) * kstep;
;             const char* a3 = a2 + kstep; const char* b3 = b2 + kstep;
;             if (last && has_next) S.a_ready(nxt);
;             if constexpr (SP2) {
;             PG8_LDB(B0, 0, 0); PG8_LDB(B1, 0, 1); PG8_SCHED; PG8_LDA(At, 0, 0); PG8_STAGE(PG8_SA(1, 1), a1 + hstep, voffA);
;             PG8_WAIT_V(8); PG8_WAIT_L(0); PG8_BAR; PG8_MMA(0, 0, At, B0); PG8_MMA(0, 1, At, B1); PG8_BAR; PG8_SCHED;
;             PG8_LDA(At, 0, 1); PG8_STAGE(PG8_SB(0, 0), b2, voffB); PG8_STAGE(PG8_SB(0, 1), b2 + hstep, voffB); PG8_STAGE(PG8_SA(0, 0), a2, voffA);
;             PG8_WAIT_V(8); PG8_WAIT_L(0); PG8_BAR; PG8_MMA(1, 0, At, B0); PG8_MMA(1, 1, At, B1); PG8_BAR; PG8_SCHED;
.LBB0_901:
	ds_read_b128 v[144:147], v159
	ds_read_b128 v[168:171], v159 offset:1024
	ds_read_b128 v[172:175], v159 offset:2048
	ds_read_b128 v[176:179], v159 offset:3072
	ds_read_b128 v[180:183], v163
	ds_read_b128 v[184:187], v163 offset:1024
	ds_read_b128 v[188:191], v163 offset:2048
	ds_read_b128 v[196:199], v163 offset:3072
	s_add_u32 s6, s56, 0xfffc0080
	s_addc_u32 s7, s57, -1
	s_cmp_eq_u32 s72, 12
	s_cselect_b32 s61, s49, s7
	s_cselect_b32 s60, s76, s6
	s_cselect_b32 s59, s41, s33
	s_cselect_b32 s58, s77, s78
	s_add_i32 m0, s30, 0xc000
	ds_read_b128 v[200:203], v166
	ds_read_b128 v[204:207], v166 offset:1024
	ds_read_b128 v[208:211], v166 offset:2048
	ds_read_b128 v[212:215], v166 offset:3072
	ds_read_b128 v[216:219], v166 offset:4096
	ds_read_b128 v[220:223], v166 offset:5120
	ds_read_b128 v[224:227], v166 offset:6144
	ds_read_b128 v[228:231], v166 offset:7168
	global_load_lds_dwordx4 v136, s[56:57]
	s_add_i32 m0, s30, 0xe000
	s_nop 0
	global_load_lds_dwordx4 v138, s[56:57]
	s_waitcnt vmcnt(8)
	s_waitcnt lgkmcnt(0)
	s_barrier
	s_waitcnt lgkmcnt(0)
	v_mfma_f32_16x16x32_bf16 v[124:127], v[144:147], v[200:203], v[124:127]
	v_mfma_f32_16x16x32_bf16 v[116:119], v[172:175], v[200:203], v[116:119]
	v_mfma_f32_16x16x32_bf16 v[108:111], v[144:147], v[208:211], v[108:111]
	v_mfma_f32_16x16x32_bf16 v[100:103], v[172:175], v[208:211], v[100:103]
	v_mfma_f32_16x16x32_bf16 v[92:95], v[144:147], v[216:219], v[92:95]
	v_mfma_f32_16x16x32_bf16 v[84:87], v[172:175], v[216:219], v[84:87]
	v_mfma_f32_16x16x32_bf16 v[76:79], v[144:147], v[224:227], v[76:79]
	v_mfma_f32_16x16x32_bf16 v[68:71], v[172:175], v[224:227], v[68:71]
	v_mfma_f32_16x16x32_bf16 v[124:127], v[168:171], v[204:207], v[124:127]
	v_mfma_f32_16x16x32_bf16 v[116:119], v[176:179], v[204:207], v[116:119]
	v_mfma_f32_16x16x32_bf16 v[108:111], v[168:171], v[212:215], v[108:111]
	v_mfma_f32_16x16x32_bf16 v[100:103], v[176:179], v[212:215], v[100:103]
	v_mfma_f32_16x16x32_bf16 v[92:95], v[168:171], v[220:223], v[92:95]
	v_mfma_f32_16x16x32_bf16 v[84:87], v[176:179], v[220:223], v[84:87]
	v_mfma_f32_16x16x32_bf16 v[76:79], v[168:171], v[228:231], v[76:79]
	v_mfma_f32_16x16x32_bf16 v[68:71], v[176:179], v[228:231], v[68:71]
	v_mfma_f32_16x16x32_bf16 v[120:123], v[180:183], v[200:203], v[120:123]
	v_mfma_f32_16x16x32_bf16 v[112:115], v[188:191], v[200:203], v[112:115]
	v_mfma_f32_16x16x32_bf16 v[104:107], v[180:183], v[208:211], v[104:107]
	v_mfma_f32_16x16x32_bf16 v[96:99], v[188:191], v[208:211], v[96:99]
	v_mfma_f32_16x16x32_bf16 v[88:91], v[180:183], v[216:219], v[88:91]
	v_mfma_f32_16x16x32_bf16 v[80:83], v[188:191], v[216:219], v[80:83]
	v_mfma_f32_16x16x32_bf16 v[72:75], v[180:183], v[224:227], v[72:75]
	v_mfma_f32_16x16x32_bf16 v[64:67], v[188:191], v[224:227], v[64:67]
	v_mfma_f32_16x16x32_bf16 v[120:123], v[184:187], v[204:207], v[120:123]
	v_mfma_f32_16x16x32_bf16 v[112:115], v[196:199], v[204:207], v[112:115]
	v_mfma_f32_16x16x32_bf16 v[104:107], v[184:187], v[212:215], v[104:107]
	v_mfma_f32_16x16x32_bf16 v[96:99], v[196:199], v[212:215], v[96:99]
	v_mfma_f32_16x16x32_bf16 v[88:91], v[184:187], v[220:223], v[88:91]
	v_mfma_f32_16x16x32_bf16 v[80:83], v[196:199], v[220:223], v[80:83]
	v_mfma_f32_16x16x32_bf16 v[72:75], v[184:187], v[228:231], v[72:75]
	v_mfma_f32_16x16x32_bf16 v[64:67], v[196:199], v[228:231], v[64:67]
	s_barrier
	s_add_i32 s6, s67, s27
	s_mov_b32 m0, s6
	ds_read_b128 v[200:203], v166 offset:16384
	ds_read_b128 v[204:207], v166 offset:17408
	ds_read_b128 v[208:211], v166 offset:18432
	ds_read_b128 v[212:215], v166 offset:19456
	ds_read_b128 v[216:219], v166 offset:20480
	ds_read_b128 v[220:223], v166 offset:21504
	ds_read_b128 v[224:227], v166 offset:22528
	ds_read_b128 v[228:231], v166 offset:23552
	global_load_lds_dwordx4 v132, s[58:59]
	s_add_i32 m0, s6, 0x2000
	s_add_u32 s6, s58, 0x40000
	s_addc_u32 s7, s59, 0
	s_add_i32 s73, s68, s27
	global_load_lds_dwordx4 v128, s[58:59]
	s_mov_b32 m0, s73
	s_nop 0
	global_load_lds_dwordx4 v132, s[6:7]
	s_add_i32 m0, s73, 0x2000
	s_nop 0
	global_load_lds_dwordx4 v128, s[6:7]
	s_mov_b32 m0, s30
	s_nop 0
	global_load_lds_dwordx4 v134, s[60:61]
	s_mov_b32 m0, s31
	s_nop 0
	global_load_lds_dwordx4 v130, s[60:61]
	s_waitcnt vmcnt(8)
	s_waitcnt lgkmcnt(0)
	s_barrier
	s_waitcnt lgkmcnt(0)
	v_mfma_f32_16x16x32_bf16 v[60:63], v[144:147], v[200:203], v[60:63]
	v_mfma_f32_16x16x32_bf16 v[52:55], v[172:175], v[200:203], v[52:55]
	v_mfma_f32_16x16x32_bf16 v[44:47], v[144:147], v[208:211], v[44:47]
	v_mfma_f32_16x16x32_bf16 v[36:39], v[172:175], v[208:211], v[36:39]
	v_mfma_f32_16x16x32_bf16 v[28:31], v[144:147], v[216:219], v[28:31]
	v_mfma_f32_16x16x32_bf16 v[20:23], v[172:175], v[216:219], v[20:23]
	v_mfma_f32_16x16x32_bf16 v[12:15], v[144:147], v[224:227], v[12:15]
	v_mfma_f32_16x16x32_bf16 v[4:7], v[172:175], v[224:227], v[4:7]
	v_mfma_f32_16x16x32_bf16 v[60:63], v[168:171], v[204:207], v[60:63]
	v_mfma_f32_16x16x32_bf16 v[52:55], v[176:179], v[204:207], v[52:55]
	v_mfma_f32_16x16x32_bf16 v[44:47], v[168:171], v[212:215], v[44:47]
	v_mfma_f32_16x16x32_bf16 v[36:39], v[176:179], v[212:215], v[36:39]
	v_mfma_f32_16x16x32_bf16 v[28:31], v[168:171], v[220:223], v[28:31]
	v_mfma_f32_16x16x32_bf16 v[20:23], v[176:179], v[220:223], v[20:23]
	v_mfma_f32_16x16x32_bf16 v[12:15], v[168:171], v[228:231], v[12:15]
	v_mfma_f32_16x16x32_bf16 v[4:7], v[176:179], v[228:231], v[4:7]
	v_mfma_f32_16x16x32_bf16 v[56:59], v[180:183], v[200:203], v[56:59]
	v_mfma_f32_16x16x32_bf16 v[48:51], v[188:191], v[200:203], v[48:51]
	v_mfma_f32_16x16x32_bf16 v[40:43], v[180:183], v[208:211], v[40:43]
	v_mfma_f32_16x16x32_bf16 v[32:35], v[188:191], v[208:211], v[32:35]
	v_mfma_f32_16x16x32_bf16 v[24:27], v[180:183], v[216:219], v[24:27]
	v_mfma_f32_16x16x32_bf16 v[16:19], v[188:191], v[216:219], v[16:19]
	v_mfma_f32_16x16x32_bf16 v[8:11], v[180:183], v[224:227], v[8:11]
	v_mfma_f32_16x16x32_bf16 v[0:3], v[188:191], v[224:227], v[0:3]
	v_mfma_f32_16x16x32_bf16 v[56:59], v[184:187], v[204:207], v[56:59]
	v_mfma_f32_16x16x32_bf16 v[48:51], v[196:199], v[204:207], v[48:51]
	v_mfma_f32_16x16x32_bf16 v[40:43], v[184:187], v[212:215], v[40:43]
	v_mfma_f32_16x16x32_bf16 v[32:35], v[196:199], v[212:215], v[32:35]
	v_mfma_f32_16x16x32_bf16 v[24:27], v[184:187], v[220:223], v[24:27]
	v_mfma_f32_16x16x32_bf16 v[16:19], v[196:199], v[220:223], v[16:19]
	v_mfma_f32_16x16x32_bf16 v[8:11], v[184:187], v[228:231], v[8:11]
	v_mfma_f32_16x16x32_bf16 v[0:3], v[196:199], v[228:231], v[0:3]
	s_barrier
; #define PG8_STAGE(bufoff, gbase, voff) do { _Pragma("unroll") for (int _i = 0; _i < 2; ++_i) \
;         __builtin_amdgcn_global_load_lds((const unsigned*)((const char*)(gbase) + (voff)[_i]), (PG8_LAS unsigned*)(lds + (bufoff) + ldsw + _i * 8192), 16, 0, 0); } while (0)
; #define PG8_LDA(dst, b, h) do { _Pragma("unroll") for (int m = 0; m < 4; ++m) _Pragma("unroll") for (int k = 0; k < 2; ++k) dst[m][k] = *(const PG8_LAS bf16x8*)(lds + PG8_SA(b, h) + aoff + m * 2048 + k * 1024); } while (0)
; #define PG8_LDB(dst, b, h) do { _Pragma("unroll") for (int n = 0; n < 2; ++n) _Pragma("unroll") for (int k = 0; k < 2; ++k) dst[n][k] = *(const PG8_LAS bf16x8*)(lds + PG8_SB(b, h) + boff + n * 2048 + k * 1024); } while (0)
; #define PG8_MMA(ai, bj, At, Bt) do { __builtin_amdgcn_s_setprio(1); _Pragma("unroll") for (int m = 0; m < 4; ++m) _Pragma("unroll") for (int n = 0; n < 2; ++n) _Pragma("unroll") for (int k = 0; k < 2; ++k) \
;         acc[ai][bj][m][n] = __builtin_amdgcn_mfma_f32_16x16x32_bf16(Bt[n][k], At[m][k], acc[ai][bj][m][n], 0, 0, 0); __builtin_amdgcn_s_setprio(0); } while (0)
; #define PG8_WAIT_V(n) asm volatile("s_waitcnt vmcnt(" #n ")" ::: "memory")
; #define PG8_WAIT_L(n) asm volatile("s_waitcnt lgkmcnt(" #n ")" ::: "memory")
; #define PG8_BAR __builtin_amdgcn_s_barrier()
; #define PG8_SCHED __builtin_amdgcn_sched_barrier(0)
; template <class Epi, class Sched, bool ALIGN_EPI = false, bool SP2 = false>
; __device__ __forceinline__ void gemm_phase(PG8_LAS unsigned char* lds, const Gemm g, const Sched& S, const Epi& E) {
;     ...
;             PG8_LDB(B0, 1, 0); PG8_LDB(B1, 1, 1); PG8_SCHED; PG8_LDA(At, 1, 0); PG8_STAGE(PG8_SA(0, 1), a2 + hstep, voffA);
;             PG8_WAIT_V(8); PG8_WAIT_L(0); PG8_BAR; PG8_MMA(0, 0, At, B0); PG8_MMA(0, 1, At, B1); PG8_BAR; PG8_SCHED;
;             PG8_LDA(At, 1, 1); PG8_STAGE(PG8_SB(1, 0), b3, voffB); PG8_STAGE(PG8_SB(1, 1), b3 + hstep, voffB); PG8_STAGE(PG8_SA(1, 0), a3, voffA);
;             PG8_WAIT_V(8); PG8_WAIT_L(0); PG8_BAR; PG8_MMA(1, 0, At, B0); PG8_MMA(1, 1, At, B1); PG8_BAR; PG8_SCHED;
	s_add_i32 s73, 0, 0x18000
	v_add_u32_e32 v167, s73, v156
	s_add_i32 s79, 0, 0x1c000
	ds_read_b128 v[144:147], v167
	ds_read_b128 v[168:171], v167 offset:1024
	ds_read_b128 v[172:175], v167 offset:2048
	ds_read_b128 v[176:179], v167 offset:3072
	v_add_u32_e32 v167, s79, v156
	ds_read_b128 v[180:183], v167
	ds_read_b128 v[184:187], v167 offset:1024
	ds_read_b128 v[188:191], v167 offset:2048
	ds_read_b128 v[196:199], v167 offset:3072
	s_add_u32 s6, s60, 0x40000
	s_addc_u32 s7, s61, 0
	s_mov_b32 m0, s42
	ds_read_b128 v[200:203], v166 offset:32768
	ds_read_b128 v[204:207], v166 offset:33792
	ds_read_b128 v[208:211], v166 offset:34816
	ds_read_b128 v[212:215], v166 offset:35840
	ds_read_b128 v[216:219], v166 offset:36864
	ds_read_b128 v[220:223], v166 offset:37888
	ds_read_b128 v[224:227], v166 offset:38912
	ds_read_b128 v[228:231], v166 offset:39936
	global_load_lds_dwordx4 v134, s[6:7]
	s_mov_b32 m0, s43
	s_nop 0
	global_load_lds_dwordx4 v130, s[6:7]
	s_waitcnt vmcnt(8)
	s_waitcnt lgkmcnt(0)
	s_barrier
	s_waitcnt lgkmcnt(0)
	v_mfma_f32_16x16x32_bf16 v[124:127], v[144:147], v[200:203], v[124:127]
	v_mfma_f32_16x16x32_bf16 v[116:119], v[172:175], v[200:203], v[116:119]
	v_mfma_f32_16x16x32_bf16 v[108:111], v[144:147], v[208:211], v[108:111]
	v_mfma_f32_16x16x32_bf16 v[100:103], v[172:175], v[208:211], v[100:103]
	v_mfma_f32_16x16x32_bf16 v[92:95], v[144:147], v[216:219], v[92:95]
	v_mfma_f32_16x16x32_bf16 v[84:87], v[172:175], v[216:219], v[84:87]
	v_mfma_f32_16x16x32_bf16 v[76:79], v[144:147], v[224:227], v[76:79]
	v_mfma_f32_16x16x32_bf16 v[68:71], v[172:175], v[224:227], v[68:71]
	v_mfma_f32_16x16x32_bf16 v[124:127], v[168:171], v[204:207], v[124:127]
	v_mfma_f32_16x16x32_bf16 v[116:119], v[176:179], v[204:207], v[116:119]
	v_mfma_f32_16x16x32_bf16 v[108:111], v[168:171], v[212:215], v[108:111]
	v_mfma_f32_16x16x32_bf16 v[100:103], v[176:179], v[212:215], v[100:103]
	v_mfma_f32_16x16x32_bf16 v[92:95], v[168:171], v[220:223], v[92:95]
	v_mfma_f32_16x16x32_bf16 v[84:87], v[176:179], v[220:223], v[84:87]
	v_mfma_f32_16x16x32_bf16 v[76:79], v[168:171], v[228:231], v[76:79]
	v_mfma_f32_16x16x32_bf16 v[68:71], v[176:179], v[228:231], v[68:71]
	v_mfma_f32_16x16x32_bf16 v[120:123], v[180:183], v[200:203], v[120:123]
	v_mfma_f32_16x16x32_bf16 v[112:115], v[188:191], v[200:203], v[112:115]
	v_mfma_f32_16x16x32_bf16 v[104:107], v[180:183], v[208:211], v[104:107]
	v_mfma_f32_16x16x32_bf16 v[96:99], v[188:191], v[208:211], v[96:99]
	v_mfma_f32_16x16x32_bf16 v[88:91], v[180:183], v[216:219], v[88:91]
	v_mfma_f32_16x16x32_bf16 v[80:83], v[188:191], v[216:219], v[80:83]
	v_mfma_f32_16x16x32_bf16 v[72:75], v[180:183], v[224:227], v[72:75]
	v_mfma_f32_16x16x32_bf16 v[64:67], v[188:191], v[224:227], v[64:67]
	v_mfma_f32_16x16x32_bf16 v[120:123], v[184:187], v[204:207], v[120:123]
	v_mfma_f32_16x16x32_bf16 v[112:115], v[196:199], v[204:207], v[112:115]
	v_mfma_f32_16x16x32_bf16 v[104:107], v[184:187], v[212:215], v[104:107]
	v_mfma_f32_16x16x32_bf16 v[96:99], v[196:199], v[212:215], v[96:99]
	v_mfma_f32_16x16x32_bf16 v[88:91], v[184:187], v[220:223], v[88:91]
	v_mfma_f32_16x16x32_bf16 v[80:83], v[196:199], v[220:223], v[80:83]
	v_mfma_f32_16x16x32_bf16 v[72:75], v[184:187], v[228:231], v[72:75]
	v_mfma_f32_16x16x32_bf16 v[64:67], v[196:199], v[228:231], v[64:67]
	s_barrier
	s_add_i32 s6, s73, s27
	s_add_u32 s98, s58, 0x80
	s_addc_u32 s99, s59, 0
	s_add_u32 s100, s60, 0x80
	s_addc_u32 s101, s61, 0
	s_mov_b32 m0, s6
	ds_read_b128 v[200:203], v166 offset:49152
	ds_read_b128 v[204:207], v166 offset:50176
	ds_read_b128 v[208:211], v166 offset:51200
	ds_read_b128 v[212:215], v166 offset:52224
	ds_read_b128 v[216:219], v166 offset:53248
	ds_read_b128 v[220:223], v166 offset:54272
	ds_read_b128 v[224:227], v166 offset:55296
	ds_read_b128 v[228:231], v166 offset:56320
	global_load_lds_dwordx4 v132, s[98:99]
	s_add_i32 m0, s6, 0x2000
	s_add_u32 s6, s58, 0x40080
	s_addc_u32 s7, s59, 0
	s_add_i32 s58, s79, s27
	global_load_lds_dwordx4 v128, s[98:99]
	s_mov_b32 m0, s58
	s_nop 0
	global_load_lds_dwordx4 v132, s[6:7]
	s_add_i32 m0, s58, 0x2000
	s_nop 0
	global_load_lds_dwordx4 v128, s[6:7]
	s_mov_b32 m0, s44
	s_nop 0
	global_load_lds_dwordx4 v134, s[100:101]
	s_mov_b32 m0, s45
	s_nop 0
	global_load_lds_dwordx4 v130, s[100:101]
	s_waitcnt vmcnt(8)
	s_waitcnt lgkmcnt(0)
	s_barrier
	s_waitcnt lgkmcnt(0)
	v_mfma_f32_16x16x32_bf16 v[60:63], v[144:147], v[200:203], v[60:63]
	v_mfma_f32_16x16x32_bf16 v[52:55], v[172:175], v[200:203], v[52:55]
	v_mfma_f32_16x16x32_bf16 v[44:47], v[144:147], v[208:211], v[44:47]
	v_mfma_f32_16x16x32_bf16 v[36:39], v[172:175], v[208:211], v[36:39]
	v_mfma_f32_16x16x32_bf16 v[28:31], v[144:147], v[216:219], v[28:31]
	v_mfma_f32_16x16x32_bf16 v[20:23], v[172:175], v[216:219], v[20:23]
	v_mfma_f32_16x16x32_bf16 v[12:15], v[144:147], v[224:227], v[12:15]
	v_mfma_f32_16x16x32_bf16 v[4:7], v[172:175], v[224:227], v[4:7]
	v_mfma_f32_16x16x32_bf16 v[60:63], v[168:171], v[204:207], v[60:63]
	v_mfma_f32_16x16x32_bf16 v[52:55], v[176:179], v[204:207], v[52:55]
	v_mfma_f32_16x16x32_bf16 v[44:47], v[168:171], v[212:215], v[44:47]
	v_mfma_f32_16x16x32_bf16 v[36:39], v[176:179], v[212:215], v[36:39]
	v_mfma_f32_16x16x32_bf16 v[28:31], v[168:171], v[220:223], v[28:31]
	v_mfma_f32_16x16x32_bf16 v[20:23], v[176:179], v[220:223], v[20:23]
	v_mfma_f32_16x16x32_bf16 v[12:15], v[168:171], v[228:231], v[12:15]
	v_mfma_f32_16x16x32_bf16 v[4:7], v[176:179], v[228:231], v[4:7]
	v_mfma_f32_16x16x32_bf16 v[56:59], v[180:183], v[200:203], v[56:59]
	v_mfma_f32_16x16x32_bf16 v[48:51], v[188:191], v[200:203], v[48:51]
	v_mfma_f32_16x16x32_bf16 v[40:43], v[180:183], v[208:211], v[40:43]
	v_mfma_f32_16x16x32_bf16 v[32:35], v[188:191], v[208:211], v[32:35]
	v_mfma_f32_16x16x32_bf16 v[24:27], v[180:183], v[216:219], v[24:27]
	v_mfma_f32_16x16x32_bf16 v[16:19], v[188:191], v[216:219], v[16:19]
	v_mfma_f32_16x16x32_bf16 v[8:11], v[180:183], v[224:227], v[8:11]
	v_mfma_f32_16x16x32_bf16 v[0:3], v[188:191], v[224:227], v[0:3]
	v_mfma_f32_16x16x32_bf16 v[56:59], v[184:187], v[204:207], v[56:59]
	v_mfma_f32_16x16x32_bf16 v[48:51], v[196:199], v[204:207], v[48:51]
	v_mfma_f32_16x16x32_bf16 v[40:43], v[184:187], v[212:215], v[40:43]
	v_mfma_f32_16x16x32_bf16 v[32:35], v[196:199], v[212:215], v[32:35]
	v_mfma_f32_16x16x32_bf16 v[24:27], v[184:187], v[220:223], v[24:27]
	v_mfma_f32_16x16x32_bf16 v[16:19], v[196:199], v[220:223], v[16:19]
	v_mfma_f32_16x16x32_bf16 v[8:11], v[184:187], v[228:231], v[8:11]
	v_mfma_f32_16x16x32_bf16 v[0:3], v[196:199], v[228:231], v[0:3]
	s_barrier
	s_add_i32 s72, s72, 2
	s_add_u32 s56, s56, 0x100
	s_addc_u32 s57, s57, 0
	s_add_u32 s78, s78, 0x100
	s_addc_u32 s33, s33, 0
	s_cmp_gt_u32 s72, 13
	s_cbranch_scc0 .LBB0_901
	s_and_b64 vcc, exec, s[38:39]
	s_cbranch_vccz .LBB0_904
	s_barrier

; #define PG8_STAGE(bufoff, gbase, voff) do { _Pragma("unroll") for (int _i = 0; _i < 2; ++_i) \
;         __builtin_amdgcn_global_load_lds((const unsigned*)((const char*)(gbase) + (voff)[_i]), (PG8_LAS unsigned*)(lds + (bufoff) + ldsw + _i * 8192), 16, 0, 0); } while (0)
; #define PG8_LDA(dst, b, h) do { _Pragma("unroll") for (int m = 0; m < 4; ++m) _Pragma("unroll") for (int k = 0; k < 2; ++k) dst[m][k] = *(const PG8_LAS bf16x8*)(lds + PG8_SA(b, h) + aoff + m * 2048 + k * 1024); } while (0)
; #define PG8_LDB(dst, b, h) do { _Pragma("unroll") for (int n = 0; n < 2; ++n) _Pragma("unroll") for (int k = 0; k < 2; ++k) dst[n][k] = *(const PG8_LAS bf16x8*)(lds + PG8_SB(b, h) + boff + n * 2048 + k * 1024); } while (0)
; #define PG8_MMA(ai, bj, At, Bt) do { __builtin_amdgcn_s_setprio(1); _Pragma("unroll") for (int m = 0; m < 4; ++m) _Pragma("unroll") for (int n = 0; n < 2; ++n) _Pragma("unroll") for (int k = 0; k < 2; ++k) \
;         acc[ai][bj][m][n] = __builtin_amdgcn_mfma_f32_16x16x32_bf16(Bt[n][k], At[m][k], acc[ai][bj][m][n], 0, 0, 0); __builtin_amdgcn_s_setprio(0); } while (0)
; #define PG8_WAIT_V(n) asm volatile("s_waitcnt vmcnt(" #n ")" ::: "memory")
; #define PG8_WAIT_L(n) asm volatile("s_waitcnt lgkmcnt(" #n ")" ::: "memory")
; template <class Epi, class Sched, bool ALIGN_EPI = false, bool SP2 = false>
; __device__ __forceinline__ void gemm_phase(PG8_LAS unsigned char* lds, const Gemm g, const Sched& S, const Epi& E) {
;     ...
;             const bool last = (t == nt - 2);
;             const char* a1 = cA + (size_t)(t + 1) * kstep;
;             const char* a2 = last ? nA : cA + (size_t)(t + 2) * kstep; const char* b2 = last ? nB : cB + (size_t)(t + 2) * kstep;
;             const char* a3 = a2 + kstep; const char* b3 = b2 + kstep;
;             if (last && has_next) S.a_ready(nxt);
;             if constexpr (SP2) {
;             PG8_LDB(B0, 0, 0); PG8_LDB(B1, 0, 1); PG8_SCHED; PG8_LDA(At, 0, 0); PG8_STAGE(PG8_SA(1, 1), a1 + hstep, voffA);
;             PG8_WAIT_V(8); PG8_WAIT_L(0); PG8_BAR; PG8_MMA(0, 0, At, B0); PG8_MMA(0, 1, At, B1); PG8_BAR; PG8_SCHED;
;             PG8_LDA(At, 0, 1); PG8_STAGE(PG8_SB(0, 0), b2, voffB); PG8_STAGE(PG8_SB(0, 1), b2 + hstep, voffB); PG8_STAGE(PG8_SA(0, 0), a2, voffA);
;             PG8_WAIT_V(8); PG8_WAIT_L(0); PG8_BAR; PG8_MMA(1, 0, At, B0); PG8_MMA(1, 1, At, B1); PG8_BAR; PG8_SCHED;
.LBB0_1014:
	ds_read_b128 v[144:147], v158
	ds_read_b128 v[168:171], v158 offset:1024
	ds_read_b128 v[172:175], v158 offset:2048
	ds_read_b128 v[176:179], v158 offset:3072
	ds_read_b128 v[180:183], v159
	ds_read_b128 v[184:187], v159 offset:1024
	ds_read_b128 v[188:191], v159 offset:2048
	ds_read_b128 v[196:199], v159 offset:3072
	s_add_u32 s58, s56, 0x100
	s_addc_u32 s59, s57, 0
	s_cmp_eq_u32 s72, 40
	s_cselect_b32 s79, s51, s59
	s_cselect_b32 s78, s50, s58
	s_cselect_b32 s61, s55, s80
	s_cselect_b32 s60, s54, s33
	s_add_i32 m0, s45, 0xc000
	ds_read_b128 v[200:203], v163
	ds_read_b128 v[204:207], v163 offset:1024
	ds_read_b128 v[208:211], v163 offset:2048
	ds_read_b128 v[212:215], v163 offset:3072
	ds_read_b128 v[216:219], v163 offset:4096
	ds_read_b128 v[220:223], v163 offset:5120
	ds_read_b128 v[224:227], v163 offset:6144
	ds_read_b128 v[228:231], v163 offset:7168
	global_load_lds_dwordx4 v136, s[56:57]
	s_add_i32 m0, s45, 0xe000
	s_nop 0
	global_load_lds_dwordx4 v138, s[56:57]
	s_waitcnt vmcnt(8)
	s_waitcnt lgkmcnt(0)
	s_barrier
	s_waitcnt lgkmcnt(0)
	v_mfma_f32_16x16x32_bf16 v[124:127], v[144:147], v[200:203], v[124:127]
	v_mfma_f32_16x16x32_bf16 v[120:123], v[172:175], v[200:203], v[120:123]
	v_mfma_f32_16x16x32_bf16 v[108:111], v[144:147], v[208:211], v[108:111]
	v_mfma_f32_16x16x32_bf16 v[104:107], v[172:175], v[208:211], v[104:107]
	v_mfma_f32_16x16x32_bf16 v[92:95], v[144:147], v[216:219], v[92:95]
	v_mfma_f32_16x16x32_bf16 v[88:91], v[172:175], v[216:219], v[88:91]
	v_mfma_f32_16x16x32_bf16 v[76:79], v[144:147], v[224:227], v[76:79]
	v_mfma_f32_16x16x32_bf16 v[72:75], v[172:175], v[224:227], v[72:75]
	v_mfma_f32_16x16x32_bf16 v[124:127], v[168:171], v[204:207], v[124:127]
	v_mfma_f32_16x16x32_bf16 v[120:123], v[176:179], v[204:207], v[120:123]
	v_mfma_f32_16x16x32_bf16 v[108:111], v[168:171], v[212:215], v[108:111]
	v_mfma_f32_16x16x32_bf16 v[104:107], v[176:179], v[212:215], v[104:107]
	v_mfma_f32_16x16x32_bf16 v[92:95], v[168:171], v[220:223], v[92:95]
	v_mfma_f32_16x16x32_bf16 v[88:91], v[176:179], v[220:223], v[88:91]
	v_mfma_f32_16x16x32_bf16 v[76:79], v[168:171], v[228:231], v[76:79]
	v_mfma_f32_16x16x32_bf16 v[72:75], v[176:179], v[228:231], v[72:75]
	v_mfma_f32_16x16x32_bf16 v[116:119], v[180:183], v[200:203], v[116:119]
	v_mfma_f32_16x16x32_bf16 v[112:115], v[188:191], v[200:203], v[112:115]
	v_mfma_f32_16x16x32_bf16 v[100:103], v[180:183], v[208:211], v[100:103]
	v_mfma_f32_16x16x32_bf16 v[96:99], v[188:191], v[208:211], v[96:99]
	v_mfma_f32_16x16x32_bf16 v[84:87], v[180:183], v[216:219], v[84:87]
	v_mfma_f32_16x16x32_bf16 v[80:83], v[188:191], v[216:219], v[80:83]
	v_mfma_f32_16x16x32_bf16 v[68:71], v[180:183], v[224:227], v[68:71]
	v_mfma_f32_16x16x32_bf16 v[64:67], v[188:191], v[224:227], v[64:67]
	v_mfma_f32_16x16x32_bf16 v[116:119], v[184:187], v[204:207], v[116:119]
	v_mfma_f32_16x16x32_bf16 v[112:115], v[196:199], v[204:207], v[112:115]
	v_mfma_f32_16x16x32_bf16 v[100:103], v[184:187], v[212:215], v[100:103]
	v_mfma_f32_16x16x32_bf16 v[96:99], v[196:199], v[212:215], v[96:99]
	v_mfma_f32_16x16x32_bf16 v[84:87], v[184:187], v[220:223], v[84:87]
	v_mfma_f32_16x16x32_bf16 v[80:83], v[196:199], v[220:223], v[80:83]
	v_mfma_f32_16x16x32_bf16 v[68:71], v[184:187], v[228:231], v[68:71]
	v_mfma_f32_16x16x32_bf16 v[64:67], v[196:199], v[228:231], v[64:67]
	s_barrier
	s_add_i32 s6, s26, s44
	s_mov_b32 m0, s6
	ds_read_b128 v[200:203], v163 offset:16384
	ds_read_b128 v[204:207], v163 offset:17408
	ds_read_b128 v[208:211], v163 offset:18432
	ds_read_b128 v[212:215], v163 offset:19456
	ds_read_b128 v[216:219], v163 offset:20480
	ds_read_b128 v[220:223], v163 offset:21504
	ds_read_b128 v[224:227], v163 offset:22528
	ds_read_b128 v[228:231], v163 offset:23552
	global_load_lds_dwordx4 v130, s[60:61]
	s_add_i32 m0, s6, 0x2000
	s_add_u32 s6, s60, 0xb0000
	s_addc_u32 s7, s61, 0
	s_add_i32 s56, s74, s44
	global_load_lds_dwordx4 v134, s[60:61]
	s_mov_b32 m0, s56
	s_nop 0
	global_load_lds_dwordx4 v130, s[6:7]
	s_add_i32 m0, s56, 0x2000
	s_nop 0
	global_load_lds_dwordx4 v134, s[6:7]
	s_mov_b32 m0, s45
	s_nop 0
	global_load_lds_dwordx4 v128, s[78:79]
	s_mov_b32 m0, s67
	s_nop 0
	global_load_lds_dwordx4 v132, s[78:79]
	s_waitcnt vmcnt(8)
	s_waitcnt lgkmcnt(0)
	s_barrier
	s_waitcnt lgkmcnt(0)
	v_mfma_f32_16x16x32_bf16 v[60:63], v[144:147], v[200:203], v[60:63]
	v_mfma_f32_16x16x32_bf16 v[56:59], v[172:175], v[200:203], v[56:59]
	v_mfma_f32_16x16x32_bf16 v[44:47], v[144:147], v[208:211], v[44:47]
	v_mfma_f32_16x16x32_bf16 v[40:43], v[172:175], v[208:211], v[40:43]
	v_mfma_f32_16x16x32_bf16 v[28:31], v[144:147], v[216:219], v[28:31]
	v_mfma_f32_16x16x32_bf16 v[24:27], v[172:175], v[216:219], v[24:27]
	v_mfma_f32_16x16x32_bf16 v[12:15], v[144:147], v[224:227], v[12:15]
	v_mfma_f32_16x16x32_bf16 v[8:11], v[172:175], v[224:227], v[8:11]
	v_mfma_f32_16x16x32_bf16 v[60:63], v[168:171], v[204:207], v[60:63]
	v_mfma_f32_16x16x32_bf16 v[56:59], v[176:179], v[204:207], v[56:59]
	v_mfma_f32_16x16x32_bf16 v[44:47], v[168:171], v[212:215], v[44:47]
	v_mfma_f32_16x16x32_bf16 v[40:43], v[176:179], v[212:215], v[40:43]
	v_mfma_f32_16x16x32_bf16 v[28:31], v[168:171], v[220:223], v[28:31]
	v_mfma_f32_16x16x32_bf16 v[24:27], v[176:179], v[220:223], v[24:27]
	v_mfma_f32_16x16x32_bf16 v[12:15], v[168:171], v[228:231], v[12:15]
	v_mfma_f32_16x16x32_bf16 v[8:11], v[176:179], v[228:231], v[8:11]
	v_mfma_f32_16x16x32_bf16 v[52:55], v[180:183], v[200:203], v[52:55]
	v_mfma_f32_16x16x32_bf16 v[48:51], v[188:191], v[200:203], v[48:51]
	v_mfma_f32_16x16x32_bf16 v[36:39], v[180:183], v[208:211], v[36:39]
	v_mfma_f32_16x16x32_bf16 v[32:35], v[188:191], v[208:211], v[32:35]
	v_mfma_f32_16x16x32_bf16 v[20:23], v[180:183], v[216:219], v[20:23]
	v_mfma_f32_16x16x32_bf16 v[16:19], v[188:191], v[216:219], v[16:19]
	v_mfma_f32_16x16x32_bf16 v[4:7], v[180:183], v[224:227], v[4:7]
	v_mfma_f32_16x16x32_bf16 v[0:3], v[188:191], v[224:227], v[0:3]
	v_mfma_f32_16x16x32_bf16 v[52:55], v[184:187], v[204:207], v[52:55]
	v_mfma_f32_16x16x32_bf16 v[48:51], v[196:199], v[204:207], v[48:51]
	v_mfma_f32_16x16x32_bf16 v[36:39], v[184:187], v[212:215], v[36:39]
	v_mfma_f32_16x16x32_bf16 v[32:35], v[196:199], v[212:215], v[32:35]
	v_mfma_f32_16x16x32_bf16 v[20:23], v[184:187], v[220:223], v[20:23]
	v_mfma_f32_16x16x32_bf16 v[16:19], v[196:199], v[220:223], v[16:19]
	v_mfma_f32_16x16x32_bf16 v[4:7], v[184:187], v[228:231], v[4:7]
	v_mfma_f32_16x16x32_bf16 v[0:3], v[196:199], v[228:231], v[0:3]
	s_barrier
; #define PG8_STAGE(bufoff, gbase, voff) do { _Pragma("unroll") for (int _i = 0; _i < 2; ++_i) \
;         __builtin_amdgcn_global_load_lds((const unsigned*)((const char*)(gbase) + (voff)[_i]), (PG8_LAS unsigned*)(lds + (bufoff) + ldsw + _i * 8192), 16, 0, 0); } while (0)
; #define PG8_LDA(dst, b, h) do { _Pragma("unroll") for (int m = 0; m < 4; ++m) _Pragma("unroll") for (int k = 0; k < 2; ++k) dst[m][k] = *(const PG8_LAS bf16x8*)(lds + PG8_SA(b, h) + aoff + m * 2048 + k * 1024); } while (0)
; #define PG8_LDB(dst, b, h) do { _Pragma("unroll") for (int n = 0; n < 2; ++n) _Pragma("unroll") for (int k = 0; k < 2; ++k) dst[n][k] = *(const PG8_LAS bf16x8*)(lds + PG8_SB(b, h) + boff + n * 2048 + k * 1024); } while (0)
; #define PG8_MMA(ai, bj, At, Bt) do { __builtin_amdgcn_s_setprio(1); _Pragma("unroll") for (int m = 0; m < 4; ++m) _Pragma("unroll") for (int n = 0; n < 2; ++n) _Pragma("unroll") for (int k = 0; k < 2; ++k) \
;         acc[ai][bj][m][n] = __builtin_amdgcn_mfma_f32_16x16x32_bf16(Bt[n][k], At[m][k], acc[ai][bj][m][n], 0, 0, 0); __builtin_amdgcn_s_setprio(0); } while (0)
; #define PG8_WAIT_V(n) asm volatile("s_waitcnt vmcnt(" #n ")" ::: "memory")
; #define PG8_WAIT_L(n) asm volatile("s_waitcnt lgkmcnt(" #n ")" ::: "memory")
; #define PG8_BAR __builtin_amdgcn_s_barrier()
; #define PG8_SCHED __builtin_amdgcn_sched_barrier(0)
; template <class Epi, class Sched, bool ALIGN_EPI = false, bool SP2 = false>
; __device__ __forceinline__ void gemm_phase(PG8_LAS unsigned char* lds, const Gemm g, const Sched& S, const Epi& E) {
;     ...
;             PG8_LDB(B0, 1, 0); PG8_LDB(B1, 1, 1); PG8_SCHED; PG8_LDA(At, 1, 0); PG8_STAGE(PG8_SA(0, 1), a2 + hstep, voffA);
;             PG8_WAIT_V(8); PG8_WAIT_L(0); PG8_BAR; PG8_MMA(0, 0, At, B0); PG8_MMA(0, 1, At, B1); PG8_BAR; PG8_SCHED;
;             PG8_LDA(At, 1, 1); PG8_STAGE(PG8_SB(1, 0), b3, voffB); PG8_STAGE(PG8_SB(1, 1), b3 + hstep, voffB); PG8_STAGE(PG8_SA(1, 0), a3, voffA);
;             PG8_WAIT_V(8); PG8_WAIT_L(0); PG8_BAR; PG8_MMA(1, 0, At, B0); PG8_MMA(1, 1, At, B1); PG8_BAR; PG8_SCHED;
	s_add_i32 s56, 0, 0x18000
	v_add_u32_e32 v167, s56, v156
	s_add_i32 s57, 0, 0x1c000
	ds_read_b128 v[144:147], v167
	ds_read_b128 v[168:171], v167 offset:1024
	ds_read_b128 v[172:175], v167 offset:2048
	ds_read_b128 v[176:179], v167 offset:3072
	v_add_u32_e32 v167, s57, v156
	ds_read_b128 v[180:183], v167
	ds_read_b128 v[184:187], v167 offset:1024
	ds_read_b128 v[188:191], v167 offset:2048
	ds_read_b128 v[196:199], v167 offset:3072
	s_add_u32 s6, s78, 0xb0000
	s_addc_u32 s7, s79, 0
	s_mov_b32 m0, s76
	ds_read_b128 v[200:203], v163 offset:32768
	ds_read_b128 v[204:207], v163 offset:33792
	ds_read_b128 v[208:211], v163 offset:34816
	ds_read_b128 v[212:215], v163 offset:35840
	ds_read_b128 v[216:219], v163 offset:36864
	ds_read_b128 v[220:223], v163 offset:37888
	ds_read_b128 v[224:227], v163 offset:38912
	ds_read_b128 v[228:231], v163 offset:39936
	global_load_lds_dwordx4 v128, s[6:7]
	s_mov_b32 m0, s77
	s_nop 0
	global_load_lds_dwordx4 v132, s[6:7]
	s_waitcnt vmcnt(8)
	s_waitcnt lgkmcnt(0)
	s_barrier
	s_waitcnt lgkmcnt(0)
	v_mfma_f32_16x16x32_bf16 v[124:127], v[144:147], v[200:203], v[124:127]
	v_mfma_f32_16x16x32_bf16 v[120:123], v[172:175], v[200:203], v[120:123]
	v_mfma_f32_16x16x32_bf16 v[108:111], v[144:147], v[208:211], v[108:111]
	v_mfma_f32_16x16x32_bf16 v[104:107], v[172:175], v[208:211], v[104:107]
	v_mfma_f32_16x16x32_bf16 v[92:95], v[144:147], v[216:219], v[92:95]
	v_mfma_f32_16x16x32_bf16 v[88:91], v[172:175], v[216:219], v[88:91]
	v_mfma_f32_16x16x32_bf16 v[76:79], v[144:147], v[224:227], v[76:79]
	v_mfma_f32_16x16x32_bf16 v[72:75], v[172:175], v[224:227], v[72:75]
	v_mfma_f32_16x16x32_bf16 v[124:127], v[168:171], v[204:207], v[124:127]
	v_mfma_f32_16x16x32_bf16 v[120:123], v[176:179], v[204:207], v[120:123]
	v_mfma_f32_16x16x32_bf16 v[108:111], v[168:171], v[212:215], v[108:111]
	v_mfma_f32_16x16x32_bf16 v[104:107], v[176:179], v[212:215], v[104:107]
	v_mfma_f32_16x16x32_bf16 v[92:95], v[168:171], v[220:223], v[92:95]
	v_mfma_f32_16x16x32_bf16 v[88:91], v[176:179], v[220:223], v[88:91]
	v_mfma_f32_16x16x32_bf16 v[76:79], v[168:171], v[228:231], v[76:79]
	v_mfma_f32_16x16x32_bf16 v[72:75], v[176:179], v[228:231], v[72:75]
	v_mfma_f32_16x16x32_bf16 v[116:119], v[180:183], v[200:203], v[116:119]
	v_mfma_f32_16x16x32_bf16 v[112:115], v[188:191], v[200:203], v[112:115]
	v_mfma_f32_16x16x32_bf16 v[100:103], v[180:183], v[208:211], v[100:103]
	v_mfma_f32_16x16x32_bf16 v[96:99], v[188:191], v[208:211], v[96:99]
	v_mfma_f32_16x16x32_bf16 v[84:87], v[180:183], v[216:219], v[84:87]
	v_mfma_f32_16x16x32_bf16 v[80:83], v[188:191], v[216:219], v[80:83]
	v_mfma_f32_16x16x32_bf16 v[68:71], v[180:183], v[224:227], v[68:71]
	v_mfma_f32_16x16x32_bf16 v[64:67], v[188:191], v[224:227], v[64:67]
	v_mfma_f32_16x16x32_bf16 v[116:119], v[184:187], v[204:207], v[116:119]
	v_mfma_f32_16x16x32_bf16 v[112:115], v[196:199], v[204:207], v[112:115]
	v_mfma_f32_16x16x32_bf16 v[100:103], v[184:187], v[212:215], v[100:103]
	v_mfma_f32_16x16x32_bf16 v[96:99], v[196:199], v[212:215], v[96:99]
	v_mfma_f32_16x16x32_bf16 v[84:87], v[184:187], v[220:223], v[84:87]
	v_mfma_f32_16x16x32_bf16 v[80:83], v[196:199], v[220:223], v[80:83]
	v_mfma_f32_16x16x32_bf16 v[68:71], v[184:187], v[228:231], v[68:71]
	v_mfma_f32_16x16x32_bf16 v[64:67], v[196:199], v[228:231], v[64:67]
	s_barrier
	s_add_i32 s6, s56, s44
	s_add_u32 s98, s60, 0x80
	s_addc_u32 s99, s61, 0
	s_add_u32 s100, s78, 0x80
	s_addc_u32 s101, s79, 0
	s_mov_b32 m0, s6
	ds_read_b128 v[200:203], v163 offset:49152
	ds_read_b128 v[204:207], v163 offset:50176
	ds_read_b128 v[208:211], v163 offset:51200
	ds_read_b128 v[212:215], v163 offset:52224
	ds_read_b128 v[216:219], v163 offset:53248
	ds_read_b128 v[220:223], v163 offset:54272
	ds_read_b128 v[224:227], v163 offset:55296
	ds_read_b128 v[228:231], v163 offset:56320
	global_load_lds_dwordx4 v130, s[98:99]
	s_add_i32 m0, s6, 0x2000
	s_add_u32 s6, s60, 0xb0080
	s_addc_u32 s7, s61, 0
	s_add_i32 s56, s57, s44
	global_load_lds_dwordx4 v134, s[98:99]
	s_mov_b32 m0, s56
	s_nop 0
	global_load_lds_dwordx4 v130, s[6:7]
	s_add_i32 m0, s56, 0x2000
	s_nop 0
	global_load_lds_dwordx4 v134, s[6:7]
	s_mov_b32 m0, s31
	s_nop 0
	global_load_lds_dwordx4 v128, s[100:101]
	s_mov_b32 m0, s4
	s_nop 0
	global_load_lds_dwordx4 v132, s[100:101]
	s_waitcnt vmcnt(8)
	s_waitcnt lgkmcnt(0)
	s_barrier
	s_waitcnt lgkmcnt(0)
	v_mfma_f32_16x16x32_bf16 v[60:63], v[144:147], v[200:203], v[60:63]
	v_mfma_f32_16x16x32_bf16 v[56:59], v[172:175], v[200:203], v[56:59]
	v_mfma_f32_16x16x32_bf16 v[44:47], v[144:147], v[208:211], v[44:47]
	v_mfma_f32_16x16x32_bf16 v[40:43], v[172:175], v[208:211], v[40:43]
	v_mfma_f32_16x16x32_bf16 v[28:31], v[144:147], v[216:219], v[28:31]
	v_mfma_f32_16x16x32_bf16 v[24:27], v[172:175], v[216:219], v[24:27]
	v_mfma_f32_16x16x32_bf16 v[12:15], v[144:147], v[224:227], v[12:15]
	v_mfma_f32_16x16x32_bf16 v[8:11], v[172:175], v[224:227], v[8:11]
	v_mfma_f32_16x16x32_bf16 v[60:63], v[168:171], v[204:207], v[60:63]
	v_mfma_f32_16x16x32_bf16 v[56:59], v[176:179], v[204:207], v[56:59]
	v_mfma_f32_16x16x32_bf16 v[44:47], v[168:171], v[212:215], v[44:47]
	v_mfma_f32_16x16x32_bf16 v[40:43], v[176:179], v[212:215], v[40:43]
	v_mfma_f32_16x16x32_bf16 v[28:31], v[168:171], v[220:223], v[28:31]
	v_mfma_f32_16x16x32_bf16 v[24:27], v[176:179], v[220:223], v[24:27]
	v_mfma_f32_16x16x32_bf16 v[12:15], v[168:171], v[228:231], v[12:15]
	v_mfma_f32_16x16x32_bf16 v[8:11], v[176:179], v[228:231], v[8:11]
	v_mfma_f32_16x16x32_bf16 v[52:55], v[180:183], v[200:203], v[52:55]
	v_mfma_f32_16x16x32_bf16 v[48:51], v[188:191], v[200:203], v[48:51]
	v_mfma_f32_16x16x32_bf16 v[36:39], v[180:183], v[208:211], v[36:39]
	v_mfma_f32_16x16x32_bf16 v[32:35], v[188:191], v[208:211], v[32:35]
	v_mfma_f32_16x16x32_bf16 v[20:23], v[180:183], v[216:219], v[20:23]
	v_mfma_f32_16x16x32_bf16 v[16:19], v[188:191], v[216:219], v[16:19]
	v_mfma_f32_16x16x32_bf16 v[4:7], v[180:183], v[224:227], v[4:7]
	v_mfma_f32_16x16x32_bf16 v[0:3], v[188:191], v[224:227], v[0:3]
	v_mfma_f32_16x16x32_bf16 v[52:55], v[184:187], v[204:207], v[52:55]
	v_mfma_f32_16x16x32_bf16 v[48:51], v[196:199], v[204:207], v[48:51]
	v_mfma_f32_16x16x32_bf16 v[36:39], v[184:187], v[212:215], v[36:39]
	v_mfma_f32_16x16x32_bf16 v[32:35], v[196:199], v[212:215], v[32:35]
	v_mfma_f32_16x16x32_bf16 v[20:23], v[184:187], v[220:223], v[20:23]
	v_mfma_f32_16x16x32_bf16 v[16:19], v[196:199], v[220:223], v[16:19]
	v_mfma_f32_16x16x32_bf16 v[4:7], v[184:187], v[228:231], v[4:7]
	v_mfma_f32_16x16x32_bf16 v[0:3], v[196:199], v[228:231], v[0:3]
	s_barrier
	s_add_i32 s72, s72, 2
	s_add_u32 s33, s33, 0x100
	s_addc_u32 s80, s80, 0
	s_cmp_gt_u32 s72, 41
	s_mov_b64 s[56:57], s[58:59]
	s_cbranch_scc0 .LBB0_1014
	s_and_b64 vcc, exec, s[52:53]
	s_cbranch_vccz .LBB0_1017
	s_barrier

; #define PG8_STAGE(bufoff, gbase, voff) do { _Pragma("unroll") for (int _i = 0; _i < 2; ++_i) \
;         __builtin_amdgcn_global_load_lds((const unsigned*)((const char*)(gbase) + (voff)[_i]), (PG8_LAS unsigned*)(lds + (bufoff) + ldsw + _i * 8192), 16, 0, 0); } while (0)
; #define PG8_LDA(dst, b, h) do { _Pragma("unroll") for (int m = 0; m < 4; ++m) _Pragma("unroll") for (int k = 0; k < 2; ++k) dst[m][k] = *(const PG8_LAS bf16x8*)(lds + PG8_SA(b, h) + aoff + m * 2048 + k * 1024); } while (0)
; #define PG8_LDB(dst, b, h) do { _Pragma("unroll") for (int n = 0; n < 2; ++n) _Pragma("unroll") for (int k = 0; k < 2; ++k) dst[n][k] = *(const PG8_LAS bf16x8*)(lds + PG8_SB(b, h) + boff + n * 2048 + k * 1024); } while (0)
; #define PG8_MMA(ai, bj, At, Bt) do { __builtin_amdgcn_s_setprio(1); _Pragma("unroll") for (int m = 0; m < 4; ++m) _Pragma("unroll") for (int n = 0; n < 2; ++n) _Pragma("unroll") for (int k = 0; k < 2; ++k) \
;         acc[ai][bj][m][n] = __builtin_amdgcn_mfma_f32_16x16x32_bf16(Bt[n][k], At[m][k], acc[ai][bj][m][n], 0, 0, 0); __builtin_amdgcn_s_setprio(0); } while (0)
; #define PG8_WAIT_V(n) asm volatile("s_waitcnt vmcnt(" #n ")" ::: "memory")
; #define PG8_WAIT_L(n) asm volatile("s_waitcnt lgkmcnt(" #n ")" ::: "memory")
; template <class Epi, class Sched, bool ALIGN_EPI = false, bool SP2 = false>
; __device__ __forceinline__ void gemm_phase(PG8_LAS unsigned char* lds, const Gemm g, const Sched& S, const Epi& E) {
;     ...
;             const bool last = (t == nt - 2);
;             const char* a1 = cA + (size_t)(t + 1) * kstep;
;             const char* a2 = last ? nA : cA + (size_t)(t + 2) * kstep; const char* b2 = last ? nB : cB + (size_t)(t + 2) * kstep;
;             const char* a3 = a2 + kstep; const char* b3 = b2 + kstep;
;             if (last && has_next) S.a_ready(nxt);
;             if constexpr (SP2) {
;             PG8_LDB(B0, 0, 0); PG8_LDB(B1, 0, 1); PG8_SCHED; PG8_LDA(At, 0, 0); PG8_STAGE(PG8_SA(1, 1), a1 + hstep, voffA);
;             PG8_WAIT_V(8); PG8_WAIT_L(0); PG8_BAR; PG8_MMA(0, 0, At, B0); PG8_MMA(0, 1, At, B1); PG8_BAR; PG8_SCHED;
;             PG8_LDA(At, 0, 1); PG8_STAGE(PG8_SB(0, 0), b2, voffB); PG8_STAGE(PG8_SB(0, 1), b2 + hstep, voffB); PG8_STAGE(PG8_SA(0, 0), a2, voffA);
;             PG8_WAIT_V(8); PG8_WAIT_L(0); PG8_BAR; PG8_MMA(1, 0, At, B0); PG8_MMA(1, 1, At, B1); PG8_BAR; PG8_SCHED;
.LBB0_1617:
	ds_read_b128 v[32:35], v191
	ds_read_b128 v[36:39], v191 offset:1024
	ds_read_b128 v[48:51], v191 offset:2048
	ds_read_b128 v[52:55], v191 offset:3072
	ds_read_b128 v[128:131], v195
	ds_read_b128 v[148:151], v195 offset:1024
	ds_read_b128 v[152:155], v195 offset:2048
	ds_read_b128 v[180:183], v195 offset:3072
	s_add_u32 s6, s56, 0xfffc0080
	s_addc_u32 s7, s57, -1
	s_cmp_eq_u32 s69, 12
	s_cselect_b32 s61, s26, s7
	s_cselect_b32 s60, s29, s6
	s_cselect_b32 s59, s49, s33
	s_cselect_b32 s58, s51, s68
	s_add_i32 m0, s78, 0xc000
	ds_read_b128 v[184:187], v198
	ds_read_b128 v[200:203], v198 offset:1024
	ds_read_b128 v[204:207], v198 offset:2048
	ds_read_b128 v[208:211], v198 offset:3072
	ds_read_b128 v[212:215], v198 offset:4096
	ds_read_b128 v[216:219], v198 offset:5120
	ds_read_b128 v[220:223], v198 offset:6144
	ds_read_b128 v[224:227], v198 offset:7168
	global_load_lds_dwordx4 v172, s[56:57]
	s_add_i32 m0, s78, 0xe000
	s_nop 0
	global_load_lds_dwordx4 v174, s[56:57]
	s_waitcnt vmcnt(8)
	s_waitcnt lgkmcnt(0)
	s_barrier
	s_waitcnt lgkmcnt(0)
	v_mfma_f32_16x16x32_bf16 v[144:147], v[32:35], v[184:187], v[144:147]
	v_mfma_f32_16x16x32_bf16 v[140:143], v[48:51], v[184:187], v[140:143]
	v_mfma_f32_16x16x32_bf16 v[124:127], v[32:35], v[204:207], v[124:127]
	v_mfma_f32_16x16x32_bf16 v[120:123], v[48:51], v[204:207], v[120:123]
	v_mfma_f32_16x16x32_bf16 v[108:111], v[32:35], v[212:215], v[108:111]
	v_mfma_f32_16x16x32_bf16 v[104:107], v[48:51], v[212:215], v[104:107]
	v_mfma_f32_16x16x32_bf16 v[92:95], v[32:35], v[220:223], v[92:95]
	v_mfma_f32_16x16x32_bf16 v[88:91], v[48:51], v[220:223], v[88:91]
	v_mfma_f32_16x16x32_bf16 v[144:147], v[36:39], v[200:203], v[144:147]
	v_mfma_f32_16x16x32_bf16 v[140:143], v[52:55], v[200:203], v[140:143]
	v_mfma_f32_16x16x32_bf16 v[124:127], v[36:39], v[208:211], v[124:127]
	v_mfma_f32_16x16x32_bf16 v[120:123], v[52:55], v[208:211], v[120:123]
	v_mfma_f32_16x16x32_bf16 v[108:111], v[36:39], v[216:219], v[108:111]
	v_mfma_f32_16x16x32_bf16 v[104:107], v[52:55], v[216:219], v[104:107]
	v_mfma_f32_16x16x32_bf16 v[92:95], v[36:39], v[224:227], v[92:95]
	v_mfma_f32_16x16x32_bf16 v[88:91], v[52:55], v[224:227], v[88:91]
	v_mfma_f32_16x16x32_bf16 v[136:139], v[128:131], v[184:187], v[136:139]
	v_mfma_f32_16x16x32_bf16 v[132:135], v[152:155], v[184:187], v[132:135]
	v_mfma_f32_16x16x32_bf16 v[116:119], v[128:131], v[204:207], v[116:119]
	v_mfma_f32_16x16x32_bf16 v[112:115], v[152:155], v[204:207], v[112:115]
	v_mfma_f32_16x16x32_bf16 v[100:103], v[128:131], v[212:215], v[100:103]
	v_mfma_f32_16x16x32_bf16 v[96:99], v[152:155], v[212:215], v[96:99]
	v_mfma_f32_16x16x32_bf16 v[84:87], v[128:131], v[220:223], v[84:87]
	v_mfma_f32_16x16x32_bf16 v[80:83], v[152:155], v[220:223], v[80:83]
	v_mfma_f32_16x16x32_bf16 v[136:139], v[148:151], v[200:203], v[136:139]
	v_mfma_f32_16x16x32_bf16 v[132:135], v[180:183], v[200:203], v[132:135]
	v_mfma_f32_16x16x32_bf16 v[116:119], v[148:151], v[208:211], v[116:119]
	v_mfma_f32_16x16x32_bf16 v[112:115], v[180:183], v[208:211], v[112:115]
	v_mfma_f32_16x16x32_bf16 v[100:103], v[148:151], v[216:219], v[100:103]
	v_mfma_f32_16x16x32_bf16 v[96:99], v[180:183], v[216:219], v[96:99]
	v_mfma_f32_16x16x32_bf16 v[84:87], v[148:151], v[224:227], v[84:87]
	v_mfma_f32_16x16x32_bf16 v[80:83], v[180:183], v[224:227], v[80:83]
	s_barrier
	s_add_i32 s6, s43, s67
	s_mov_b32 m0, s6
	ds_read_b128 v[184:187], v198 offset:16384
	ds_read_b128 v[200:203], v198 offset:17408
	ds_read_b128 v[204:207], v198 offset:18432
	ds_read_b128 v[208:211], v198 offset:19456
	ds_read_b128 v[212:215], v198 offset:20480
	ds_read_b128 v[216:219], v198 offset:21504
	ds_read_b128 v[220:223], v198 offset:22528
	ds_read_b128 v[224:227], v198 offset:23552
	global_load_lds_dwordx4 v158, s[58:59]
	s_add_i32 m0, s6, 0x2000
	s_add_u32 s6, s58, 0x40000
	s_addc_u32 s7, s59, 0
	s_add_i32 s72, s76, s67
	global_load_lds_dwordx4 v170, s[58:59]
	s_mov_b32 m0, s72
	s_nop 0
	global_load_lds_dwordx4 v158, s[6:7]
	s_add_i32 m0, s72, 0x2000
	s_nop 0
	global_load_lds_dwordx4 v170, s[6:7]
	s_mov_b32 m0, s78
	s_nop 0
	global_load_lds_dwordx4 v156, s[60:61]
	s_mov_b32 m0, s79
	s_nop 0
	global_load_lds_dwordx4 v164, s[60:61]
	s_waitcnt vmcnt(8)
	s_waitcnt lgkmcnt(0)
	s_barrier
	s_waitcnt lgkmcnt(0)
	v_mfma_f32_16x16x32_bf16 v[76:79], v[32:35], v[184:187], v[76:79]
	v_mfma_f32_16x16x32_bf16 v[72:75], v[48:51], v[184:187], v[72:75]
	v_mfma_f32_16x16x32_bf16 v[60:63], v[32:35], v[204:207], v[60:63]
	v_mfma_f32_16x16x32_bf16 v[56:59], v[48:51], v[204:207], v[56:59]
	v_mfma_f32_16x16x32_bf16 v[28:31], v[32:35], v[212:215], v[28:31]
	v_mfma_f32_16x16x32_bf16 v[24:27], v[48:51], v[212:215], v[24:27]
	v_mfma_f32_16x16x32_bf16 v[12:15], v[32:35], v[220:223], v[12:15]
	v_mfma_f32_16x16x32_bf16 v[8:11], v[48:51], v[220:223], v[8:11]
	v_mfma_f32_16x16x32_bf16 v[76:79], v[36:39], v[200:203], v[76:79]
	v_mfma_f32_16x16x32_bf16 v[72:75], v[52:55], v[200:203], v[72:75]
	v_mfma_f32_16x16x32_bf16 v[60:63], v[36:39], v[208:211], v[60:63]
	v_mfma_f32_16x16x32_bf16 v[56:59], v[52:55], v[208:211], v[56:59]
	v_mfma_f32_16x16x32_bf16 v[28:31], v[36:39], v[216:219], v[28:31]
	v_mfma_f32_16x16x32_bf16 v[24:27], v[52:55], v[216:219], v[24:27]
	v_mfma_f32_16x16x32_bf16 v[12:15], v[36:39], v[224:227], v[12:15]
	v_mfma_f32_16x16x32_bf16 v[8:11], v[52:55], v[224:227], v[8:11]
	v_mfma_f32_16x16x32_bf16 v[44:47], v[128:131], v[204:207], v[44:47]
	v_mfma_f32_16x16x32_bf16 v[40:43], v[152:155], v[204:207], v[40:43]
	v_mfma_f32_16x16x32_bf16 v[20:23], v[128:131], v[212:215], v[20:23]
	v_mfma_f32_16x16x32_bf16 v[16:19], v[152:155], v[212:215], v[16:19]
	v_mfma_f32_16x16x32_bf16 v[4:7], v[128:131], v[220:223], v[4:7]
	v_mfma_f32_16x16x32_bf16 v[0:3], v[152:155], v[220:223], v[0:3]
	v_mfma_f32_16x16x32_bf16 v[32:35], v[128:131], v[184:187], v[68:71]
	v_mfma_f32_16x16x32_bf16 v[36:39], v[152:155], v[184:187], v[64:67]
	v_mfma_f32_16x16x32_bf16 v[44:47], v[148:151], v[208:211], v[44:47]
	v_mfma_f32_16x16x32_bf16 v[40:43], v[180:183], v[208:211], v[40:43]
	v_mfma_f32_16x16x32_bf16 v[20:23], v[148:151], v[216:219], v[20:23]
	v_mfma_f32_16x16x32_bf16 v[16:19], v[180:183], v[216:219], v[16:19]
	v_mfma_f32_16x16x32_bf16 v[4:7], v[148:151], v[224:227], v[4:7]
	v_mfma_f32_16x16x32_bf16 v[0:3], v[180:183], v[224:227], v[0:3]
	v_mfma_f32_16x16x32_bf16 v[32:35], v[148:151], v[200:203], v[32:35]
	v_mfma_f32_16x16x32_bf16 v[36:39], v[180:183], v[200:203], v[36:39]
	s_barrier
; #define PG8_STAGE(bufoff, gbase, voff) do { _Pragma("unroll") for (int _i = 0; _i < 2; ++_i) \
;         __builtin_amdgcn_global_load_lds((const unsigned*)((const char*)(gbase) + (voff)[_i]), (PG8_LAS unsigned*)(lds + (bufoff) + ldsw + _i * 8192), 16, 0, 0); } while (0)
; #define PG8_LDA(dst, b, h) do { _Pragma("unroll") for (int m = 0; m < 4; ++m) _Pragma("unroll") for (int k = 0; k < 2; ++k) dst[m][k] = *(const PG8_LAS bf16x8*)(lds + PG8_SA(b, h) + aoff + m * 2048 + k * 1024); } while (0)
; #define PG8_LDB(dst, b, h) do { _Pragma("unroll") for (int n = 0; n < 2; ++n) _Pragma("unroll") for (int k = 0; k < 2; ++k) dst[n][k] = *(const PG8_LAS bf16x8*)(lds + PG8_SB(b, h) + boff + n * 2048 + k * 1024); } while (0)
; #define PG8_MMA(ai, bj, At, Bt) do { __builtin_amdgcn_s_setprio(1); _Pragma("unroll") for (int m = 0; m < 4; ++m) _Pragma("unroll") for (int n = 0; n < 2; ++n) _Pragma("unroll") for (int k = 0; k < 2; ++k) \
;         acc[ai][bj][m][n] = __builtin_amdgcn_mfma_f32_16x16x32_bf16(Bt[n][k], At[m][k], acc[ai][bj][m][n], 0, 0, 0); __builtin_amdgcn_s_setprio(0); } while (0)
; #define PG8_WAIT_V(n) asm volatile("s_waitcnt vmcnt(" #n ")" ::: "memory")
; #define PG8_WAIT_L(n) asm volatile("s_waitcnt lgkmcnt(" #n ")" ::: "memory")
; #define PG8_BAR __builtin_amdgcn_s_barrier()
; #define PG8_SCHED __builtin_amdgcn_sched_barrier(0)
; template <class Epi, class Sched, bool ALIGN_EPI = false, bool SP2 = false>
; __device__ __forceinline__ void gemm_phase(PG8_LAS unsigned char* lds, const Gemm g, const Sched& S, const Epi& E) {
;     ...
;             PG8_LDB(B0, 1, 0); PG8_LDB(B1, 1, 1); PG8_SCHED; PG8_LDA(At, 1, 0); PG8_STAGE(PG8_SA(0, 1), a2 + hstep, voffA);
;             PG8_WAIT_V(8); PG8_WAIT_L(0); PG8_BAR; PG8_MMA(0, 0, At, B0); PG8_MMA(0, 1, At, B1); PG8_BAR; PG8_SCHED;
;             PG8_LDA(At, 1, 1); PG8_STAGE(PG8_SB(1, 0), b3, voffB); PG8_STAGE(PG8_SB(1, 1), b3 + hstep, voffB); PG8_STAGE(PG8_SA(1, 0), a3, voffA);
;             PG8_WAIT_V(8); PG8_WAIT_L(0); PG8_BAR; PG8_MMA(1, 0, At, B0); PG8_MMA(1, 1, At, B1); PG8_BAR; PG8_SCHED;
	s_add_i32 s72, 0, 0x18000
	s_add_i32 s73, 0, 0x1c000
	v_add_u32_e32 v68, s72, v169
	v_add_u32_e32 v180, s73, v169
	ds_read_b128 v[48:51], v68
	ds_read_b128 v[52:55], v68 offset:1024
	ds_read_b128 v[64:67], v68 offset:2048
	ds_read_b128 v[68:71], v68 offset:3072
	ds_read_b128 v[128:131], v180
	ds_read_b128 v[148:151], v180 offset:1024
	ds_read_b128 v[152:155], v180 offset:2048
	ds_read_b128 v[180:183], v180 offset:3072
	s_add_u32 s6, s60, 0x40000
	s_addc_u32 s7, s61, 0
	s_mov_b32 m0, s80
	ds_read_b128 v[184:187], v198 offset:32768
	ds_read_b128 v[200:203], v198 offset:33792
	ds_read_b128 v[204:207], v198 offset:34816
	ds_read_b128 v[208:211], v198 offset:35840
	ds_read_b128 v[212:215], v198 offset:36864
	ds_read_b128 v[216:219], v198 offset:37888
	ds_read_b128 v[220:223], v198 offset:38912
	ds_read_b128 v[224:227], v198 offset:39936
	global_load_lds_dwordx4 v156, s[6:7]
	s_mov_b32 m0, s81
	s_nop 0
	global_load_lds_dwordx4 v164, s[6:7]
	s_waitcnt vmcnt(8)
	s_waitcnt lgkmcnt(0)
	s_barrier
	s_waitcnt lgkmcnt(0)
	v_mfma_f32_16x16x32_bf16 v[144:147], v[48:51], v[184:187], v[144:147]
	v_mfma_f32_16x16x32_bf16 v[140:143], v[64:67], v[184:187], v[140:143]
	v_mfma_f32_16x16x32_bf16 v[124:127], v[48:51], v[204:207], v[124:127]
	v_mfma_f32_16x16x32_bf16 v[120:123], v[64:67], v[204:207], v[120:123]
	v_mfma_f32_16x16x32_bf16 v[108:111], v[48:51], v[212:215], v[108:111]
	v_mfma_f32_16x16x32_bf16 v[104:107], v[64:67], v[212:215], v[104:107]
	v_mfma_f32_16x16x32_bf16 v[92:95], v[48:51], v[220:223], v[92:95]
	v_mfma_f32_16x16x32_bf16 v[88:91], v[64:67], v[220:223], v[88:91]
	v_mfma_f32_16x16x32_bf16 v[144:147], v[52:55], v[200:203], v[144:147]
	v_mfma_f32_16x16x32_bf16 v[140:143], v[68:71], v[200:203], v[140:143]
	v_mfma_f32_16x16x32_bf16 v[124:127], v[52:55], v[208:211], v[124:127]
	v_mfma_f32_16x16x32_bf16 v[120:123], v[68:71], v[208:211], v[120:123]
	v_mfma_f32_16x16x32_bf16 v[108:111], v[52:55], v[216:219], v[108:111]
	v_mfma_f32_16x16x32_bf16 v[104:107], v[68:71], v[216:219], v[104:107]
	v_mfma_f32_16x16x32_bf16 v[92:95], v[52:55], v[224:227], v[92:95]
	v_mfma_f32_16x16x32_bf16 v[88:91], v[68:71], v[224:227], v[88:91]
	v_mfma_f32_16x16x32_bf16 v[136:139], v[128:131], v[184:187], v[136:139]
	v_mfma_f32_16x16x32_bf16 v[132:135], v[152:155], v[184:187], v[132:135]
	v_mfma_f32_16x16x32_bf16 v[116:119], v[128:131], v[204:207], v[116:119]
	v_mfma_f32_16x16x32_bf16 v[112:115], v[152:155], v[204:207], v[112:115]
	v_mfma_f32_16x16x32_bf16 v[100:103], v[128:131], v[212:215], v[100:103]
	v_mfma_f32_16x16x32_bf16 v[96:99], v[152:155], v[212:215], v[96:99]
	v_mfma_f32_16x16x32_bf16 v[84:87], v[128:131], v[220:223], v[84:87]
	v_mfma_f32_16x16x32_bf16 v[80:83], v[152:155], v[220:223], v[80:83]
	v_mfma_f32_16x16x32_bf16 v[136:139], v[148:151], v[200:203], v[136:139]
	v_mfma_f32_16x16x32_bf16 v[132:135], v[180:183], v[200:203], v[132:135]
	v_mfma_f32_16x16x32_bf16 v[116:119], v[148:151], v[208:211], v[116:119]
	v_mfma_f32_16x16x32_bf16 v[112:115], v[180:183], v[208:211], v[112:115]
	v_mfma_f32_16x16x32_bf16 v[100:103], v[148:151], v[216:219], v[100:103]
	v_mfma_f32_16x16x32_bf16 v[96:99], v[180:183], v[216:219], v[96:99]
	v_mfma_f32_16x16x32_bf16 v[84:87], v[148:151], v[224:227], v[84:87]
	v_mfma_f32_16x16x32_bf16 v[80:83], v[180:183], v[224:227], v[80:83]
	s_barrier
	s_add_i32 s6, s72, s67
	s_add_u32 s98, s58, 0x80
	s_addc_u32 s99, s59, 0
	s_add_u32 s100, s60, 0x80
	s_addc_u32 s101, s61, 0
	s_mov_b32 m0, s6
	ds_read_b128 v[184:187], v198 offset:49152
	ds_read_b128 v[200:203], v198 offset:50176
	ds_read_b128 v[204:207], v198 offset:51200
	ds_read_b128 v[208:211], v198 offset:52224
	ds_read_b128 v[212:215], v198 offset:53248
	ds_read_b128 v[216:219], v198 offset:54272
	ds_read_b128 v[220:223], v198 offset:55296
	ds_read_b128 v[224:227], v198 offset:56320
	global_load_lds_dwordx4 v158, s[98:99]
	s_add_i32 m0, s6, 0x2000
	s_add_u32 s6, s58, 0x40080
	s_addc_u32 s7, s59, 0
	s_add_i32 s58, s73, s67
	global_load_lds_dwordx4 v170, s[98:99]
	s_mov_b32 m0, s58
	s_nop 0
	global_load_lds_dwordx4 v158, s[6:7]
	s_add_i32 m0, s58, 0x2000
	s_nop 0
	global_load_lds_dwordx4 v170, s[6:7]
	s_mov_b32 m0, s45
	s_nop 0
	global_load_lds_dwordx4 v156, s[100:101]
	s_mov_b32 m0, s42
	s_nop 0
	global_load_lds_dwordx4 v164, s[100:101]
	s_waitcnt vmcnt(8)
	s_waitcnt lgkmcnt(0)
	s_barrier
	s_waitcnt lgkmcnt(0)
	v_mfma_f32_16x16x32_bf16 v[76:79], v[48:51], v[184:187], v[76:79]
	v_mfma_f32_16x16x32_bf16 v[72:75], v[64:67], v[184:187], v[72:75]
	v_mfma_f32_16x16x32_bf16 v[60:63], v[48:51], v[204:207], v[60:63]
	v_mfma_f32_16x16x32_bf16 v[56:59], v[64:67], v[204:207], v[56:59]
	v_mfma_f32_16x16x32_bf16 v[28:31], v[48:51], v[212:215], v[28:31]
	v_mfma_f32_16x16x32_bf16 v[24:27], v[64:67], v[212:215], v[24:27]
	v_mfma_f32_16x16x32_bf16 v[12:15], v[48:51], v[220:223], v[12:15]
	v_mfma_f32_16x16x32_bf16 v[8:11], v[64:67], v[220:223], v[8:11]
	v_mfma_f32_16x16x32_bf16 v[76:79], v[52:55], v[200:203], v[76:79]
	v_mfma_f32_16x16x32_bf16 v[72:75], v[68:71], v[200:203], v[72:75]
	v_mfma_f32_16x16x32_bf16 v[60:63], v[52:55], v[208:211], v[60:63]
	v_mfma_f32_16x16x32_bf16 v[56:59], v[68:71], v[208:211], v[56:59]
	v_mfma_f32_16x16x32_bf16 v[28:31], v[52:55], v[216:219], v[28:31]
	v_mfma_f32_16x16x32_bf16 v[24:27], v[68:71], v[216:219], v[24:27]
	v_mfma_f32_16x16x32_bf16 v[12:15], v[52:55], v[224:227], v[12:15]
	v_mfma_f32_16x16x32_bf16 v[8:11], v[68:71], v[224:227], v[8:11]
	v_mfma_f32_16x16x32_bf16 v[32:35], v[128:131], v[184:187], v[32:35]
	v_mfma_f32_16x16x32_bf16 v[68:71], v[148:151], v[200:203], v[32:35]
	v_mfma_f32_16x16x32_bf16 v[32:35], v[152:155], v[184:187], v[36:39]
	v_mfma_f32_16x16x32_bf16 v[64:67], v[180:183], v[200:203], v[32:35]
	v_mfma_f32_16x16x32_bf16 v[32:35], v[128:131], v[204:207], v[44:47]
	v_mfma_f32_16x16x32_bf16 v[44:47], v[148:151], v[208:211], v[32:35]
	v_mfma_f32_16x16x32_bf16 v[32:35], v[152:155], v[204:207], v[40:43]
	v_mfma_f32_16x16x32_bf16 v[20:23], v[128:131], v[212:215], v[20:23]
	v_mfma_f32_16x16x32_bf16 v[16:19], v[152:155], v[212:215], v[16:19]
	v_mfma_f32_16x16x32_bf16 v[4:7], v[128:131], v[220:223], v[4:7]
	v_mfma_f32_16x16x32_bf16 v[0:3], v[152:155], v[220:223], v[0:3]
	v_mfma_f32_16x16x32_bf16 v[40:43], v[180:183], v[208:211], v[32:35]
	v_mfma_f32_16x16x32_bf16 v[20:23], v[148:151], v[216:219], v[20:23]
	v_mfma_f32_16x16x32_bf16 v[16:19], v[180:183], v[216:219], v[16:19]
	v_mfma_f32_16x16x32_bf16 v[4:7], v[148:151], v[224:227], v[4:7]
	v_mfma_f32_16x16x32_bf16 v[0:3], v[180:183], v[224:227], v[0:3]
	s_barrier
	s_add_i32 s69, s69, 2
	s_add_u32 s56, s56, 0x100
	s_addc_u32 s57, s57, 0
	s_add_u32 s68, s68, 0x100
	s_addc_u32 s33, s33, 0
	s_cmp_gt_u32 s69, 13
	s_cbranch_scc0 .LBB0_1617
	v_readlane_b32 s68, v243, 59
	s_and_b64 vcc, exec, s[40:41]
	v_readlane_b32 s69, v243, 60
	s_cbranch_vccz .LBB0_1620
	s_barrier

; #define PG8_STAGE(bufoff, gbase, voff) do { _Pragma("unroll") for (int _i = 0; _i < 2; ++_i) \
;         __builtin_amdgcn_global_load_lds((const unsigned*)((const char*)(gbase) + (voff)[_i]), (PG8_LAS unsigned*)(lds + (bufoff) + ldsw + _i * 8192), 16, 0, 0); } while (0)
; #define PG8_LDA(dst, b, h) do { _Pragma("unroll") for (int m = 0; m < 4; ++m) _Pragma("unroll") for (int k = 0; k < 2; ++k) dst[m][k] = *(const PG8_LAS bf16x8*)(lds + PG8_SA(b, h) + aoff + m * 2048 + k * 1024); } while (0)
; #define PG8_LDB(dst, b, h) do { _Pragma("unroll") for (int n = 0; n < 2; ++n) _Pragma("unroll") for (int k = 0; k < 2; ++k) dst[n][k] = *(const PG8_LAS bf16x8*)(lds + PG8_SB(b, h) + boff + n * 2048 + k * 1024); } while (0)
; #define PG8_MMA(ai, bj, At, Bt) do { __builtin_amdgcn_s_setprio(1); _Pragma("unroll") for (int m = 0; m < 4; ++m) _Pragma("unroll") for (int n = 0; n < 2; ++n) _Pragma("unroll") for (int k = 0; k < 2; ++k) \
;         acc[ai][bj][m][n] = __builtin_amdgcn_mfma_f32_16x16x32_bf16(Bt[n][k], At[m][k], acc[ai][bj][m][n], 0, 0, 0); __builtin_amdgcn_s_setprio(0); } while (0)
; #define PG8_WAIT_V(n) asm volatile("s_waitcnt vmcnt(" #n ")" ::: "memory")
; #define PG8_WAIT_L(n) asm volatile("s_waitcnt lgkmcnt(" #n ")" ::: "memory")
; template <class Epi, class Sched, bool ALIGN_EPI = false, bool SP2 = false>
; __device__ __forceinline__ void gemm_phase(PG8_LAS unsigned char* lds, const Gemm g, const Sched& S, const Epi& E) {
;     ...
;             const bool last = (t == nt - 2);
;             const char* a1 = cA + (size_t)(t + 1) * kstep;
;             const char* a2 = last ? nA : cA + (size_t)(t + 2) * kstep; const char* b2 = last ? nB : cB + (size_t)(t + 2) * kstep;
;             const char* a3 = a2 + kstep; const char* b3 = b2 + kstep;
;             if (last && has_next) S.a_ready(nxt);
;             if constexpr (SP2) {
;             PG8_LDB(B0, 0, 0); PG8_LDB(B1, 0, 1); PG8_SCHED; PG8_LDA(At, 0, 0); PG8_STAGE(PG8_SA(1, 1), a1 + hstep, voffA);
;             PG8_WAIT_V(8); PG8_WAIT_L(0); PG8_BAR; PG8_MMA(0, 0, At, B0); PG8_MMA(0, 1, At, B1); PG8_BAR; PG8_SCHED;
;             PG8_LDA(At, 0, 1); PG8_STAGE(PG8_SB(0, 0), b2, voffB); PG8_STAGE(PG8_SB(0, 1), b2 + hstep, voffB); PG8_STAGE(PG8_SA(0, 0), a2, voffA);
;             PG8_WAIT_V(8); PG8_WAIT_L(0); PG8_BAR; PG8_MMA(1, 0, At, B0); PG8_MMA(1, 1, At, B1); PG8_BAR; PG8_SCHED;
.LBB0_1698:
	ds_read_b128 v[144:147], v153
	ds_read_b128 v[170:173], v153 offset:1024
	ds_read_b128 v[174:177], v153 offset:2048
	ds_read_b128 v[178:181], v153 offset:3072
	ds_read_b128 v[182:185], v154
	ds_read_b128 v[186:189], v154 offset:1024
	ds_read_b128 v[198:201], v154 offset:2048
	ds_read_b128 v[202:205], v154 offset:3072
	s_add_u32 s6, s60, 0xfffc0080
	s_addc_u32 s7, s61, -1
	s_cmp_eq_u32 s72, 12
	s_cselect_b32 s81, s29, s7
	s_cselect_b32 s80, s55, s6
	s_cselect_b32 s79, s53, s33
	s_cselect_b32 s78, s68, s69
	s_add_i32 m0, s43, 0xc000
	ds_read_b128 v[206:209], v155
	ds_read_b128 v[210:213], v155 offset:1024
	ds_read_b128 v[214:217], v155 offset:2048
	ds_read_b128 v[218:221], v155 offset:3072
	ds_read_b128 v[222:225], v155 offset:4096
	ds_read_b128 v[226:229], v155 offset:5120
	ds_read_b128 v[230:233], v155 offset:6144
	ds_read_b128 v[234:237], v155 offset:7168
	global_load_lds_dwordx4 v136, s[60:61]
	s_add_i32 m0, s43, 0xe000
	s_nop 0
	global_load_lds_dwordx4 v138, s[60:61]
	s_waitcnt vmcnt(8)
	s_waitcnt lgkmcnt(0)
	s_barrier
	s_waitcnt lgkmcnt(0)
	v_mfma_f32_16x16x32_bf16 v[124:127], v[144:147], v[206:209], v[124:127]
	v_mfma_f32_16x16x32_bf16 v[120:123], v[174:177], v[206:209], v[120:123]
	v_mfma_f32_16x16x32_bf16 v[108:111], v[144:147], v[214:217], v[108:111]
	v_mfma_f32_16x16x32_bf16 v[104:107], v[174:177], v[214:217], v[104:107]
	v_mfma_f32_16x16x32_bf16 v[92:95], v[144:147], v[222:225], v[92:95]
	v_mfma_f32_16x16x32_bf16 v[88:91], v[174:177], v[222:225], v[88:91]
	v_mfma_f32_16x16x32_bf16 v[76:79], v[144:147], v[230:233], v[76:79]
	v_mfma_f32_16x16x32_bf16 v[72:75], v[174:177], v[230:233], v[72:75]
	v_mfma_f32_16x16x32_bf16 v[124:127], v[170:173], v[210:213], v[124:127]
	v_mfma_f32_16x16x32_bf16 v[120:123], v[178:181], v[210:213], v[120:123]
	v_mfma_f32_16x16x32_bf16 v[108:111], v[170:173], v[218:221], v[108:111]
	v_mfma_f32_16x16x32_bf16 v[104:107], v[178:181], v[218:221], v[104:107]
	v_mfma_f32_16x16x32_bf16 v[92:95], v[170:173], v[226:229], v[92:95]
	v_mfma_f32_16x16x32_bf16 v[88:91], v[178:181], v[226:229], v[88:91]
	v_mfma_f32_16x16x32_bf16 v[76:79], v[170:173], v[234:237], v[76:79]
	v_mfma_f32_16x16x32_bf16 v[72:75], v[178:181], v[234:237], v[72:75]
	v_mfma_f32_16x16x32_bf16 v[116:119], v[182:185], v[206:209], v[116:119]
	v_mfma_f32_16x16x32_bf16 v[112:115], v[198:201], v[206:209], v[112:115]
	v_mfma_f32_16x16x32_bf16 v[100:103], v[182:185], v[214:217], v[100:103]
	v_mfma_f32_16x16x32_bf16 v[96:99], v[198:201], v[214:217], v[96:99]
	v_mfma_f32_16x16x32_bf16 v[84:87], v[182:185], v[222:225], v[84:87]
	v_mfma_f32_16x16x32_bf16 v[80:83], v[198:201], v[222:225], v[80:83]
	v_mfma_f32_16x16x32_bf16 v[68:71], v[182:185], v[230:233], v[68:71]
	v_mfma_f32_16x16x32_bf16 v[64:67], v[198:201], v[230:233], v[64:67]
	v_mfma_f32_16x16x32_bf16 v[116:119], v[186:189], v[210:213], v[116:119]
	v_mfma_f32_16x16x32_bf16 v[112:115], v[202:205], v[210:213], v[112:115]
	v_mfma_f32_16x16x32_bf16 v[100:103], v[186:189], v[218:221], v[100:103]
	v_mfma_f32_16x16x32_bf16 v[96:99], v[202:205], v[218:221], v[96:99]
	v_mfma_f32_16x16x32_bf16 v[84:87], v[186:189], v[226:229], v[84:87]
	v_mfma_f32_16x16x32_bf16 v[80:83], v[202:205], v[226:229], v[80:83]
	v_mfma_f32_16x16x32_bf16 v[68:71], v[186:189], v[234:237], v[68:71]
	v_mfma_f32_16x16x32_bf16 v[64:67], v[202:205], v[234:237], v[64:67]
	s_barrier
	s_add_i32 s6, s26, s42
	s_mov_b32 m0, s6
	ds_read_b128 v[206:209], v155 offset:16384
	ds_read_b128 v[210:213], v155 offset:17408
	ds_read_b128 v[214:217], v155 offset:18432
	ds_read_b128 v[218:221], v155 offset:19456
	ds_read_b128 v[222:225], v155 offset:20480
	ds_read_b128 v[226:229], v155 offset:21504
	ds_read_b128 v[230:233], v155 offset:22528
	ds_read_b128 v[234:237], v155 offset:23552
	global_load_lds_dwordx4 v130, s[78:79]
	s_add_i32 m0, s6, 0x2000
	s_add_u32 s6, s78, 0x40000
	s_addc_u32 s7, s79, 0
	s_add_i32 s73, s74, s42
	global_load_lds_dwordx4 v134, s[78:79]
	s_mov_b32 m0, s73
	s_nop 0
	global_load_lds_dwordx4 v130, s[6:7]
	s_add_i32 m0, s73, 0x2000
	s_nop 0
	global_load_lds_dwordx4 v134, s[6:7]
	s_mov_b32 m0, s43
	s_nop 0
	global_load_lds_dwordx4 v128, s[80:81]
	s_mov_b32 m0, s44
	s_nop 0
	global_load_lds_dwordx4 v132, s[80:81]
	s_waitcnt vmcnt(8)
	s_waitcnt lgkmcnt(0)
	s_barrier
	s_waitcnt lgkmcnt(0)
	v_mfma_f32_16x16x32_bf16 v[60:63], v[144:147], v[206:209], v[60:63]
	v_mfma_f32_16x16x32_bf16 v[56:59], v[174:177], v[206:209], v[56:59]
	v_mfma_f32_16x16x32_bf16 v[44:47], v[144:147], v[214:217], v[44:47]
	v_mfma_f32_16x16x32_bf16 v[40:43], v[174:177], v[214:217], v[40:43]
	v_mfma_f32_16x16x32_bf16 v[28:31], v[144:147], v[222:225], v[28:31]
	v_mfma_f32_16x16x32_bf16 v[24:27], v[174:177], v[222:225], v[24:27]
	v_mfma_f32_16x16x32_bf16 v[12:15], v[144:147], v[230:233], v[12:15]
	v_mfma_f32_16x16x32_bf16 v[8:11], v[174:177], v[230:233], v[8:11]
	v_mfma_f32_16x16x32_bf16 v[60:63], v[170:173], v[210:213], v[60:63]
	v_mfma_f32_16x16x32_bf16 v[56:59], v[178:181], v[210:213], v[56:59]
	v_mfma_f32_16x16x32_bf16 v[44:47], v[170:173], v[218:221], v[44:47]
	v_mfma_f32_16x16x32_bf16 v[40:43], v[178:181], v[218:221], v[40:43]
	v_mfma_f32_16x16x32_bf16 v[28:31], v[170:173], v[226:229], v[28:31]
	v_mfma_f32_16x16x32_bf16 v[24:27], v[178:181], v[226:229], v[24:27]
	v_mfma_f32_16x16x32_bf16 v[12:15], v[170:173], v[234:237], v[12:15]
	v_mfma_f32_16x16x32_bf16 v[8:11], v[178:181], v[234:237], v[8:11]
	v_mfma_f32_16x16x32_bf16 v[52:55], v[182:185], v[206:209], v[52:55]
	v_mfma_f32_16x16x32_bf16 v[48:51], v[198:201], v[206:209], v[48:51]
	v_mfma_f32_16x16x32_bf16 v[36:39], v[182:185], v[214:217], v[36:39]
	v_mfma_f32_16x16x32_bf16 v[32:35], v[198:201], v[214:217], v[32:35]
	v_mfma_f32_16x16x32_bf16 v[20:23], v[182:185], v[222:225], v[20:23]
	v_mfma_f32_16x16x32_bf16 v[16:19], v[198:201], v[222:225], v[16:19]
	v_mfma_f32_16x16x32_bf16 v[4:7], v[182:185], v[230:233], v[4:7]
	v_mfma_f32_16x16x32_bf16 v[0:3], v[198:201], v[230:233], v[0:3]
	v_mfma_f32_16x16x32_bf16 v[52:55], v[186:189], v[210:213], v[52:55]
	v_mfma_f32_16x16x32_bf16 v[48:51], v[202:205], v[210:213], v[48:51]
	v_mfma_f32_16x16x32_bf16 v[36:39], v[186:189], v[218:221], v[36:39]
	v_mfma_f32_16x16x32_bf16 v[32:35], v[202:205], v[218:221], v[32:35]
	v_mfma_f32_16x16x32_bf16 v[20:23], v[186:189], v[226:229], v[20:23]
	v_mfma_f32_16x16x32_bf16 v[16:19], v[202:205], v[226:229], v[16:19]
	v_mfma_f32_16x16x32_bf16 v[4:7], v[186:189], v[234:237], v[4:7]
	v_mfma_f32_16x16x32_bf16 v[0:3], v[202:205], v[234:237], v[0:3]
	s_barrier
; #define PG8_STAGE(bufoff, gbase, voff) do { _Pragma("unroll") for (int _i = 0; _i < 2; ++_i) \
;         __builtin_amdgcn_global_load_lds((const unsigned*)((const char*)(gbase) + (voff)[_i]), (PG8_LAS unsigned*)(lds + (bufoff) + ldsw + _i * 8192), 16, 0, 0); } while (0)
; #define PG8_LDA(dst, b, h) do { _Pragma("unroll") for (int m = 0; m < 4; ++m) _Pragma("unroll") for (int k = 0; k < 2; ++k) dst[m][k] = *(const PG8_LAS bf16x8*)(lds + PG8_SA(b, h) + aoff + m * 2048 + k * 1024); } while (0)
; #define PG8_LDB(dst, b, h) do { _Pragma("unroll") for (int n = 0; n < 2; ++n) _Pragma("unroll") for (int k = 0; k < 2; ++k) dst[n][k] = *(const PG8_LAS bf16x8*)(lds + PG8_SB(b, h) + boff + n * 2048 + k * 1024); } while (0)
; #define PG8_MMA(ai, bj, At, Bt) do { __builtin_amdgcn_s_setprio(1); _Pragma("unroll") for (int m = 0; m < 4; ++m) _Pragma("unroll") for (int n = 0; n < 2; ++n) _Pragma("unroll") for (int k = 0; k < 2; ++k) \
;         acc[ai][bj][m][n] = __builtin_amdgcn_mfma_f32_16x16x32_bf16(Bt[n][k], At[m][k], acc[ai][bj][m][n], 0, 0, 0); __builtin_amdgcn_s_setprio(0); } while (0)
; #define PG8_WAIT_V(n) asm volatile("s_waitcnt vmcnt(" #n ")" ::: "memory")
; #define PG8_WAIT_L(n) asm volatile("s_waitcnt lgkmcnt(" #n ")" ::: "memory")
; #define PG8_BAR __builtin_amdgcn_s_barrier()
; #define PG8_SCHED __builtin_amdgcn_sched_barrier(0)
; template <class Epi, class Sched, bool ALIGN_EPI = false, bool SP2 = false>
; __device__ __forceinline__ void gemm_phase(PG8_LAS unsigned char* lds, const Gemm g, const Sched& S, const Epi& E) {
;     ...
;             PG8_LDB(B0, 1, 0); PG8_LDB(B1, 1, 1); PG8_SCHED; PG8_LDA(At, 1, 0); PG8_STAGE(PG8_SA(0, 1), a2 + hstep, voffA);
;             PG8_WAIT_V(8); PG8_WAIT_L(0); PG8_BAR; PG8_MMA(0, 0, At, B0); PG8_MMA(0, 1, At, B1); PG8_BAR; PG8_SCHED;
;             PG8_LDA(At, 1, 1); PG8_STAGE(PG8_SB(1, 0), b3, voffB); PG8_STAGE(PG8_SB(1, 1), b3 + hstep, voffB); PG8_STAGE(PG8_SA(1, 0), a3, voffA);
;             PG8_WAIT_V(8); PG8_WAIT_L(0); PG8_BAR; PG8_MMA(1, 0, At, B0); PG8_MMA(1, 1, At, B1); PG8_BAR; PG8_SCHED;
	s_add_i32 s73, 0, 0x18000
	v_add_u32_e32 v157, s73, v151
	s_add_i32 s82, 0, 0x1c000
	ds_read_b128 v[144:147], v157
	ds_read_b128 v[170:173], v157 offset:1024
	ds_read_b128 v[174:177], v157 offset:2048
	ds_read_b128 v[178:181], v157 offset:3072
	v_add_u32_e32 v157, s82, v151
	ds_read_b128 v[182:185], v157
	ds_read_b128 v[186:189], v157 offset:1024
	ds_read_b128 v[198:201], v157 offset:2048
	ds_read_b128 v[202:205], v157 offset:3072
	s_add_u32 s6, s80, 0x40000
	s_addc_u32 s7, s81, 0
	s_mov_b32 m0, s45
	ds_read_b128 v[206:209], v155 offset:32768
	ds_read_b128 v[210:213], v155 offset:33792
	ds_read_b128 v[214:217], v155 offset:34816
	ds_read_b128 v[218:221], v155 offset:35840
	ds_read_b128 v[222:225], v155 offset:36864
	ds_read_b128 v[226:229], v155 offset:37888
	ds_read_b128 v[230:233], v155 offset:38912
	ds_read_b128 v[234:237], v155 offset:39936
	global_load_lds_dwordx4 v128, s[6:7]
	s_mov_b32 m0, s67
	s_nop 0
	global_load_lds_dwordx4 v132, s[6:7]
	s_waitcnt vmcnt(8)
	s_waitcnt lgkmcnt(0)
	s_barrier
	s_waitcnt lgkmcnt(0)
	v_mfma_f32_16x16x32_bf16 v[124:127], v[144:147], v[206:209], v[124:127]
	v_mfma_f32_16x16x32_bf16 v[120:123], v[174:177], v[206:209], v[120:123]
	v_mfma_f32_16x16x32_bf16 v[108:111], v[144:147], v[214:217], v[108:111]
	v_mfma_f32_16x16x32_bf16 v[104:107], v[174:177], v[214:217], v[104:107]
	v_mfma_f32_16x16x32_bf16 v[92:95], v[144:147], v[222:225], v[92:95]
	v_mfma_f32_16x16x32_bf16 v[88:91], v[174:177], v[222:225], v[88:91]
	v_mfma_f32_16x16x32_bf16 v[76:79], v[144:147], v[230:233], v[76:79]
	v_mfma_f32_16x16x32_bf16 v[72:75], v[174:177], v[230:233], v[72:75]
	v_mfma_f32_16x16x32_bf16 v[124:127], v[170:173], v[210:213], v[124:127]
	v_mfma_f32_16x16x32_bf16 v[120:123], v[178:181], v[210:213], v[120:123]
	v_mfma_f32_16x16x32_bf16 v[108:111], v[170:173], v[218:221], v[108:111]
	v_mfma_f32_16x16x32_bf16 v[104:107], v[178:181], v[218:221], v[104:107]
	v_mfma_f32_16x16x32_bf16 v[92:95], v[170:173], v[226:229], v[92:95]
	v_mfma_f32_16x16x32_bf16 v[88:91], v[178:181], v[226:229], v[88:91]
	v_mfma_f32_16x16x32_bf16 v[76:79], v[170:173], v[234:237], v[76:79]
	v_mfma_f32_16x16x32_bf16 v[72:75], v[178:181], v[234:237], v[72:75]
	v_mfma_f32_16x16x32_bf16 v[116:119], v[182:185], v[206:209], v[116:119]
	v_mfma_f32_16x16x32_bf16 v[112:115], v[198:201], v[206:209], v[112:115]
	v_mfma_f32_16x16x32_bf16 v[100:103], v[182:185], v[214:217], v[100:103]
	v_mfma_f32_16x16x32_bf16 v[96:99], v[198:201], v[214:217], v[96:99]
	v_mfma_f32_16x16x32_bf16 v[84:87], v[182:185], v[222:225], v[84:87]
	v_mfma_f32_16x16x32_bf16 v[80:83], v[198:201], v[222:225], v[80:83]
	v_mfma_f32_16x16x32_bf16 v[68:71], v[182:185], v[230:233], v[68:71]
	v_mfma_f32_16x16x32_bf16 v[64:67], v[198:201], v[230:233], v[64:67]
	v_mfma_f32_16x16x32_bf16 v[116:119], v[186:189], v[210:213], v[116:119]
	v_mfma_f32_16x16x32_bf16 v[112:115], v[202:205], v[210:213], v[112:115]
	v_mfma_f32_16x16x32_bf16 v[100:103], v[186:189], v[218:221], v[100:103]
	v_mfma_f32_16x16x32_bf16 v[96:99], v[202:205], v[218:221], v[96:99]
	v_mfma_f32_16x16x32_bf16 v[84:87], v[186:189], v[226:229], v[84:87]
	v_mfma_f32_16x16x32_bf16 v[80:83], v[202:205], v[226:229], v[80:83]
	v_mfma_f32_16x16x32_bf16 v[68:71], v[186:189], v[234:237], v[68:71]
	v_mfma_f32_16x16x32_bf16 v[64:67], v[202:205], v[234:237], v[64:67]
	s_barrier
	s_add_i32 s6, s73, s42
	s_add_u32 s98, s78, 0x80
	s_addc_u32 s99, s79, 0
	s_add_u32 s100, s80, 0x80
	s_addc_u32 s101, s81, 0
	s_mov_b32 m0, s6
	ds_read_b128 v[206:209], v155 offset:49152
	ds_read_b128 v[210:213], v155 offset:50176
	ds_read_b128 v[214:217], v155 offset:51200
	ds_read_b128 v[218:221], v155 offset:52224
	ds_read_b128 v[222:225], v155 offset:53248
	ds_read_b128 v[226:229], v155 offset:54272
	ds_read_b128 v[230:233], v155 offset:55296
	ds_read_b128 v[234:237], v155 offset:56320
	global_load_lds_dwordx4 v130, s[98:99]
	s_add_i32 m0, s6, 0x2000
	s_add_u32 s6, s78, 0x40080
	s_addc_u32 s7, s79, 0
	s_add_i32 s73, s82, s42
	global_load_lds_dwordx4 v134, s[98:99]
	s_mov_b32 m0, s73
	s_nop 0
	global_load_lds_dwordx4 v130, s[6:7]
	s_add_i32 m0, s73, 0x2000
	s_nop 0
	global_load_lds_dwordx4 v134, s[6:7]
	s_mov_b32 m0, s4
	s_nop 0
	global_load_lds_dwordx4 v128, s[100:101]
	s_mov_b32 m0, s77
	s_nop 0
	global_load_lds_dwordx4 v132, s[100:101]
	s_waitcnt vmcnt(8)
	s_waitcnt lgkmcnt(0)
	s_barrier
	s_waitcnt lgkmcnt(0)
	v_mfma_f32_16x16x32_bf16 v[60:63], v[144:147], v[206:209], v[60:63]
	v_mfma_f32_16x16x32_bf16 v[56:59], v[174:177], v[206:209], v[56:59]
	v_mfma_f32_16x16x32_bf16 v[44:47], v[144:147], v[214:217], v[44:47]
	v_mfma_f32_16x16x32_bf16 v[40:43], v[174:177], v[214:217], v[40:43]
	v_mfma_f32_16x16x32_bf16 v[28:31], v[144:147], v[222:225], v[28:31]
	v_mfma_f32_16x16x32_bf16 v[24:27], v[174:177], v[222:225], v[24:27]
	v_mfma_f32_16x16x32_bf16 v[12:15], v[144:147], v[230:233], v[12:15]
	v_mfma_f32_16x16x32_bf16 v[8:11], v[174:177], v[230:233], v[8:11]
	v_mfma_f32_16x16x32_bf16 v[60:63], v[170:173], v[210:213], v[60:63]
	v_mfma_f32_16x16x32_bf16 v[56:59], v[178:181], v[210:213], v[56:59]
	v_mfma_f32_16x16x32_bf16 v[44:47], v[170:173], v[218:221], v[44:47]
	v_mfma_f32_16x16x32_bf16 v[40:43], v[178:181], v[218:221], v[40:43]
	v_mfma_f32_16x16x32_bf16 v[28:31], v[170:173], v[226:229], v[28:31]
	v_mfma_f32_16x16x32_bf16 v[24:27], v[178:181], v[226:229], v[24:27]
	v_mfma_f32_16x16x32_bf16 v[12:15], v[170:173], v[234:237], v[12:15]
	v_mfma_f32_16x16x32_bf16 v[8:11], v[178:181], v[234:237], v[8:11]
	v_mfma_f32_16x16x32_bf16 v[52:55], v[182:185], v[206:209], v[52:55]
	v_mfma_f32_16x16x32_bf16 v[48:51], v[198:201], v[206:209], v[48:51]
	v_mfma_f32_16x16x32_bf16 v[36:39], v[182:185], v[214:217], v[36:39]
	v_mfma_f32_16x16x32_bf16 v[32:35], v[198:201], v[214:217], v[32:35]
	v_mfma_f32_16x16x32_bf16 v[20:23], v[182:185], v[222:225], v[20:23]
	v_mfma_f32_16x16x32_bf16 v[16:19], v[198:201], v[222:225], v[16:19]
	v_mfma_f32_16x16x32_bf16 v[4:7], v[182:185], v[230:233], v[4:7]
	v_mfma_f32_16x16x32_bf16 v[0:3], v[198:201], v[230:233], v[0:3]
	v_mfma_f32_16x16x32_bf16 v[52:55], v[186:189], v[210:213], v[52:55]
	v_mfma_f32_16x16x32_bf16 v[48:51], v[202:205], v[210:213], v[48:51]
	v_mfma_f32_16x16x32_bf16 v[36:39], v[186:189], v[218:221], v[36:39]
	v_mfma_f32_16x16x32_bf16 v[32:35], v[202:205], v[218:221], v[32:35]
	v_mfma_f32_16x16x32_bf16 v[20:23], v[186:189], v[226:229], v[20:23]
	v_mfma_f32_16x16x32_bf16 v[16:19], v[202:205], v[226:229], v[16:19]
	v_mfma_f32_16x16x32_bf16 v[4:7], v[186:189], v[234:237], v[4:7]
	v_mfma_f32_16x16x32_bf16 v[0:3], v[202:205], v[234:237], v[0:3]
	s_barrier
	s_add_i32 s72, s72, 2
	s_add_u32 s60, s60, 0x100
	s_addc_u32 s61, s61, 0
	s_add_u32 s69, s69, 0x100
	s_addc_u32 s33, s33, 0
	s_cmp_gt_u32 s72, 13
	s_cbranch_scc0 .LBB0_1698
	s_and_b64 vcc, exec, s[50:51]
	s_cbranch_vccz .LBB0_1701
	s_barrier

; #define PG8_STAGE(bufoff, gbase, voff) do { _Pragma("unroll") for (int _i = 0; _i < 2; ++_i) \
;         __builtin_amdgcn_global_load_lds((const unsigned*)((const char*)(gbase) + (voff)[_i]), (PG8_LAS unsigned*)(lds + (bufoff) + ldsw + _i * 8192), 16, 0, 0); } while (0)
; #define PG8_LDA(dst, b, h) do { _Pragma("unroll") for (int m = 0; m < 4; ++m) _Pragma("unroll") for (int k = 0; k < 2; ++k) dst[m][k] = *(const PG8_LAS bf16x8*)(lds + PG8_SA(b, h) + aoff + m * 2048 + k * 1024); } while (0)
; #define PG8_LDB(dst, b, h) do { _Pragma("unroll") for (int n = 0; n < 2; ++n) _Pragma("unroll") for (int k = 0; k < 2; ++k) dst[n][k] = *(const PG8_LAS bf16x8*)(lds + PG8_SB(b, h) + boff + n * 2048 + k * 1024); } while (0)
; #define PG8_MMA(ai, bj, At, Bt) do { __builtin_amdgcn_s_setprio(1); _Pragma("unroll") for (int m = 0; m < 4; ++m) _Pragma("unroll") for (int n = 0; n < 2; ++n) _Pragma("unroll") for (int k = 0; k < 2; ++k) \
;         acc[ai][bj][m][n] = __builtin_amdgcn_mfma_f32_16x16x32_bf16(Bt[n][k], At[m][k], acc[ai][bj][m][n], 0, 0, 0); __builtin_amdgcn_s_setprio(0); } while (0)
; #define PG8_WAIT_V(n) asm volatile("s_waitcnt vmcnt(" #n ")" ::: "memory")
; #define PG8_WAIT_L(n) asm volatile("s_waitcnt lgkmcnt(" #n ")" ::: "memory")
; template <class Epi, class Sched, bool ALIGN_EPI = false, bool SP2 = false>
; __device__ __forceinline__ void gemm_phase(PG8_LAS unsigned char* lds, const Gemm g, const Sched& S, const Epi& E) {
;     ...
;             const bool last = (t == nt - 2);
;             const char* a1 = cA + (size_t)(t + 1) * kstep;
;             const char* a2 = last ? nA : cA + (size_t)(t + 2) * kstep; const char* b2 = last ? nB : cB + (size_t)(t + 2) * kstep;
;             const char* a3 = a2 + kstep; const char* b3 = b2 + kstep;
;             if (last && has_next) S.a_ready(nxt);
;             if constexpr (SP2) {
;             PG8_LDB(B0, 0, 0); PG8_LDB(B1, 0, 1); PG8_SCHED; PG8_LDA(At, 0, 0); PG8_STAGE(PG8_SA(1, 1), a1 + hstep, voffA);
;             PG8_WAIT_V(8); PG8_WAIT_L(0); PG8_BAR; PG8_MMA(0, 0, At, B0); PG8_MMA(0, 1, At, B1); PG8_BAR; PG8_SCHED;
;             PG8_LDA(At, 0, 1); PG8_STAGE(PG8_SB(0, 0), b2, voffB); PG8_STAGE(PG8_SB(0, 1), b2 + hstep, voffB); PG8_STAGE(PG8_SA(0, 0), a2, voffA);
;             PG8_WAIT_V(8); PG8_WAIT_L(0); PG8_BAR; PG8_MMA(1, 0, At, B0); PG8_MMA(1, 1, At, B1); PG8_BAR; PG8_SCHED;
.LBB0_1822:
	ds_read_b128 v[144:147], v154
	ds_read_b128 v[168:171], v154 offset:1024
	ds_read_b128 v[172:175], v154 offset:2048
	ds_read_b128 v[176:179], v154 offset:3072
	ds_read_b128 v[180:183], v155
	ds_read_b128 v[184:187], v155 offset:1024
	ds_read_b128 v[188:191], v155 offset:2048
	ds_read_b128 v[198:201], v155 offset:3072
	s_add_u32 s6, s50, 0xfffc0080
	s_addc_u32 s7, s51, -1
	s_cmp_eq_u32 s72, 12
	s_cselect_b32 s55, s39, s7
	s_cselect_b32 s54, s69, s6
	s_cselect_b32 s53, s37, s33
	s_cselect_b32 s52, s74, s75
	s_add_i32 m0, s27, 0xc000
	ds_read_b128 v[202:205], v156
	ds_read_b128 v[206:209], v156 offset:1024
	ds_read_b128 v[210:213], v156 offset:2048
	ds_read_b128 v[214:217], v156 offset:3072
	ds_read_b128 v[218:221], v156 offset:4096
	ds_read_b128 v[222:225], v156 offset:5120
	ds_read_b128 v[226:229], v156 offset:6144
	ds_read_b128 v[230:233], v156 offset:7168
	global_load_lds_dwordx4 v136, s[50:51]
	s_add_i32 m0, s27, 0xe000
	s_nop 0
	global_load_lds_dwordx4 v138, s[50:51]
	s_waitcnt vmcnt(8)
	s_waitcnt lgkmcnt(0)
	s_barrier
	s_waitcnt lgkmcnt(0)
	v_mfma_f32_16x16x32_bf16 v[124:127], v[144:147], v[202:205], v[124:127]
	v_mfma_f32_16x16x32_bf16 v[116:119], v[172:175], v[202:205], v[116:119]
	v_mfma_f32_16x16x32_bf16 v[108:111], v[144:147], v[210:213], v[108:111]
	v_mfma_f32_16x16x32_bf16 v[100:103], v[172:175], v[210:213], v[100:103]
	v_mfma_f32_16x16x32_bf16 v[92:95], v[144:147], v[218:221], v[92:95]
	v_mfma_f32_16x16x32_bf16 v[84:87], v[172:175], v[218:221], v[84:87]
	v_mfma_f32_16x16x32_bf16 v[76:79], v[144:147], v[226:229], v[76:79]
	v_mfma_f32_16x16x32_bf16 v[68:71], v[172:175], v[226:229], v[68:71]
	v_mfma_f32_16x16x32_bf16 v[124:127], v[168:171], v[206:209], v[124:127]
	v_mfma_f32_16x16x32_bf16 v[116:119], v[176:179], v[206:209], v[116:119]
	v_mfma_f32_16x16x32_bf16 v[108:111], v[168:171], v[214:217], v[108:111]
	v_mfma_f32_16x16x32_bf16 v[100:103], v[176:179], v[214:217], v[100:103]
	v_mfma_f32_16x16x32_bf16 v[92:95], v[168:171], v[222:225], v[92:95]
	v_mfma_f32_16x16x32_bf16 v[84:87], v[176:179], v[222:225], v[84:87]
	v_mfma_f32_16x16x32_bf16 v[76:79], v[168:171], v[230:233], v[76:79]
	v_mfma_f32_16x16x32_bf16 v[68:71], v[176:179], v[230:233], v[68:71]
	v_mfma_f32_16x16x32_bf16 v[120:123], v[180:183], v[202:205], v[120:123]
	v_mfma_f32_16x16x32_bf16 v[112:115], v[188:191], v[202:205], v[112:115]
	v_mfma_f32_16x16x32_bf16 v[104:107], v[180:183], v[210:213], v[104:107]
	v_mfma_f32_16x16x32_bf16 v[96:99], v[188:191], v[210:213], v[96:99]
	v_mfma_f32_16x16x32_bf16 v[88:91], v[180:183], v[218:221], v[88:91]
	v_mfma_f32_16x16x32_bf16 v[80:83], v[188:191], v[218:221], v[80:83]
	v_mfma_f32_16x16x32_bf16 v[72:75], v[180:183], v[226:229], v[72:75]
	v_mfma_f32_16x16x32_bf16 v[64:67], v[188:191], v[226:229], v[64:67]
	v_mfma_f32_16x16x32_bf16 v[120:123], v[184:187], v[206:209], v[120:123]
	v_mfma_f32_16x16x32_bf16 v[112:115], v[198:201], v[206:209], v[112:115]
	v_mfma_f32_16x16x32_bf16 v[104:107], v[184:187], v[214:217], v[104:107]
	v_mfma_f32_16x16x32_bf16 v[96:99], v[198:201], v[214:217], v[96:99]
	v_mfma_f32_16x16x32_bf16 v[88:91], v[184:187], v[222:225], v[88:91]
	v_mfma_f32_16x16x32_bf16 v[80:83], v[198:201], v[222:225], v[80:83]
	v_mfma_f32_16x16x32_bf16 v[72:75], v[184:187], v[230:233], v[72:75]
	v_mfma_f32_16x16x32_bf16 v[64:67], v[198:201], v[230:233], v[64:67]
	s_barrier
	s_add_i32 s6, s59, s26
	s_mov_b32 m0, s6
	ds_read_b128 v[202:205], v156 offset:16384
	ds_read_b128 v[206:209], v156 offset:17408
	ds_read_b128 v[210:213], v156 offset:18432
	ds_read_b128 v[214:217], v156 offset:19456
	ds_read_b128 v[218:221], v156 offset:20480
	ds_read_b128 v[222:225], v156 offset:21504
	ds_read_b128 v[226:229], v156 offset:22528
	ds_read_b128 v[230:233], v156 offset:23552
	global_load_lds_dwordx4 v132, s[52:53]
	s_add_i32 m0, s6, 0x2000
	s_add_u32 s6, s52, 0x40000
	s_addc_u32 s7, s53, 0
	s_add_i32 s73, s60, s26
	global_load_lds_dwordx4 v128, s[52:53]
	s_mov_b32 m0, s73
	s_nop 0
	global_load_lds_dwordx4 v132, s[6:7]
	s_add_i32 m0, s73, 0x2000
	s_nop 0
	global_load_lds_dwordx4 v128, s[6:7]
	s_mov_b32 m0, s27
	s_nop 0
	global_load_lds_dwordx4 v134, s[54:55]
	s_mov_b32 m0, s42
	s_nop 0
	global_load_lds_dwordx4 v130, s[54:55]
	s_waitcnt vmcnt(8)
	s_waitcnt lgkmcnt(0)
	s_barrier
	s_waitcnt lgkmcnt(0)
	v_mfma_f32_16x16x32_bf16 v[60:63], v[144:147], v[202:205], v[60:63]
	v_mfma_f32_16x16x32_bf16 v[52:55], v[172:175], v[202:205], v[52:55]
	v_mfma_f32_16x16x32_bf16 v[44:47], v[144:147], v[210:213], v[44:47]
	v_mfma_f32_16x16x32_bf16 v[36:39], v[172:175], v[210:213], v[36:39]
	v_mfma_f32_16x16x32_bf16 v[28:31], v[144:147], v[218:221], v[28:31]
	v_mfma_f32_16x16x32_bf16 v[20:23], v[172:175], v[218:221], v[20:23]
	v_mfma_f32_16x16x32_bf16 v[12:15], v[144:147], v[226:229], v[12:15]
	v_mfma_f32_16x16x32_bf16 v[4:7], v[172:175], v[226:229], v[4:7]
	v_mfma_f32_16x16x32_bf16 v[60:63], v[168:171], v[206:209], v[60:63]
	v_mfma_f32_16x16x32_bf16 v[52:55], v[176:179], v[206:209], v[52:55]
	v_mfma_f32_16x16x32_bf16 v[44:47], v[168:171], v[214:217], v[44:47]
	v_mfma_f32_16x16x32_bf16 v[36:39], v[176:179], v[214:217], v[36:39]
	v_mfma_f32_16x16x32_bf16 v[28:31], v[168:171], v[222:225], v[28:31]
	v_mfma_f32_16x16x32_bf16 v[20:23], v[176:179], v[222:225], v[20:23]
	v_mfma_f32_16x16x32_bf16 v[12:15], v[168:171], v[230:233], v[12:15]
	v_mfma_f32_16x16x32_bf16 v[4:7], v[176:179], v[230:233], v[4:7]
	v_mfma_f32_16x16x32_bf16 v[56:59], v[180:183], v[202:205], v[56:59]
	v_mfma_f32_16x16x32_bf16 v[48:51], v[188:191], v[202:205], v[48:51]
	v_mfma_f32_16x16x32_bf16 v[40:43], v[180:183], v[210:213], v[40:43]
	v_mfma_f32_16x16x32_bf16 v[32:35], v[188:191], v[210:213], v[32:35]
	v_mfma_f32_16x16x32_bf16 v[24:27], v[180:183], v[218:221], v[24:27]
	v_mfma_f32_16x16x32_bf16 v[16:19], v[188:191], v[218:221], v[16:19]
	v_mfma_f32_16x16x32_bf16 v[8:11], v[180:183], v[226:229], v[8:11]
	v_mfma_f32_16x16x32_bf16 v[0:3], v[188:191], v[226:229], v[0:3]
	v_mfma_f32_16x16x32_bf16 v[56:59], v[184:187], v[206:209], v[56:59]
	v_mfma_f32_16x16x32_bf16 v[48:51], v[198:201], v[206:209], v[48:51]
	v_mfma_f32_16x16x32_bf16 v[40:43], v[184:187], v[214:217], v[40:43]
	v_mfma_f32_16x16x32_bf16 v[32:35], v[198:201], v[214:217], v[32:35]
	v_mfma_f32_16x16x32_bf16 v[24:27], v[184:187], v[222:225], v[24:27]
	v_mfma_f32_16x16x32_bf16 v[16:19], v[198:201], v[222:225], v[16:19]
	v_mfma_f32_16x16x32_bf16 v[8:11], v[184:187], v[230:233], v[8:11]
	v_mfma_f32_16x16x32_bf16 v[0:3], v[198:201], v[230:233], v[0:3]
	s_barrier
; #define PG8_STAGE(bufoff, gbase, voff) do { _Pragma("unroll") for (int _i = 0; _i < 2; ++_i) \
;         __builtin_amdgcn_global_load_lds((const unsigned*)((const char*)(gbase) + (voff)[_i]), (PG8_LAS unsigned*)(lds + (bufoff) + ldsw + _i * 8192), 16, 0, 0); } while (0)
; #define PG8_LDA(dst, b, h) do { _Pragma("unroll") for (int m = 0; m < 4; ++m) _Pragma("unroll") for (int k = 0; k < 2; ++k) dst[m][k] = *(const PG8_LAS bf16x8*)(lds + PG8_SA(b, h) + aoff + m * 2048 + k * 1024); } while (0)
; #define PG8_LDB(dst, b, h) do { _Pragma("unroll") for (int n = 0; n < 2; ++n) _Pragma("unroll") for (int k = 0; k < 2; ++k) dst[n][k] = *(const PG8_LAS bf16x8*)(lds + PG8_SB(b, h) + boff + n * 2048 + k * 1024); } while (0)
; #define PG8_MMA(ai, bj, At, Bt) do { __builtin_amdgcn_s_setprio(1); _Pragma("unroll") for (int m = 0; m < 4; ++m) _Pragma("unroll") for (int n = 0; n < 2; ++n) _Pragma("unroll") for (int k = 0; k < 2; ++k) \
;         acc[ai][bj][m][n] = __builtin_amdgcn_mfma_f32_16x16x32_bf16(Bt[n][k], At[m][k], acc[ai][bj][m][n], 0, 0, 0); __builtin_amdgcn_s_setprio(0); } while (0)
; #define PG8_WAIT_V(n) asm volatile("s_waitcnt vmcnt(" #n ")" ::: "memory")
; #define PG8_WAIT_L(n) asm volatile("s_waitcnt lgkmcnt(" #n ")" ::: "memory")
; #define PG8_BAR __builtin_amdgcn_s_barrier()
; #define PG8_SCHED __builtin_amdgcn_sched_barrier(0)
; template <class Epi, class Sched, bool ALIGN_EPI = false, bool SP2 = false>
; __device__ __forceinline__ void gemm_phase(PG8_LAS unsigned char* lds, const Gemm g, const Sched& S, const Epi& E) {
;     ...
;             PG8_LDB(B0, 1, 0); PG8_LDB(B1, 1, 1); PG8_SCHED; PG8_LDA(At, 1, 0); PG8_STAGE(PG8_SA(0, 1), a2 + hstep, voffA);
;             PG8_WAIT_V(8); PG8_WAIT_L(0); PG8_BAR; PG8_MMA(0, 0, At, B0); PG8_MMA(0, 1, At, B1); PG8_BAR; PG8_SCHED;
;             PG8_LDA(At, 1, 1); PG8_STAGE(PG8_SB(1, 0), b3, voffB); PG8_STAGE(PG8_SB(1, 1), b3 + hstep, voffB); PG8_STAGE(PG8_SA(1, 0), a3, voffA);
;             PG8_WAIT_V(8); PG8_WAIT_L(0); PG8_BAR; PG8_MMA(1, 0, At, B0); PG8_MMA(1, 1, At, B1); PG8_BAR; PG8_SCHED;
	s_add_i32 s73, 0, 0x18000
	v_add_u32_e32 v157, s73, v151
	s_add_i32 s76, 0, 0x1c000
	ds_read_b128 v[144:147], v157
	ds_read_b128 v[168:171], v157 offset:1024
	ds_read_b128 v[172:175], v157 offset:2048
	ds_read_b128 v[176:179], v157 offset:3072
	v_add_u32_e32 v157, s76, v151
	ds_read_b128 v[180:183], v157
	ds_read_b128 v[184:187], v157 offset:1024
	ds_read_b128 v[188:191], v157 offset:2048
	ds_read_b128 v[198:201], v157 offset:3072
	s_add_u32 s6, s54, 0x40000
	s_addc_u32 s7, s55, 0
	s_mov_b32 m0, s43
	ds_read_b128 v[202:205], v156 offset:32768
	ds_read_b128 v[206:209], v156 offset:33792
	ds_read_b128 v[210:213], v156 offset:34816
	ds_read_b128 v[214:217], v156 offset:35840
	ds_read_b128 v[218:221], v156 offset:36864
	ds_read_b128 v[222:225], v156 offset:37888
	ds_read_b128 v[226:229], v156 offset:38912
	ds_read_b128 v[230:233], v156 offset:39936
	global_load_lds_dwordx4 v134, s[6:7]
	s_mov_b32 m0, s56
	s_nop 0
	global_load_lds_dwordx4 v130, s[6:7]
	s_waitcnt vmcnt(8)
	s_waitcnt lgkmcnt(0)
	s_barrier
	s_waitcnt lgkmcnt(0)
	v_mfma_f32_16x16x32_bf16 v[124:127], v[144:147], v[202:205], v[124:127]
	v_mfma_f32_16x16x32_bf16 v[116:119], v[172:175], v[202:205], v[116:119]
	v_mfma_f32_16x16x32_bf16 v[108:111], v[144:147], v[210:213], v[108:111]
	v_mfma_f32_16x16x32_bf16 v[100:103], v[172:175], v[210:213], v[100:103]
	v_mfma_f32_16x16x32_bf16 v[92:95], v[144:147], v[218:221], v[92:95]
	v_mfma_f32_16x16x32_bf16 v[84:87], v[172:175], v[218:221], v[84:87]
	v_mfma_f32_16x16x32_bf16 v[76:79], v[144:147], v[226:229], v[76:79]
	v_mfma_f32_16x16x32_bf16 v[68:71], v[172:175], v[226:229], v[68:71]
	v_mfma_f32_16x16x32_bf16 v[124:127], v[168:171], v[206:209], v[124:127]
	v_mfma_f32_16x16x32_bf16 v[116:119], v[176:179], v[206:209], v[116:119]
	v_mfma_f32_16x16x32_bf16 v[108:111], v[168:171], v[214:217], v[108:111]
	v_mfma_f32_16x16x32_bf16 v[100:103], v[176:179], v[214:217], v[100:103]
	v_mfma_f32_16x16x32_bf16 v[92:95], v[168:171], v[222:225], v[92:95]
	v_mfma_f32_16x16x32_bf16 v[84:87], v[176:179], v[222:225], v[84:87]
	v_mfma_f32_16x16x32_bf16 v[76:79], v[168:171], v[230:233], v[76:79]
	v_mfma_f32_16x16x32_bf16 v[68:71], v[176:179], v[230:233], v[68:71]
	v_mfma_f32_16x16x32_bf16 v[120:123], v[180:183], v[202:205], v[120:123]
	v_mfma_f32_16x16x32_bf16 v[112:115], v[188:191], v[202:205], v[112:115]
	v_mfma_f32_16x16x32_bf16 v[104:107], v[180:183], v[210:213], v[104:107]
	v_mfma_f32_16x16x32_bf16 v[96:99], v[188:191], v[210:213], v[96:99]
	v_mfma_f32_16x16x32_bf16 v[88:91], v[180:183], v[218:221], v[88:91]
	v_mfma_f32_16x16x32_bf16 v[80:83], v[188:191], v[218:221], v[80:83]
	v_mfma_f32_16x16x32_bf16 v[72:75], v[180:183], v[226:229], v[72:75]
	v_mfma_f32_16x16x32_bf16 v[64:67], v[188:191], v[226:229], v[64:67]
	v_mfma_f32_16x16x32_bf16 v[120:123], v[184:187], v[206:209], v[120:123]
	v_mfma_f32_16x16x32_bf16 v[112:115], v[198:201], v[206:209], v[112:115]
	v_mfma_f32_16x16x32_bf16 v[104:107], v[184:187], v[214:217], v[104:107]
	v_mfma_f32_16x16x32_bf16 v[96:99], v[198:201], v[214:217], v[96:99]
	v_mfma_f32_16x16x32_bf16 v[88:91], v[184:187], v[222:225], v[88:91]
	v_mfma_f32_16x16x32_bf16 v[80:83], v[198:201], v[222:225], v[80:83]
	v_mfma_f32_16x16x32_bf16 v[72:75], v[184:187], v[230:233], v[72:75]
	v_mfma_f32_16x16x32_bf16 v[64:67], v[198:201], v[230:233], v[64:67]
	s_barrier
	s_add_i32 s6, s73, s26
	s_add_u32 s98, s52, 0x80
	s_addc_u32 s99, s53, 0
	s_add_u32 s100, s54, 0x80
	s_addc_u32 s101, s55, 0
	s_mov_b32 m0, s6
	ds_read_b128 v[202:205], v156 offset:49152
	ds_read_b128 v[206:209], v156 offset:50176
	ds_read_b128 v[210:213], v156 offset:51200
	ds_read_b128 v[214:217], v156 offset:52224
	ds_read_b128 v[218:221], v156 offset:53248
	ds_read_b128 v[222:225], v156 offset:54272
	ds_read_b128 v[226:229], v156 offset:55296
	ds_read_b128 v[230:233], v156 offset:56320
	global_load_lds_dwordx4 v132, s[98:99]
	s_add_i32 m0, s6, 0x2000
	s_add_u32 s6, s52, 0x40080
	s_addc_u32 s7, s53, 0
	s_add_i32 s52, s76, s26
	global_load_lds_dwordx4 v128, s[98:99]
	s_mov_b32 m0, s52
	s_nop 0
	global_load_lds_dwordx4 v132, s[6:7]
	s_add_i32 m0, s52, 0x2000
	s_nop 0
	global_load_lds_dwordx4 v128, s[6:7]
	s_mov_b32 m0, s57
	s_nop 0
	global_load_lds_dwordx4 v134, s[100:101]
	s_mov_b32 m0, s58
	s_nop 0
	global_load_lds_dwordx4 v130, s[100:101]
	s_waitcnt vmcnt(8)
	s_waitcnt lgkmcnt(0)
	s_barrier
	s_waitcnt lgkmcnt(0)
	v_mfma_f32_16x16x32_bf16 v[60:63], v[144:147], v[202:205], v[60:63]
	v_mfma_f32_16x16x32_bf16 v[52:55], v[172:175], v[202:205], v[52:55]
	v_mfma_f32_16x16x32_bf16 v[44:47], v[144:147], v[210:213], v[44:47]
	v_mfma_f32_16x16x32_bf16 v[36:39], v[172:175], v[210:213], v[36:39]
	v_mfma_f32_16x16x32_bf16 v[28:31], v[144:147], v[218:221], v[28:31]
	v_mfma_f32_16x16x32_bf16 v[20:23], v[172:175], v[218:221], v[20:23]
	v_mfma_f32_16x16x32_bf16 v[12:15], v[144:147], v[226:229], v[12:15]
	v_mfma_f32_16x16x32_bf16 v[4:7], v[172:175], v[226:229], v[4:7]
	v_mfma_f32_16x16x32_bf16 v[60:63], v[168:171], v[206:209], v[60:63]
	v_mfma_f32_16x16x32_bf16 v[52:55], v[176:179], v[206:209], v[52:55]
	v_mfma_f32_16x16x32_bf16 v[44:47], v[168:171], v[214:217], v[44:47]
	v_mfma_f32_16x16x32_bf16 v[36:39], v[176:179], v[214:217], v[36:39]
	v_mfma_f32_16x16x32_bf16 v[28:31], v[168:171], v[222:225], v[28:31]
	v_mfma_f32_16x16x32_bf16 v[20:23], v[176:179], v[222:225], v[20:23]
	v_mfma_f32_16x16x32_bf16 v[12:15], v[168:171], v[230:233], v[12:15]
	v_mfma_f32_16x16x32_bf16 v[4:7], v[176:179], v[230:233], v[4:7]
	v_mfma_f32_16x16x32_bf16 v[56:59], v[180:183], v[202:205], v[56:59]
	v_mfma_f32_16x16x32_bf16 v[48:51], v[188:191], v[202:205], v[48:51]
	v_mfma_f32_16x16x32_bf16 v[40:43], v[180:183], v[210:213], v[40:43]
	v_mfma_f32_16x16x32_bf16 v[32:35], v[188:191], v[210:213], v[32:35]
	v_mfma_f32_16x16x32_bf16 v[24:27], v[180:183], v[218:221], v[24:27]
	v_mfma_f32_16x16x32_bf16 v[16:19], v[188:191], v[218:221], v[16:19]
	v_mfma_f32_16x16x32_bf16 v[8:11], v[180:183], v[226:229], v[8:11]
	v_mfma_f32_16x16x32_bf16 v[0:3], v[188:191], v[226:229], v[0:3]
	v_mfma_f32_16x16x32_bf16 v[56:59], v[184:187], v[206:209], v[56:59]
	v_mfma_f32_16x16x32_bf16 v[48:51], v[198:201], v[206:209], v[48:51]
	v_mfma_f32_16x16x32_bf16 v[40:43], v[184:187], v[214:217], v[40:43]
	v_mfma_f32_16x16x32_bf16 v[32:35], v[198:201], v[214:217], v[32:35]
	v_mfma_f32_16x16x32_bf16 v[24:27], v[184:187], v[222:225], v[24:27]
	v_mfma_f32_16x16x32_bf16 v[16:19], v[198:201], v[222:225], v[16:19]
	v_mfma_f32_16x16x32_bf16 v[8:11], v[184:187], v[230:233], v[8:11]
	v_mfma_f32_16x16x32_bf16 v[0:3], v[198:201], v[230:233], v[0:3]
	s_barrier
	s_add_i32 s72, s72, 2
	s_add_u32 s50, s50, 0x100
	s_addc_u32 s51, s51, 0
	s_add_u32 s75, s75, 0x100
	s_addc_u32 s33, s33, 0
	s_cmp_gt_u32 s72, 13
	s_cbranch_scc0 .LBB0_1822
	v_readlane_b32 s74, v243, 57
	s_and_b64 vcc, exec, s[34:35]
	v_readlane_b32 s75, v243, 58
	s_cbranch_vccz .LBB0_1825
	s_barrier

; #define PG8_STAGE(bufoff, gbase, voff) do { _Pragma("unroll") for (int _i = 0; _i < 2; ++_i) \
;         __builtin_amdgcn_global_load_lds((const unsigned*)((const char*)(gbase) + (voff)[_i]), (PG8_LAS unsigned*)(lds + (bufoff) + ldsw + _i * 8192), 16, 0, 0); } while (0)
; #define PG8_LDA(dst, b, h) do { _Pragma("unroll") for (int m = 0; m < 4; ++m) _Pragma("unroll") for (int k = 0; k < 2; ++k) dst[m][k] = *(const PG8_LAS bf16x8*)(lds + PG8_SA(b, h) + aoff + m * 2048 + k * 1024); } while (0)
; #define PG8_LDB(dst, b, h) do { _Pragma("unroll") for (int n = 0; n < 2; ++n) _Pragma("unroll") for (int k = 0; k < 2; ++k) dst[n][k] = *(const PG8_LAS bf16x8*)(lds + PG8_SB(b, h) + boff + n * 2048 + k * 1024); } while (0)
; #define PG8_MMA(ai, bj, At, Bt) do { __builtin_amdgcn_s_setprio(1); _Pragma("unroll") for (int m = 0; m < 4; ++m) _Pragma("unroll") for (int n = 0; n < 2; ++n) _Pragma("unroll") for (int k = 0; k < 2; ++k) \
;         acc[ai][bj][m][n] = __builtin_amdgcn_mfma_f32_16x16x32_bf16(Bt[n][k], At[m][k], acc[ai][bj][m][n], 0, 0, 0); __builtin_amdgcn_s_setprio(0); } while (0)
; #define PG8_WAIT_V(n) asm volatile("s_waitcnt vmcnt(" #n ")" ::: "memory")
; #define PG8_WAIT_L(n) asm volatile("s_waitcnt lgkmcnt(" #n ")" ::: "memory")
; template <class Epi, class Sched, bool ALIGN_EPI = false, bool SP2 = false>
; __device__ __forceinline__ void gemm_phase(PG8_LAS unsigned char* lds, const Gemm g, const Sched& S, const Epi& E) {
;     ...
;             const bool last = (t == nt - 2);
;             const char* a1 = cA + (size_t)(t + 1) * kstep;
;             const char* a2 = last ? nA : cA + (size_t)(t + 2) * kstep; const char* b2 = last ? nB : cB + (size_t)(t + 2) * kstep;
;             const char* a3 = a2 + kstep; const char* b3 = b2 + kstep;
;             if (last && has_next) S.a_ready(nxt);
;             if constexpr (SP2) {
;             PG8_LDB(B0, 0, 0); PG8_LDB(B1, 0, 1); PG8_SCHED; PG8_LDA(At, 0, 0); PG8_STAGE(PG8_SA(1, 1), a1 + hstep, voffA);
;             PG8_WAIT_V(8); PG8_WAIT_L(0); PG8_BAR; PG8_MMA(0, 0, At, B0); PG8_MMA(0, 1, At, B1); PG8_BAR; PG8_SCHED;
;             PG8_LDA(At, 0, 1); PG8_STAGE(PG8_SB(0, 0), b2, voffB); PG8_STAGE(PG8_SB(0, 1), b2 + hstep, voffB); PG8_STAGE(PG8_SA(0, 0), a2, voffA);
;             PG8_WAIT_V(8); PG8_WAIT_L(0); PG8_BAR; PG8_MMA(1, 0, At, B0); PG8_MMA(1, 1, At, B1); PG8_BAR; PG8_SCHED;
.LBB0_1935:
	ds_read_b128 v[144:147], v153
	ds_read_b128 v[168:171], v153 offset:1024
	ds_read_b128 v[172:175], v153 offset:2048
	ds_read_b128 v[176:179], v153 offset:3072
	ds_read_b128 v[180:183], v154
	ds_read_b128 v[184:187], v154 offset:1024
	ds_read_b128 v[188:191], v154 offset:2048
	ds_read_b128 v[198:201], v154 offset:3072
	s_add_u32 s50, s48, 0x100
	s_addc_u32 s51, s49, 0
	s_cmp_eq_u32 s72, 40
	s_cselect_b32 s55, s41, s51
	s_cselect_b32 s54, s40, s50
	s_cselect_b32 s53, s47, s77
	s_cselect_b32 s52, s46, s33
	s_add_i32 m0, s58, 0xc000
	ds_read_b128 v[202:205], v155
	ds_read_b128 v[206:209], v155 offset:1024
	ds_read_b128 v[210:213], v155 offset:2048
	ds_read_b128 v[214:217], v155 offset:3072
	ds_read_b128 v[218:221], v155 offset:4096
	ds_read_b128 v[222:225], v155 offset:5120
	ds_read_b128 v[226:229], v155 offset:6144
	ds_read_b128 v[230:233], v155 offset:7168
	global_load_lds_dwordx4 v136, s[48:49]
	s_add_i32 m0, s58, 0xe000
	s_nop 0
	global_load_lds_dwordx4 v138, s[48:49]
	s_waitcnt vmcnt(8)
	s_waitcnt lgkmcnt(0)
	s_barrier
	s_waitcnt lgkmcnt(0)
	v_mfma_f32_16x16x32_bf16 v[124:127], v[144:147], v[202:205], v[124:127]
	v_mfma_f32_16x16x32_bf16 v[120:123], v[172:175], v[202:205], v[120:123]
	v_mfma_f32_16x16x32_bf16 v[108:111], v[144:147], v[210:213], v[108:111]
	v_mfma_f32_16x16x32_bf16 v[104:107], v[172:175], v[210:213], v[104:107]
	v_mfma_f32_16x16x32_bf16 v[92:95], v[144:147], v[218:221], v[92:95]
	v_mfma_f32_16x16x32_bf16 v[88:91], v[172:175], v[218:221], v[88:91]
	v_mfma_f32_16x16x32_bf16 v[76:79], v[144:147], v[226:229], v[76:79]
	v_mfma_f32_16x16x32_bf16 v[72:75], v[172:175], v[226:229], v[72:75]
	v_mfma_f32_16x16x32_bf16 v[124:127], v[168:171], v[206:209], v[124:127]
	v_mfma_f32_16x16x32_bf16 v[120:123], v[176:179], v[206:209], v[120:123]
	v_mfma_f32_16x16x32_bf16 v[108:111], v[168:171], v[214:217], v[108:111]
	v_mfma_f32_16x16x32_bf16 v[104:107], v[176:179], v[214:217], v[104:107]
	v_mfma_f32_16x16x32_bf16 v[92:95], v[168:171], v[222:225], v[92:95]
	v_mfma_f32_16x16x32_bf16 v[88:91], v[176:179], v[222:225], v[88:91]
	v_mfma_f32_16x16x32_bf16 v[76:79], v[168:171], v[230:233], v[76:79]
	v_mfma_f32_16x16x32_bf16 v[72:75], v[176:179], v[230:233], v[72:75]
	v_mfma_f32_16x16x32_bf16 v[116:119], v[180:183], v[202:205], v[116:119]
	v_mfma_f32_16x16x32_bf16 v[112:115], v[188:191], v[202:205], v[112:115]
	v_mfma_f32_16x16x32_bf16 v[100:103], v[180:183], v[210:213], v[100:103]
	v_mfma_f32_16x16x32_bf16 v[96:99], v[188:191], v[210:213], v[96:99]
	v_mfma_f32_16x16x32_bf16 v[84:87], v[180:183], v[218:221], v[84:87]
	v_mfma_f32_16x16x32_bf16 v[80:83], v[188:191], v[218:221], v[80:83]
	v_mfma_f32_16x16x32_bf16 v[68:71], v[180:183], v[226:229], v[68:71]
	v_mfma_f32_16x16x32_bf16 v[64:67], v[188:191], v[226:229], v[64:67]
	v_mfma_f32_16x16x32_bf16 v[116:119], v[184:187], v[206:209], v[116:119]
	v_mfma_f32_16x16x32_bf16 v[112:115], v[198:201], v[206:209], v[112:115]
	v_mfma_f32_16x16x32_bf16 v[100:103], v[184:187], v[214:217], v[100:103]
	v_mfma_f32_16x16x32_bf16 v[96:99], v[198:201], v[214:217], v[96:99]
	v_mfma_f32_16x16x32_bf16 v[84:87], v[184:187], v[222:225], v[84:87]
	v_mfma_f32_16x16x32_bf16 v[80:83], v[198:201], v[222:225], v[80:83]
	v_mfma_f32_16x16x32_bf16 v[68:71], v[184:187], v[230:233], v[68:71]
	v_mfma_f32_16x16x32_bf16 v[64:67], v[198:201], v[230:233], v[64:67]
	s_barrier
	s_add_i32 s6, s26, s57
	s_mov_b32 m0, s6
	ds_read_b128 v[202:205], v155 offset:16384
	ds_read_b128 v[206:209], v155 offset:17408
	ds_read_b128 v[210:213], v155 offset:18432
	ds_read_b128 v[214:217], v155 offset:19456
	ds_read_b128 v[218:221], v155 offset:20480
	ds_read_b128 v[222:225], v155 offset:21504
	ds_read_b128 v[226:229], v155 offset:22528
	ds_read_b128 v[230:233], v155 offset:23552
	global_load_lds_dwordx4 v130, s[52:53]
	s_add_i32 m0, s6, 0x2000
	s_add_u32 s6, s52, 0xb0000
	s_addc_u32 s7, s53, 0
	s_add_i32 s48, s74, s57
	global_load_lds_dwordx4 v134, s[52:53]
	s_mov_b32 m0, s48
	s_nop 0
	global_load_lds_dwordx4 v130, s[6:7]
	s_add_i32 m0, s48, 0x2000
	s_nop 0
	global_load_lds_dwordx4 v134, s[6:7]
	s_mov_b32 m0, s58
	s_nop 0
	global_load_lds_dwordx4 v128, s[54:55]
	s_mov_b32 m0, s59
	s_nop 0
	global_load_lds_dwordx4 v132, s[54:55]
	s_waitcnt vmcnt(8)
	s_waitcnt lgkmcnt(0)
	s_barrier
	s_waitcnt lgkmcnt(0)
	v_mfma_f32_16x16x32_bf16 v[60:63], v[144:147], v[202:205], v[60:63]
	v_mfma_f32_16x16x32_bf16 v[56:59], v[172:175], v[202:205], v[56:59]
	v_mfma_f32_16x16x32_bf16 v[44:47], v[144:147], v[210:213], v[44:47]
	v_mfma_f32_16x16x32_bf16 v[40:43], v[172:175], v[210:213], v[40:43]
	v_mfma_f32_16x16x32_bf16 v[28:31], v[144:147], v[218:221], v[28:31]
	v_mfma_f32_16x16x32_bf16 v[24:27], v[172:175], v[218:221], v[24:27]
	v_mfma_f32_16x16x32_bf16 v[12:15], v[144:147], v[226:229], v[12:15]
	v_mfma_f32_16x16x32_bf16 v[8:11], v[172:175], v[226:229], v[8:11]
	v_mfma_f32_16x16x32_bf16 v[60:63], v[168:171], v[206:209], v[60:63]
	v_mfma_f32_16x16x32_bf16 v[56:59], v[176:179], v[206:209], v[56:59]
	v_mfma_f32_16x16x32_bf16 v[44:47], v[168:171], v[214:217], v[44:47]
	v_mfma_f32_16x16x32_bf16 v[40:43], v[176:179], v[214:217], v[40:43]
	v_mfma_f32_16x16x32_bf16 v[28:31], v[168:171], v[222:225], v[28:31]
	v_mfma_f32_16x16x32_bf16 v[24:27], v[176:179], v[222:225], v[24:27]
	v_mfma_f32_16x16x32_bf16 v[12:15], v[168:171], v[230:233], v[12:15]
	v_mfma_f32_16x16x32_bf16 v[8:11], v[176:179], v[230:233], v[8:11]
	v_mfma_f32_16x16x32_bf16 v[52:55], v[180:183], v[202:205], v[52:55]
	v_mfma_f32_16x16x32_bf16 v[48:51], v[188:191], v[202:205], v[48:51]
	v_mfma_f32_16x16x32_bf16 v[36:39], v[180:183], v[210:213], v[36:39]
	v_mfma_f32_16x16x32_bf16 v[32:35], v[188:191], v[210:213], v[32:35]
	v_mfma_f32_16x16x32_bf16 v[20:23], v[180:183], v[218:221], v[20:23]
	v_mfma_f32_16x16x32_bf16 v[16:19], v[188:191], v[218:221], v[16:19]
	v_mfma_f32_16x16x32_bf16 v[4:7], v[180:183], v[226:229], v[4:7]
	v_mfma_f32_16x16x32_bf16 v[0:3], v[188:191], v[226:229], v[0:3]
	v_mfma_f32_16x16x32_bf16 v[52:55], v[184:187], v[206:209], v[52:55]
	v_mfma_f32_16x16x32_bf16 v[48:51], v[198:201], v[206:209], v[48:51]
	v_mfma_f32_16x16x32_bf16 v[36:39], v[184:187], v[214:217], v[36:39]
	v_mfma_f32_16x16x32_bf16 v[32:35], v[198:201], v[214:217], v[32:35]
	v_mfma_f32_16x16x32_bf16 v[20:23], v[184:187], v[222:225], v[20:23]
	v_mfma_f32_16x16x32_bf16 v[16:19], v[198:201], v[222:225], v[16:19]
	v_mfma_f32_16x16x32_bf16 v[4:7], v[184:187], v[230:233], v[4:7]
	v_mfma_f32_16x16x32_bf16 v[0:3], v[198:201], v[230:233], v[0:3]
	s_barrier
; #define PG8_STAGE(bufoff, gbase, voff) do { _Pragma("unroll") for (int _i = 0; _i < 2; ++_i) \
;         __builtin_amdgcn_global_load_lds((const unsigned*)((const char*)(gbase) + (voff)[_i]), (PG8_LAS unsigned*)(lds + (bufoff) + ldsw + _i * 8192), 16, 0, 0); } while (0)
; #define PG8_LDA(dst, b, h) do { _Pragma("unroll") for (int m = 0; m < 4; ++m) _Pragma("unroll") for (int k = 0; k < 2; ++k) dst[m][k] = *(const PG8_LAS bf16x8*)(lds + PG8_SA(b, h) + aoff + m * 2048 + k * 1024); } while (0)
; #define PG8_LDB(dst, b, h) do { _Pragma("unroll") for (int n = 0; n < 2; ++n) _Pragma("unroll") for (int k = 0; k < 2; ++k) dst[n][k] = *(const PG8_LAS bf16x8*)(lds + PG8_SB(b, h) + boff + n * 2048 + k * 1024); } while (0)
; #define PG8_MMA(ai, bj, At, Bt) do { __builtin_amdgcn_s_setprio(1); _Pragma("unroll") for (int m = 0; m < 4; ++m) _Pragma("unroll") for (int n = 0; n < 2; ++n) _Pragma("unroll") for (int k = 0; k < 2; ++k) \
;         acc[ai][bj][m][n] = __builtin_amdgcn_mfma_f32_16x16x32_bf16(Bt[n][k], At[m][k], acc[ai][bj][m][n], 0, 0, 0); __builtin_amdgcn_s_setprio(0); } while (0)
; #define PG8_WAIT_V(n) asm volatile("s_waitcnt vmcnt(" #n ")" ::: "memory")
; #define PG8_WAIT_L(n) asm volatile("s_waitcnt lgkmcnt(" #n ")" ::: "memory")
; #define PG8_BAR __builtin_amdgcn_s_barrier()
; #define PG8_SCHED __builtin_amdgcn_sched_barrier(0)
; template <class Epi, class Sched, bool ALIGN_EPI = false, bool SP2 = false>
; __device__ __forceinline__ void gemm_phase(PG8_LAS unsigned char* lds, const Gemm g, const Sched& S, const Epi& E) {
;     ...
;             PG8_LDB(B0, 1, 0); PG8_LDB(B1, 1, 1); PG8_SCHED; PG8_LDA(At, 1, 0); PG8_STAGE(PG8_SA(0, 1), a2 + hstep, voffA);
;             PG8_WAIT_V(8); PG8_WAIT_L(0); PG8_BAR; PG8_MMA(0, 0, At, B0); PG8_MMA(0, 1, At, B1); PG8_BAR; PG8_SCHED;
;             PG8_LDA(At, 1, 1); PG8_STAGE(PG8_SB(1, 0), b3, voffB); PG8_STAGE(PG8_SB(1, 1), b3 + hstep, voffB); PG8_STAGE(PG8_SA(1, 0), a3, voffA);
;             PG8_WAIT_V(8); PG8_WAIT_L(0); PG8_BAR; PG8_MMA(1, 0, At, B0); PG8_MMA(1, 1, At, B1); PG8_BAR; PG8_SCHED;
	s_add_i32 s48, 0, 0x18000
	v_add_u32_e32 v157, s48, v151
	s_add_i32 s49, 0, 0x1c000
	ds_read_b128 v[144:147], v157
	ds_read_b128 v[168:171], v157 offset:1024
	ds_read_b128 v[172:175], v157 offset:2048
	ds_read_b128 v[176:179], v157 offset:3072
	v_add_u32_e32 v157, s49, v151
	ds_read_b128 v[180:183], v157
	ds_read_b128 v[184:187], v157 offset:1024
	ds_read_b128 v[188:191], v157 offset:2048
	ds_read_b128 v[198:201], v157 offset:3072
	s_add_u32 s6, s54, 0xb0000
	s_addc_u32 s7, s55, 0
	s_mov_b32 m0, s60
	ds_read_b128 v[202:205], v155 offset:32768
	ds_read_b128 v[206:209], v155 offset:33792
	ds_read_b128 v[210:213], v155 offset:34816
	ds_read_b128 v[214:217], v155 offset:35840
	ds_read_b128 v[218:221], v155 offset:36864
	ds_read_b128 v[222:225], v155 offset:37888
	ds_read_b128 v[226:229], v155 offset:38912
	ds_read_b128 v[230:233], v155 offset:39936
	global_load_lds_dwordx4 v128, s[6:7]
	s_mov_b32 m0, s61
	s_nop 0
	global_load_lds_dwordx4 v132, s[6:7]
	s_waitcnt vmcnt(8)
	s_waitcnt lgkmcnt(0)
	s_barrier
	s_waitcnt lgkmcnt(0)
	v_mfma_f32_16x16x32_bf16 v[124:127], v[144:147], v[202:205], v[124:127]
	v_mfma_f32_16x16x32_bf16 v[120:123], v[172:175], v[202:205], v[120:123]
	v_mfma_f32_16x16x32_bf16 v[108:111], v[144:147], v[210:213], v[108:111]
	v_mfma_f32_16x16x32_bf16 v[104:107], v[172:175], v[210:213], v[104:107]
	v_mfma_f32_16x16x32_bf16 v[92:95], v[144:147], v[218:221], v[92:95]
	v_mfma_f32_16x16x32_bf16 v[88:91], v[172:175], v[218:221], v[88:91]
	v_mfma_f32_16x16x32_bf16 v[76:79], v[144:147], v[226:229], v[76:79]
	v_mfma_f32_16x16x32_bf16 v[72:75], v[172:175], v[226:229], v[72:75]
	v_mfma_f32_16x16x32_bf16 v[124:127], v[168:171], v[206:209], v[124:127]
	v_mfma_f32_16x16x32_bf16 v[120:123], v[176:179], v[206:209], v[120:123]
	v_mfma_f32_16x16x32_bf16 v[108:111], v[168:171], v[214:217], v[108:111]
	v_mfma_f32_16x16x32_bf16 v[104:107], v[176:179], v[214:217], v[104:107]
	v_mfma_f32_16x16x32_bf16 v[92:95], v[168:171], v[222:225], v[92:95]
	v_mfma_f32_16x16x32_bf16 v[88:91], v[176:179], v[222:225], v[88:91]
	v_mfma_f32_16x16x32_bf16 v[76:79], v[168:171], v[230:233], v[76:79]
	v_mfma_f32_16x16x32_bf16 v[72:75], v[176:179], v[230:233], v[72:75]
	v_mfma_f32_16x16x32_bf16 v[116:119], v[180:183], v[202:205], v[116:119]
	v_mfma_f32_16x16x32_bf16 v[112:115], v[188:191], v[202:205], v[112:115]
	v_mfma_f32_16x16x32_bf16 v[100:103], v[180:183], v[210:213], v[100:103]
	v_mfma_f32_16x16x32_bf16 v[96:99], v[188:191], v[210:213], v[96:99]
	v_mfma_f32_16x16x32_bf16 v[84:87], v[180:183], v[218:221], v[84:87]
	v_mfma_f32_16x16x32_bf16 v[80:83], v[188:191], v[218:221], v[80:83]
	v_mfma_f32_16x16x32_bf16 v[68:71], v[180:183], v[226:229], v[68:71]
	v_mfma_f32_16x16x32_bf16 v[64:67], v[188:191], v[226:229], v[64:67]
	v_mfma_f32_16x16x32_bf16 v[116:119], v[184:187], v[206:209], v[116:119]
	v_mfma_f32_16x16x32_bf16 v[112:115], v[198:201], v[206:209], v[112:115]
	v_mfma_f32_16x16x32_bf16 v[100:103], v[184:187], v[214:217], v[100:103]
	v_mfma_f32_16x16x32_bf16 v[96:99], v[198:201], v[214:217], v[96:99]
	v_mfma_f32_16x16x32_bf16 v[84:87], v[184:187], v[222:225], v[84:87]
	v_mfma_f32_16x16x32_bf16 v[80:83], v[198:201], v[222:225], v[80:83]
	v_mfma_f32_16x16x32_bf16 v[68:71], v[184:187], v[230:233], v[68:71]
	v_mfma_f32_16x16x32_bf16 v[64:67], v[198:201], v[230:233], v[64:67]
	s_barrier
	s_add_i32 s6, s48, s57
	s_add_u32 s98, s52, 0x80
	s_addc_u32 s99, s53, 0
	s_add_u32 s100, s54, 0x80
	s_addc_u32 s101, s55, 0
	s_mov_b32 m0, s6
	ds_read_b128 v[202:205], v155 offset:49152
	ds_read_b128 v[206:209], v155 offset:50176
	ds_read_b128 v[210:213], v155 offset:51200
	ds_read_b128 v[214:217], v155 offset:52224
	ds_read_b128 v[218:221], v155 offset:53248
	ds_read_b128 v[222:225], v155 offset:54272
	ds_read_b128 v[226:229], v155 offset:55296
	ds_read_b128 v[230:233], v155 offset:56320
	global_load_lds_dwordx4 v130, s[98:99]
	s_add_i32 m0, s6, 0x2000
	s_add_u32 s6, s52, 0xb0080
	s_addc_u32 s7, s53, 0
	s_add_i32 s48, s49, s57
	global_load_lds_dwordx4 v134, s[98:99]
	s_mov_b32 m0, s48
	s_nop 0
	global_load_lds_dwordx4 v130, s[6:7]
	s_add_i32 m0, s48, 0x2000
	s_nop 0
	global_load_lds_dwordx4 v134, s[6:7]
	s_mov_b32 m0, s76
	s_nop 0
	global_load_lds_dwordx4 v128, s[100:101]
	s_mov_b32 m0, s4
	s_nop 0
	global_load_lds_dwordx4 v132, s[100:101]
	s_waitcnt vmcnt(8)
	s_waitcnt lgkmcnt(0)
	s_barrier
	s_waitcnt lgkmcnt(0)
	v_mfma_f32_16x16x32_bf16 v[60:63], v[144:147], v[202:205], v[60:63]
	v_mfma_f32_16x16x32_bf16 v[56:59], v[172:175], v[202:205], v[56:59]
	v_mfma_f32_16x16x32_bf16 v[44:47], v[144:147], v[210:213], v[44:47]
	v_mfma_f32_16x16x32_bf16 v[40:43], v[172:175], v[210:213], v[40:43]
	v_mfma_f32_16x16x32_bf16 v[28:31], v[144:147], v[218:221], v[28:31]
	v_mfma_f32_16x16x32_bf16 v[24:27], v[172:175], v[218:221], v[24:27]
	v_mfma_f32_16x16x32_bf16 v[12:15], v[144:147], v[226:229], v[12:15]
	v_mfma_f32_16x16x32_bf16 v[8:11], v[172:175], v[226:229], v[8:11]
	v_mfma_f32_16x16x32_bf16 v[60:63], v[168:171], v[206:209], v[60:63]
	v_mfma_f32_16x16x32_bf16 v[56:59], v[176:179], v[206:209], v[56:59]
	v_mfma_f32_16x16x32_bf16 v[44:47], v[168:171], v[214:217], v[44:47]
	v_mfma_f32_16x16x32_bf16 v[40:43], v[176:179], v[214:217], v[40:43]
	v_mfma_f32_16x16x32_bf16 v[28:31], v[168:171], v[222:225], v[28:31]
	v_mfma_f32_16x16x32_bf16 v[24:27], v[176:179], v[222:225], v[24:27]
	v_mfma_f32_16x16x32_bf16 v[12:15], v[168:171], v[230:233], v[12:15]
	v_mfma_f32_16x16x32_bf16 v[8:11], v[176:179], v[230:233], v[8:11]
	v_mfma_f32_16x16x32_bf16 v[52:55], v[180:183], v[202:205], v[52:55]
	v_mfma_f32_16x16x32_bf16 v[48:51], v[188:191], v[202:205], v[48:51]
	v_mfma_f32_16x16x32_bf16 v[36:39], v[180:183], v[210:213], v[36:39]
	v_mfma_f32_16x16x32_bf16 v[32:35], v[188:191], v[210:213], v[32:35]
	v_mfma_f32_16x16x32_bf16 v[20:23], v[180:183], v[218:221], v[20:23]
	v_mfma_f32_16x16x32_bf16 v[16:19], v[188:191], v[218:221], v[16:19]
	v_mfma_f32_16x16x32_bf16 v[4:7], v[180:183], v[226:229], v[4:7]
	v_mfma_f32_16x16x32_bf16 v[0:3], v[188:191], v[226:229], v[0:3]
	v_mfma_f32_16x16x32_bf16 v[52:55], v[184:187], v[206:209], v[52:55]
	v_mfma_f32_16x16x32_bf16 v[48:51], v[198:201], v[206:209], v[48:51]
	v_mfma_f32_16x16x32_bf16 v[36:39], v[184:187], v[214:217], v[36:39]
	v_mfma_f32_16x16x32_bf16 v[32:35], v[198:201], v[214:217], v[32:35]
	v_mfma_f32_16x16x32_bf16 v[20:23], v[184:187], v[222:225], v[20:23]
	v_mfma_f32_16x16x32_bf16 v[16:19], v[198:201], v[222:225], v[16:19]
	v_mfma_f32_16x16x32_bf16 v[4:7], v[184:187], v[230:233], v[4:7]
	v_mfma_f32_16x16x32_bf16 v[0:3], v[198:201], v[230:233], v[0:3]
	s_barrier
	s_add_i32 s72, s72, 2
	s_add_u32 s33, s33, 0x100
	s_addc_u32 s77, s77, 0
	s_cmp_gt_u32 s72, 41
	s_mov_b64 s[48:49], s[50:51]
	s_cbranch_scc0 .LBB0_1935
	s_and_b64 vcc, exec, s[38:39]
	s_cbranch_vccz .LBB0_1938
	s_barrier
